# stack on the MoBA double-buffer + w_mod permutation version: softmax self-max folds and phase-B copy removal, static MoBA item assignment, GLA pass-1 second load batch issued with the first, final-LN
# speedup vs baseline: 1.0144x; 1.0063x over previous
.LBB0_328:
	s_or_b64 exec, exec, s[38:39]
	v_readlane_b32 s2, v248, 7
	v_readlane_b32 s3, v248, 8
	s_lshl_b32 s2, s2, 9
	v_readlane_b32 s3, v249, 35
	s_or_b32 s80, s2, s3
	s_lshl_b64 s[2:3], s[80:81], 2
	v_readlane_b32 s8, v250, 48
	s_add_u32 s18, s8, s2
	v_readlane_b32 s2, v250, 49
	s_addc_u32 s19, s2, s3
	s_add_u32 s12, s18, 0x1000
	s_addc_u32 s13, s19, 0
	s_mov_b64 s[78:79], 0
	s_lshr_b32 s98, s74, 3
	v_mov_b32_e32 v254, s98
	s_and_b32 s98, s74, 7
	s_sub_i32 s98, s26, s98
	s_add_i32 s98, s98, -1
	s_lshr_b32 s98, s98, 3
	s_add_i32 s98, s98, 1
	v_mov_b32_e32 v255, s98
	s_branch .LBB0_331

.LBB0_331:
	v_mov_b32_e32 v8, v254
	v_add_u32_e32 v254, v254, v255
	s_mov_b64 s[2:3], -1
	v_cmp_gt_i32_e32 vcc, 64, v8
	s_and_saveexec_b64 s[82:83], vcc
	s_cbranch_execz .LBB0_330
	v_ashrrev_i32_e32 v33, 2, v8
	v_sub_u32_e32 v7, 15, v33
	v_mov_b32_e32 v3, v197
	v_lshlrev_b32_e32 v0, 5, v8
	v_readlane_b32 s2, v249, 37
	v_lshlrev_b32_e32 v9, 6, v7
	s_nop 0
	v_and_or_b32 v32, v0, 64, s2
	v_cmp_lt_i32_e32 vcc, v3, v9
	s_barrier
	s_and_saveexec_b64 s[2:3], vcc
	s_cbranch_execz .LBB0_344
	v_readlane_b32 s8, v249, 38
	v_lshlrev_b32_e32 v0, 2, v32
	v_mov_b32_e32 v1, v2
	v_readlane_b32 s9, v249, 39
	v_and_b32_e32 v4, 63, v3
	v_lshlrev_b32_e32 v4, 2, v4
	v_lshl_add_u64 v[0:1], s[8:9], 0, v[0:1]
	v_mov_b32_e32 v5, v2
	v_lshl_add_u64 v[0:1], v[0:1], 0, v[4:5]
	v_add_u32_e32 v5, 0x100, v3
	v_max_i32_e32 v4, v9, v5
	v_xad_u32 v12, v3, -1, v4
	s_movk_i32 s8, 0xff
	v_cmp_lt_u32_e32 vcc, s8, v12
	s_mov_b64 s[10:11], -1
	v_mov_b32_e32 v4, v3
	s_and_saveexec_b64 s[8:9], vcc
	s_cbranch_execz .LBB0_341
	v_lshrrev_b32_e32 v4, 8, v12
	v_add_u32_e32 v12, 1, v4
	v_and_b32_e32 v13, 0x1fffffe, v12
	v_mov_b32_e32 v4, v3
	v_lshl_add_u32 v15, v3, 2, v210
	s_mov_b64 s[10:11], 0
	v_mov_b32_e32 v16, v13
	v_readlane_b32 s15, v248, 5

.LBB0_411:
	s_or_b64 exec, exec, s[8:9]
	v_max_f32_e32 v139, v122, v123
	v_max_f32_e32 v140, v118, v119
	v_max3_f32 v139, v120, v121, v139
	v_max3_f32 v140, v116, v117, v140
	v_max3_f32 v139, v139, s28, v140
	v_max_f32_e32 v140, v110, v111
	v_max_f32_e32 v142, v114, v114
	v_max_f32_e32 v141, v142, v115
	v_max3_f32 v140, v108, v109, v140
	v_max3_f32 v141, v112, v113, v141
	v_max3_f32 v139, v139, v140, v141
	v_mov_b32_e32 v140, v139
	s_nop 1
	v_permlane16_swap_b32_e32 v139, v140
	v_max_f32_e32 v139, v139, v140
	v_mov_b32_e32 v140, v139
	s_nop 1
	v_permlane32_swap_b32_e32 v139, v140
	s_and_saveexec_b64 s[8:9], s[2:3]
	s_xor_b64 s[2:3], exec, s[8:9]
	s_cbranch_execz .LBB0_404
	v_or_b32_e32 v141, 16, v138
	v_lshlrev_b32_e32 v136, 2, v137
	v_sub_u32_e32 v137, v141, v136
	v_cmp_ge_i32_e32 vcc, v137, v126
	v_cmp_le_i32_e64 s[38:39], v137, v127
	s_and_b64 vcc, vcc, s[38:39]
	v_xad_u32 v137, v136, -1, v141
	v_cndmask_b32_e32 v100, v212, v100, vcc
	v_cmp_ge_i32_e32 vcc, v137, v126
	v_cmp_le_i32_e64 s[38:39], v137, v127
	v_or_b32_e32 v137, 2, v136
	s_and_b64 vcc, vcc, s[38:39]
	v_sub_u32_e32 v137, v141, v137
	v_cndmask_b32_e32 v101, v212, v101, vcc
	v_cmp_ge_i32_e32 vcc, v137, v126
	v_cmp_le_i32_e64 s[38:39], v137, v127
	v_or_b32_e32 v137, 3, v136
	s_and_b64 vcc, vcc, s[38:39]
	v_sub_u32_e32 v137, v141, v137
	v_cndmask_b32_e32 v102, v212, v102, vcc
	v_cmp_ge_i32_e32 vcc, v137, v126
	v_cmp_le_i32_e64 s[38:39], v137, v127
	s_and_b64 vcc, vcc, s[38:39]
	v_sub_u32_e32 v137, v138, v136
	v_cndmask_b32_e32 v103, v212, v103, vcc
	v_cmp_ge_i32_e32 vcc, v137, v126
	v_cmp_le_i32_e64 s[38:39], v137, v127
	v_or_b32_e32 v137, 17, v136
	s_and_b64 vcc, vcc, s[38:39]
	v_sub_u32_e32 v137, v141, v137
	v_cndmask_b32_e32 v96, v212, v96, vcc
	v_cmp_ge_i32_e32 vcc, v137, v126
	v_cmp_le_i32_e64 s[38:39], v137, v127
	v_or_b32_e32 v137, 18, v136
	s_and_b64 vcc, vcc, s[38:39]
	v_sub_u32_e32 v137, v141, v137
	v_cndmask_b32_e32 v97, v212, v97, vcc
	v_cmp_ge_i32_e32 vcc, v137, v126
	v_cmp_le_i32_e64 s[38:39], v137, v127
	v_or_b32_e32 v137, 19, v136
	s_and_b64 vcc, vcc, s[38:39]
	v_sub_u32_e32 v137, v141, v137
	v_cndmask_b32_e32 v98, v212, v98, vcc
	v_cmp_ge_i32_e32 vcc, v137, v126
	v_cmp_le_i32_e64 s[38:39], v137, v127
	v_or_b32_e32 v137, 32, v136
	s_and_b64 vcc, vcc, s[38:39]
	v_sub_u32_e32 v137, v141, v137
	v_cndmask_b32_e32 v99, v212, v99, vcc
	v_cmp_ge_i32_e32 vcc, v137, v126
	v_cmp_le_i32_e64 s[38:39], v137, v127
	v_or_b32_e32 v137, 33, v136
	s_and_b64 vcc, vcc, s[38:39]
	v_sub_u32_e32 v137, v141, v137
	v_cndmask_b32_e32 v92, v212, v92, vcc
	v_cmp_ge_i32_e32 vcc, v137, v126
	v_cmp_le_i32_e64 s[38:39], v137, v127
	v_or_b32_e32 v137, 34, v136
	s_and_b64 vcc, vcc, s[38:39]
	v_sub_u32_e32 v137, v141, v137
	v_cndmask_b32_e32 v93, v212, v93, vcc
	v_cmp_ge_i32_e32 vcc, v137, v126
	v_cmp_le_i32_e64 s[38:39], v137, v127
	v_or_b32_e32 v137, 35, v136
	s_and_b64 vcc, vcc, s[38:39]
	v_sub_u32_e32 v137, v141, v137
	v_cndmask_b32_e32 v94, v212, v94, vcc
	v_cmp_ge_i32_e32 vcc, v137, v126
	v_cmp_le_i32_e64 s[38:39], v137, v127
	v_or_b32_e32 v137, 48, v136
	s_and_b64 vcc, vcc, s[38:39]
	v_sub_u32_e32 v137, v141, v137
	v_or_b32_e32 v138, 49, v136
	v_cndmask_b32_e32 v95, v212, v95, vcc
	v_sub_u32_e32 v138, v141, v138
	v_cmp_le_i32_e32 vcc, v137, v127
	v_cmp_ge_i32_e64 s[40:41], v137, v126
	v_cmp_le_i32_e64 s[38:39], v126, v138
	v_cmp_ge_i32_e64 s[42:43], v127, v138
	s_and_b64 vcc, vcc, s[40:41]
	v_or_b32_e32 v137, 50, v136
	v_cndmask_b32_e32 v104, v212, v104, vcc
	s_and_b64 vcc, s[38:39], s[42:43]
	v_sub_u32_e32 v137, v141, v137
	v_cndmask_b32_e32 v105, v212, v105, vcc
	v_cmp_ge_i32_e32 vcc, v137, v126
	v_cmp_le_i32_e64 s[38:39], v137, v127
	v_or_b32_e32 v137, 51, v136
	s_and_b64 vcc, vcc, s[38:39]
	v_sub_u32_e32 v137, v141, v137
	v_cndmask_b32_e32 v106, v212, v106, vcc
	v_cmp_ge_i32_e32 vcc, v137, v126
	v_cmp_le_i32_e64 s[38:39], v137, v127
	s_and_b64 vcc, vcc, s[38:39]
	v_cndmask_b32_e32 v107, v212, v107, vcc
	s_branch .LBB0_404

.LBB0_414:
	v_mov_b32_e32 v16, v116
	s_nop 1
	v_permlane16_swap_b32_e32 v116, v16
	v_add_f32_e32 v16, v116, v16
	v_or_b32_e32 v93, v130, v15
	v_mov_b32_e32 v17, v16
	v_cmp_eq_u32_e64 s[38:39], 0, v3
	s_nop 0
	v_permlane32_swap_b32_e32 v16, v17
	v_lshlrev_b32_e32 v92, 2, v93
	s_and_saveexec_b64 s[2:3], s[38:39]
	v_add_f32_e32 v16, v16, v17
	ds_write2st64_b32 v92, v133, v16 offset0:208 offset1:210
	s_or_b64 exec, exec, s[2:3]
	v_mov_b32_e32 v17, v117
	s_nop 1
	v_permlane16_swap_b32_e32 v117, v17
	s_movk_i32 s2, 0x110
	v_add_f32_e32 v17, v117, v17
	v_mul_lo_u32 v16, v93, s2
	s_waitcnt vmcnt(3)
	v_mov_b32_e32 v44, v17
	v_add_u32_e32 v16, v4, v16
	s_nop 0
	v_permlane32_swap_b32_e32 v17, v44
	ds_write_b128 v16, v[76:79] offset:18432
	ds_write_b128 v16, v[80:83] offset:18496
	ds_write_b128 v16, v[84:87] offset:18560
	ds_write_b128 v16, v[88:91] offset:18624
	s_and_saveexec_b64 s[2:3], s[38:39]
	v_add_f32_e32 v17, v17, v44
	v_add_u32_e32 v44, 64, v92
	ds_write2st64_b32 v44, v1, v17 offset0:208 offset1:210
	s_or_b64 exec, exec, s[2:3]
	s_and_b64 vcc, exec, s[48:49]
	ds_write_b128 v16, v[60:63] offset:22784
	ds_write_b128 v16, v[64:67] offset:22848
	ds_write_b128 v16, v[68:71] offset:22912
	ds_write_b128 v16, v[72:75] offset:22976
	s_cbranch_vccz .LBB0_329
	v_mov_b32_e32 v1, v2
	s_lshl_b32 s2, s10, 4
	v_lshl_add_u64 v[12:13], v[12:13], 0, v[0:1]
	s_add_i32 s15, s2, 0xde88
	v_mov_b32_e32 v17, 0xf149f2ca
	v_mov_b32_e32 v16, 0
	v_mov_b32_e32 v1, 0
	s_mov_b64 s[42:43], 0
	s_mov_b64 s[48:49], 0
	v_mov_b32_e32 v219, 0xc290
	v_mov_b32_e32 v222, 0xee20
	v_cmp_lt_u32_e32 vcc, 0x7f, v197
	s_nop 1
	v_cndmask_b32_e32 v219, v219, v222, vcc
	s_mov_b32 s98, 1
	v_add_u32_e32 v220, 0x10020, v5
	v_add_u32_e32 v221, v219, v5
	s_waitcnt vmcnt(0)
	ds_write_b128 v220, v[24:27]
	ds_write_b128 v220, v[20:23] offset:16
	ds_write_b128 v221, v[32:35] offset:9216
	ds_write_b128 v221, v[28:31] offset:9232
	s_add_i32 s2, s10, 1
	s_cmp_ge_i32 s2, s14
	s_cbranch_scc1 .Lmb_pre_done
	v_mov_b32_e32 v223, s15
	ds_read_b32 v153, v223 offset:8
	s_waitcnt lgkmcnt(0)
	v_add_u32_e32 v222, v153, v7
	v_mad_i64_i32 v[224:225], s[2:3], v222, s93, v[12:13]
	global_load_dwordx4 v[20:23], v[224:225], off offset:528
	global_load_dwordx4 v[24:27], v[224:225], off offset:512
	global_load_dwordx4 v[28:31], v[224:225], off offset:1040
	global_load_dwordx4 v[32:35], v[224:225], off offset:1024
.Lmb_pre_done:
	v_mov_b64_e32 v[58:59], v[42:43]
	v_mov_b64_e32 v[54:55], v[38:39]
	v_mov_b64_e32 v[56:57], v[40:41]
	v_mov_b64_e32 v[52:53], v[36:37]
	s_branch .LBB0_423

.LBB0_423:
	s_add_i32 s16, s10, 1
	s_cmp_ge_i32 s16, s14
	s_cselect_b64 s[40:41], -1, 0
	s_and_b64 vcc, exec, s[40:41]
	s_waitcnt lgkmcnt(0)
	s_barrier
	v_mov_b32_e32 v223, s15
	ds_read_b32 v77, v223
	ds_read_b32 v153, v223 offset:24
	s_cmp_eq_u32 s98, 0
	s_cselect_b32 s99, 0x10020, 0
	v_add_u32_e32 v220, s99, v5
	s_cselect_b32 s99, 1, 0
	v_mad_u32_u24 v221, v219, s99, v5
	s_cselect_b32 s99, 0, 0x10020
	s_cselect_b32 s100, 0, 0xc290
	s_cselect_b32 s101, 0, 0xee20
	s_xor_b32 s98, s98, 1
	s_cbranch_vccnz .Lmb_last
	s_waitcnt vmcnt(0)
	ds_write_b128 v220, v[24:27]
	ds_write_b128 v220, v[20:23] offset:16
	ds_write_b128 v221, v[32:35] offset:9216
	ds_write_b128 v221, v[28:31] offset:9232
	s_waitcnt lgkmcnt(4)
	s_add_i32 s2, s10, 2
	s_cmp_ge_i32 s2, s14
	s_cbranch_scc1 .LBB0_425
	v_add_u32_e32 v222, v153, v7
	v_mad_i64_i32 v[224:225], s[2:3], v222, s93, v[12:13]
	global_load_dwordx4 v[20:23], v[224:225], off offset:528
	global_load_dwordx4 v[24:27], v[224:225], off offset:512
	global_load_dwordx4 v[28:31], v[224:225], off offset:1040
	global_load_dwordx4 v[32:35], v[224:225], off offset:1024
	s_branch .LBB0_425

.LBB0_425:
	v_cmp_ne_u32_e32 vcc, 0, v77
	s_cbranch_vccz .LBB0_427
	v_mov_b32_e32 v76, v129
	s_mov_b64 s[50:51], s[46:47]
	s_mov_b64 s[2:3], s[44:45]
	s_and_saveexec_b64 s[8:9], s[48:49]
	s_cbranch_execz .LBB0_422
	s_branch .LBB0_432
.LBB0_427:
	s_add_i32 s8, s10, 4
	s_mov_b64 s[2:3], 0
	s_cmp_ge_i32 s8, s14
	s_mov_b64 s[50:51], s[46:47]
	v_mov_b32_e32 v76, v129
	s_cbranch_scc1 .LBB0_431
	v_mov_b32_e32 v1, s15
	ds_read2_b32 v[16:17], v1 offset0:15 offset1:17
	s_mov_b64 s[50:51], s[46:47]
	v_mov_b32_e32 v76, v129
	s_waitcnt lgkmcnt(0)
	v_lshlrev_b32_e32 v1, 2, v17
	ds_read_b32 v44, v1 offset:56832
	v_lshl_add_u32 v1, v16, 6, v19
	s_waitcnt lgkmcnt(0)
	v_cmp_lt_i32_e32 vcc, v1, v44
	s_and_saveexec_b64 s[8:9], vcc
	s_cbranch_execz .LBB0_430
	v_lshlrev_b32_e32 v16, 7, v17
	v_add3_u32 v1, v16, v1, v15
	ds_read_u8 v1, v1 offset:54784
	s_movk_i32 s2, 0xff
	s_waitcnt lgkmcnt(0)
	v_cmp_ne_u16_e32 vcc, s2, v1
	s_nop 1
	v_cndmask_b32_e32 v1, 0, v1, vcc
	v_and_b32_e32 v76, 0xffff, v1
	v_add_u32_e32 v1, v128, v76
	v_mad_u64_u32 v[16:17], s[2:3], v1, s93, v[8:9]
	global_load_dwordx4 v[56:59], v[16:17], off
	global_load_dwordx4 v[52:55], v[16:17], off offset:64
	s_andn2_b64 s[2:3], s[46:47], exec
	s_and_b64 s[10:11], vcc, exec
	s_or_b64 s[50:51], s[2:3], s[10:11]
	s_mov_b64 s[2:3], exec

.LBB0_432:
	v_mov_b32_e32 v90, v197
	s_nop 0
	v_and_b32_e32 v36, 15, v90
	v_bfe_u32 v91, v90, 4, 2
	v_mul_u32_u24_e32 v36, 0x90, v36
	v_lshl_add_u32 v98, v91, 4, v36
	v_add_u32_e32 v98, s99, v98
	ds_read_b128 v[36:39], v98
	ds_read_b128 v[86:89], v98 offset:64
	ds_read_b128 v[78:81], v98 offset:4608
	ds_read_b128 v[94:97], v98 offset:4672
	ds_read_b128 v[40:43], v98 offset:2304
	ds_read_b128 v[82:85], v98 offset:6912
	s_waitcnt lgkmcnt(5)
	v_mfma_f32_16x16x32_bf16 v[36:39], v[36:39], v[44:47], 0
	s_waitcnt lgkmcnt(3)
	v_mfma_f32_16x16x32_bf16 v[78:81], v[78:81], v[44:47], 0
	v_mfma_f32_16x16x32_bf16 v[86:89], v[86:89], v[48:51], v[36:39]
	s_nop 4
	ds_read_b128 v[36:39], v98 offset:2368
	s_waitcnt lgkmcnt(3)
	v_mfma_f32_16x16x32_bf16 v[78:81], v[94:97], v[48:51], v[78:81]
	ds_read_b128 v[94:97], v98 offset:6976
	s_waitcnt lgkmcnt(3)
	v_mfma_f32_16x16x32_bf16 v[40:43], v[40:43], v[44:47], 0
	s_waitcnt lgkmcnt(2)
	v_mfma_f32_16x16x32_bf16 v[82:85], v[82:85], v[44:47], 0
	s_waitcnt lgkmcnt(1)
	v_mfma_f32_16x16x32_bf16 v[38:41], v[36:39], v[48:51], v[40:43]
	v_max_f32_e32 v36, v88, v89
	s_waitcnt lgkmcnt(0)
	v_mfma_f32_16x16x32_bf16 v[82:85], v[94:97], v[48:51], v[82:85]
	v_bfe_u32 v186, v90, 2, 2
	v_lshlrev_b32_e32 v187, 3, v90
	v_lshl_or_b32 v186, v91, 2, v186
	v_and_b32_e32 v187, 24, v187
	v_mad_u32_u24 v186, v186, s0, v187
	v_add_u32_e32 v187, s101, v186
	v_add_u32_e32 v186, s100, v186
	ds_read_b64_tr_b16 v[154:155], v186 offset:9216
	ds_read_b64_tr_b16 v[156:157], v186 offset:11520
	ds_read_b64_tr_b16 v[158:159], v186 offset:9248
	ds_read_b64_tr_b16 v[160:161], v186 offset:11552
	ds_read_b64_tr_b16 v[162:163], v186 offset:9280
	ds_read_b64_tr_b16 v[164:165], v186 offset:11584
	ds_read_b64_tr_b16 v[166:167], v186 offset:9312
	ds_read_b64_tr_b16 v[168:169], v186 offset:11616
	ds_read_b64_tr_b16 v[170:171], v187 offset:13824
	ds_read_b64_tr_b16 v[172:173], v187 offset:16128
	ds_read_b64_tr_b16 v[174:175], v187 offset:13856
	ds_read_b64_tr_b16 v[176:177], v187 offset:16160
	ds_read_b64_tr_b16 v[178:179], v187 offset:13888
	ds_read_b64_tr_b16 v[180:181], v187 offset:16192
	ds_read_b64_tr_b16 v[182:183], v187 offset:13920
	ds_read_b64_tr_b16 v[184:185], v187 offset:16224
	v_max3_f32 v36, v86, v87, v36
	s_nop 1
	v_max_f32_e32 v37, v40, v41
	v_max3_f32 v37, v38, v39, v37
	v_max3_f32 v36, v36, s28, v37
	v_max_f32_e32 v37, v80, v81
	v_max_f32_e32 v43, v84, v84
	v_max_f32_e32 v42, v43, v85
	v_max3_f32 v37, v78, v79, v37
	v_max3_f32 v42, v82, v83, v42
	v_max3_f32 v36, v36, v37, v42
	v_mov_b32_e32 v37, v36
	s_nop 1
	v_permlane16_swap_b32_e32 v36, v37
	v_max_f32_e32 v36, v36, v37
	v_mov_b32_e32 v37, v36
	s_nop 1
	v_permlane32_swap_b32_e32 v36, v37
	v_max3_f32 v37, v17, v36, v37
	v_mul_f32_e32 v36, 0x3e38aa3b, v37
	v_cmp_ngt_f32_e32 vcc, s36, v37
	v_sub_f32_e32 v17, v17, v37
	v_mul_f32_e32 v17, 0x3e38aa3b, v17
	v_cndmask_b32_e32 v36, 0, v36, vcc
	v_fma_f32 v42, v86, s29, -v36
	v_exp_f32_e32 v86, v42
	v_fma_f32 v43, v87, s29, -v36
	v_exp_f32_e32 v87, v43
	v_fma_f32 v43, v88, s29, -v36
	v_exp_f32_e32 v88, v43
	v_fma_f32 v43, v89, s29, -v36
	v_exp_f32_e32 v89, v43
	v_fma_f32 v38, v38, s29, -v36
	v_add_f32_e32 v42, 0, v86
	v_exp_f32_e32 v94, v38
	v_fma_f32 v39, v39, s29, -v36
	v_add_f32_e32 v42, v87, v42
	v_exp_f32_e32 v39, v39
	v_fma_f32 v40, v40, s29, -v36
	v_add_f32_e32 v42, v88, v42
	v_exp_f32_e32 v95, v40
	v_fma_f32 v40, v41, s29, -v36
	v_add_f32_e32 v42, v89, v42
	v_exp_f32_e32 v96, v40
	v_fma_f32 v40, v78, s29, -v36
	v_add_f32_e32 v38, v94, v42
	v_exp_f32_e32 v97, v40
	v_fma_f32 v40, v79, s29, -v36
	v_add_f32_e32 v38, v39, v38
	v_exp_f32_e32 v98, v40
	v_fma_f32 v40, v80, s29, -v36
	v_add_f32_e32 v38, v95, v38
	v_exp_f32_e32 v99, v40
	v_fma_f32 v40, v81, s29, -v36
	v_add_f32_e32 v38, v96, v38
	v_exp_f32_e32 v100, v40
	v_fma_f32 v40, v82, s29, -v36
	v_add_f32_e32 v38, v97, v38
	v_exp_f32_e32 v101, v40
	v_fma_f32 v40, v83, s29, -v36
	v_add_f32_e32 v38, v98, v38
	v_exp_f32_e32 v102, v40
	v_fma_f32 v40, v84, s29, -v36
	v_add_f32_e32 v38, v99, v38
	v_exp_f32_e32 v103, v40
	v_fma_f32 v36, v85, s29, -v36
	v_add_f32_e32 v38, v100, v38
	v_exp_f32_e32 v104, v36
	v_add_f32_e32 v38, v101, v38
	v_exp_f32_e32 v36, v17
	v_add_f32_e32 v38, v102, v38
	v_add_f32_e32 v38, v103, v38
	v_add_f32_e32 v38, v104, v38
	v_fmac_f32_e32 v38, v16, v36
	v_pk_mul_f32 v[42:43], v[62:63], v[36:37] op_sel_hi:[1,0]
	v_pk_mul_f32 v[40:41], v[60:61], v[36:37] op_sel_hi:[1,0]
	v_pk_mul_f32 v[62:63], v[66:67], v[36:37] op_sel_hi:[1,0]
	v_pk_mul_f32 v[60:61], v[64:65], v[36:37] op_sel_hi:[1,0]
	v_pk_mul_f32 v[66:67], v[70:71], v[36:37] op_sel_hi:[1,0]
	v_pk_mul_f32 v[64:65], v[68:69], v[36:37] op_sel_hi:[1,0]
	v_pk_mul_f32 v[70:71], v[74:75], v[36:37] op_sel_hi:[1,0]
	v_pk_mul_f32 v[68:69], v[72:73], v[36:37] op_sel_hi:[1,0]
	v_cvt_pk_bf16_f32 v72, v86, v87
	v_cvt_pk_bf16_f32 v73, v88, v89
	v_cvt_pk_bf16_f32 v74, v94, v39
	v_cvt_pk_bf16_f32 v75, v95, v96
	v_cvt_pk_bf16_f32 v86, v97, v98
	v_cvt_pk_bf16_f32 v87, v99, v100
	v_cvt_pk_bf16_f32 v88, v101, v102
	v_cvt_pk_bf16_f32 v89, v103, v104
	v_cmp_ne_u32_e32 vcc, 3, v77
	s_waitcnt lgkmcnt(14)
	v_mfma_f32_16x16x32_bf16 v[40:43], v[154:157], v[72:75], v[40:43]
	s_waitcnt lgkmcnt(12)
	v_mfma_f32_16x16x32_bf16 v[78:81], v[158:161], v[72:75], v[60:63]
	s_and_b64 vcc, exec, vcc
	s_waitcnt lgkmcnt(10)
	v_mfma_f32_16x16x32_bf16 v[82:85], v[162:165], v[72:75], v[64:67]
	s_waitcnt lgkmcnt(8)
	v_mfma_f32_16x16x32_bf16 v[72:75], v[166:169], v[72:75], v[68:71]
	s_waitcnt lgkmcnt(6)
	v_mfma_f32_16x16x32_bf16 v[60:63], v[170:173], v[86:89], v[40:43]
	s_waitcnt lgkmcnt(4)
	v_mfma_f32_16x16x32_bf16 v[64:67], v[174:177], v[86:89], v[78:81]
	s_waitcnt lgkmcnt(2)
	v_mfma_f32_16x16x32_bf16 v[68:71], v[178:181], v[86:89], v[82:85]
	s_waitcnt lgkmcnt(0)
	v_mfma_f32_16x16x32_bf16 v[72:75], v[182:185], v[86:89], v[72:75]
	s_cbranch_vccnz .LBB0_421
	v_mov_b32_e32 v16, v38
	v_mov_b32_e32 v17, v38
	s_nop 1
	v_permlane16_swap_b32_e32 v16, v17
	v_add_f32_e32 v39, v16, v17
	v_mov_b32_e32 v40, v39
	s_nop 1
	v_permlane32_swap_b32_e32 v39, v40
	s_and_saveexec_b64 s[10:11], s[42:43]
	s_cbranch_execz .LBB0_420
	v_lshlrev_b32_e32 v41, 2, v1
	ds_read2st64_b32 v[16:17], v41 offset0:208 offset1:210
	s_movk_i32 s17, 0x110
	v_mad_u64_u32 v[82:83], s[20:21], v1, s17, v[4:5]
	s_waitcnt lgkmcnt(0)
	v_max_f32_e32 v36, v16, v16
	v_max_f32_e32 v42, v36, v37
	v_sub_f32_e32 v36, v37, v42
	v_sub_f32_e32 v16, v16, v42
	v_mul_f32_e32 v36, 0x3e38aa3b, v36
	v_mul_f32_e32 v16, 0x3e38aa3b, v16
	v_exp_f32_e32 v36, v36
	ds_read_b128 v[78:81], v82 offset:18432
	v_exp_f32_e32 v16, v16
	v_pk_mul_f32 v[84:85], v[62:63], v[36:37] op_sel_hi:[1,0]
	v_pk_mul_f32 v[86:87], v[60:61], v[36:37] op_sel_hi:[1,0]
	s_waitcnt lgkmcnt(0)
	v_pk_fma_f32 v[80:81], v[80:81], v[16:17], v[84:85] op_sel_hi:[1,0,1]
	v_pk_fma_f32 v[78:79], v[78:79], v[16:17], v[86:87] op_sel_hi:[1,0,1]
	ds_write_b128 v82, v[78:81] offset:18432
	ds_read_b128 v[78:81], v82 offset:18496
	v_pk_mul_f32 v[84:85], v[66:67], v[36:37] op_sel_hi:[1,0]
	v_pk_mul_f32 v[86:87], v[64:65], v[36:37] op_sel_hi:[1,0]
	s_waitcnt lgkmcnt(0)
	v_pk_fma_f32 v[80:81], v[80:81], v[16:17], v[84:85] op_sel_hi:[1,0,1]
	v_pk_fma_f32 v[78:79], v[78:79], v[16:17], v[86:87] op_sel_hi:[1,0,1]
	ds_write_b128 v82, v[78:81] offset:18496
	ds_read_b128 v[78:81], v82 offset:18560
	v_pk_mul_f32 v[84:85], v[70:71], v[36:37] op_sel_hi:[1,0]
	v_pk_mul_f32 v[86:87], v[68:69], v[36:37] op_sel_hi:[1,0]
	s_waitcnt lgkmcnt(0)
	v_pk_fma_f32 v[80:81], v[16:17], v[80:81], v[84:85] op_sel_hi:[0,1,1]
	v_pk_fma_f32 v[78:79], v[16:17], v[78:79], v[86:87] op_sel_hi:[0,1,1]
	ds_write_b128 v82, v[78:81] offset:18560
	ds_read_b128 v[78:81], v82 offset:18624
	s_waitcnt lgkmcnt(0)
	v_pk_mul_f32 v[80:81], v[16:17], v[80:81] op_sel_hi:[0,1]
	v_pk_mul_f32 v[78:79], v[16:17], v[78:79] op_sel_hi:[0,1]
	v_pk_fma_f32 v[80:81], v[74:75], v[36:37], v[80:81] op_sel_hi:[1,0,1]
	v_pk_fma_f32 v[78:79], v[72:73], v[36:37], v[78:79] op_sel_hi:[1,0,1]
	ds_write_b128 v82, v[78:81] offset:18624
	s_and_b64 exec, exec, s[38:39]
	s_cbranch_execz .LBB0_420
	v_add_f32_e32 v39, v39, v40
	v_mul_f32_e32 v36, v39, v36
	v_fmac_f32_e32 v36, v17, v16
	ds_write2st64_b32 v41, v42, v36 offset0:208 offset1:210
	s_branch .LBB0_420

.LBB0_445:
	s_andn2_saveexec_b64 s[2:3], s[2:3]
	s_or_b64 exec, exec, s[2:3]
	v_max3_f32 v142, v141, v146, v147
	v_mul_f32_e32 v143, 0x3e38aa3b, v142
	v_cmp_ngt_f32_e32 vcc, s36, v142
	v_sub_f32_e32 v141, v141, v142
	v_mul_f32_e32 v141, 0x3e38aa3b, v141
	v_cndmask_b32_e32 v143, 0, v143, vcc
	v_fma_f32 v128, v128, s29, -v143
	v_exp_f32_e32 v144, v128
	v_fma_f32 v129, v129, s29, -v143
	v_exp_f32_e32 v129, v129
	v_fma_f32 v130, v130, s29, -v143
	v_exp_f32_e32 v130, v130
	v_fma_f32 v131, v131, s29, -v143
	v_exp_f32_e32 v131, v131
	v_fma_f32 v124, v124, s29, -v143
	v_add_f32_e32 v128, 0, v144
	v_exp_f32_e32 v145, v124
	v_add_f32_e32 v128, v129, v128
	v_add_f32_e32 v128, v130, v128
	v_fma_f32 v125, v125, s29, -v143
	v_add_f32_e32 v128, v131, v128
	v_exp_f32_e32 v146, v125
	v_fma_f32 v125, v126, s29, -v143
	v_fma_f32 v117, v117, s29, -v143
	v_add_f32_e32 v124, v145, v128
	v_exp_f32_e32 v147, v125
	v_fma_f32 v125, v127, s29, -v143
	v_exp_f32_e32 v127, v117
	v_fma_f32 v117, v118, s29, -v143
	v_exp_f32_e32 v128, v141
	v_exp_f32_e32 v149, v117
	v_fma_f32 v117, v119, s29, -v143
	v_exp_f32_e32 v150, v117
	v_fma_f32 v117, v120, s29, -v143
	v_exp_f32_e32 v151, v117
	v_fma_f32 v117, v121, s29, -v143
	v_exp_f32_e32 v152, v117
	v_fma_f32 v117, v122, s29, -v143
	v_pk_mul_f32 v[120:121], v[88:89], v[128:129] op_sel_hi:[1,0]
	v_pk_mul_f32 v[88:89], v[92:93], v[128:129] op_sel_hi:[1,0]
	v_exp_f32_e32 v153, v117
	v_fma_f32 v117, v123, s29, -v143
	v_pk_mul_f32 v[122:123], v[90:91], v[128:129] op_sel_hi:[1,0]
	v_pk_mul_f32 v[90:91], v[94:95], v[128:129] op_sel_hi:[1,0]
	v_max_f32_e32 v92, v110, v111
	v_max_f32_e32 v93, v106, v107
	v_max3_f32 v92, v108, v109, v92
	v_max3_f32 v93, v104, v105, v93
	v_max3_f32 v92, v92, s28, v93
	v_max_f32_e32 v93, v102, v103
	v_max_f32_e32 v95, v114, v114
	v_max_f32_e32 v94, v95, v115
	v_exp_f32_e32 v148, v125
	v_fma_f32 v116, v116, s29, -v143
	v_max3_f32 v93, v100, v101, v93
	v_max3_f32 v94, v112, v113, v94
	v_exp_f32_e32 v126, v116
	v_max3_f32 v92, v92, v93, v94
	v_add_f32_e32 v124, v146, v124
	v_mov_b32_e32 v93, v92
	v_add_f32_e32 v124, v147, v124
	s_nop 0
	v_permlane16_swap_b32_e32 v92, v93
	v_add_f32_e32 v124, v148, v124
	v_add_f32_e32 v116, v126, v124
	v_max_f32_e32 v92, v92, v93
	v_add_f32_e32 v116, v127, v116
	v_mov_b32_e32 v93, v92
	v_add_f32_e32 v116, v149, v116
	s_nop 0
	v_permlane32_swap_b32_e32 v92, v93
	v_add_f32_e32 v116, v150, v116
	v_exp_f32_e32 v143, v117
	v_max3_f32 v125, v139, v92, v93
	v_add_f32_e32 v116, v151, v116
	v_mul_f32_e32 v93, 0x3e38aa3b, v125
	v_cmp_ngt_f32_e32 vcc, s36, v125
	v_add_f32_e32 v116, v152, v116
	v_add_f32_e32 v116, v153, v116
	v_cndmask_b32_e32 v93, 0, v93, vcc
	v_fma_f32 v94, v108, s29, -v93
	v_add_f32_e32 v124, v143, v116
	v_pk_mul_f32 v[116:117], v[84:85], v[128:129] op_sel_hi:[1,0]
	v_pk_mul_f32 v[84:85], v[96:97], v[128:129] op_sel_hi:[1,0]
	v_exp_f32_e32 v96, v94
	v_fma_f32 v95, v109, s29, -v93
	v_exp_f32_e32 v97, v95
	v_fma_f32 v95, v110, s29, -v93
	v_pk_mul_f32 v[118:119], v[86:87], v[128:129] op_sel_hi:[1,0]
	v_pk_mul_f32 v[86:87], v[98:99], v[128:129] op_sel_hi:[1,0]
	v_exp_f32_e32 v98, v95
	v_fma_f32 v95, v111, s29, -v93
	v_exp_f32_e32 v99, v95
	v_fma_f32 v95, v104, s29, -v93
	v_add_f32_e32 v94, 0, v96
	v_exp_f32_e32 v104, v95
	v_fma_f32 v95, v105, s29, -v93
	v_add_f32_e32 v94, v97, v94
	v_exp_f32_e32 v105, v95
	v_fma_f32 v95, v106, s29, -v93
	v_add_f32_e32 v94, v98, v94
	v_exp_f32_e32 v106, v95
	v_fma_f32 v95, v107, s29, -v93
	v_add_f32_e32 v94, v99, v94
	v_exp_f32_e32 v107, v95
	v_fma_f32 v95, v100, s29, -v93
	v_fmac_f32_e32 v124, v140, v128
	v_add_f32_e32 v94, v104, v94
	v_exp_f32_e32 v128, v95
	v_fma_f32 v95, v101, s29, -v93
	v_sub_f32_e32 v92, v139, v125
	v_add_f32_e32 v94, v105, v94
	v_exp_f32_e32 v139, v95
	v_fma_f32 v95, v102, s29, -v93
	v_lshrrev_b32_e32 v1, 2, v1
	v_lshlrev_b32_e32 v0, 3, v0
	v_add_f32_e32 v94, v106, v94
	v_exp_f32_e32 v140, v95
	v_fma_f32 v95, v103, s29, -v93
	v_or_b32_e32 v1, v3, v1
	v_and_b32_e32 v0, 24, v0
	v_add_f32_e32 v94, v107, v94
	v_exp_f32_e32 v141, v95
	v_fma_f32 v95, v112, s29, -v93
	v_mad_i32_i24 v0, v1, s0, v0
	v_add_f32_e32 v94, v128, v94
	v_exp_f32_e32 v154, v95
	v_fma_f32 v95, v113, s29, -v93
	v_cvt_pk_bf16_f32 v96, v96, v97
	v_cvt_pk_bf16_f32 v97, v98, v99
	v_cvt_pk_bf16_f32 v98, v104, v105
	v_cvt_pk_bf16_f32 v99, v106, v107
	ds_read_b64_tr_b16 v[162:163], v0 offset:29952
	ds_read_b64_tr_b16 v[160:161], v0 offset:27648
	ds_read_b64_tr_b16 v[164:165], v0 offset:27680
	ds_read_b64_tr_b16 v[166:167], v0 offset:29984
	ds_read_b64_tr_b16 v[168:169], v0 offset:27712
	ds_read_b64_tr_b16 v[170:171], v0 offset:30016
	ds_read_b64_tr_b16 v[172:173], v0 offset:27744
	ds_read_b64_tr_b16 v[174:175], v0 offset:30048
	ds_read_b64_tr_b16 v[176:177], v0 offset:32256
	ds_read_b64_tr_b16 v[178:179], v0 offset:34560
	ds_read_b64_tr_b16 v[180:181], v0 offset:32288
	ds_read_b64_tr_b16 v[182:183], v0 offset:34592
	ds_read_b64_tr_b16 v[184:185], v0 offset:32320
	ds_read_b64_tr_b16 v[186:187], v0 offset:34624
	ds_read_b64_tr_b16 v[188:189], v0 offset:32352
	ds_read_b64_tr_b16 v[190:191], v0 offset:34656
	v_add_f32_e32 v94, v139, v94
	v_exp_f32_e32 v155, v95
	v_fma_f32 v95, v114, s29, -v93
	v_add_f32_e32 v94, v140, v94
	v_exp_f32_e32 v156, v95
	v_fma_f32 v93, v115, s29, -v93
	v_mul_f32_e32 v92, 0x3e38aa3b, v92
	v_add_f32_e32 v94, v141, v94
	v_exp_f32_e32 v157, v93
	v_add_f32_e32 v94, v154, v94
	v_exp_f32_e32 v92, v92
	v_add_f32_e32 v94, v155, v94
	v_add_f32_e32 v94, v156, v94
	v_add_f32_e32 v158, v157, v94
	v_fmac_f32_e32 v158, v137, v92
	v_pk_mul_f32 v[70:71], v[70:71], v[92:93] op_sel_hi:[1,0]
	v_pk_mul_f32 v[68:69], v[68:69], v[92:93] op_sel_hi:[1,0]
	v_pk_mul_f32 v[74:75], v[74:75], v[92:93] op_sel_hi:[1,0]
	v_pk_mul_f32 v[72:73], v[72:73], v[92:93] op_sel_hi:[1,0]
	v_pk_mul_f32 v[78:79], v[78:79], v[92:93] op_sel_hi:[1,0]
	v_pk_mul_f32 v[76:77], v[76:77], v[92:93] op_sel_hi:[1,0]
	v_pk_mul_f32 v[82:83], v[82:83], v[92:93] op_sel_hi:[1,0]
	v_pk_mul_f32 v[80:81], v[80:81], v[92:93] op_sel_hi:[1,0]
	v_cvt_pk_bf16_f32 v92, v144, v129
	v_cvt_pk_bf16_f32 v93, v130, v131
	v_cvt_pk_bf16_f32 v94, v145, v146
	v_cvt_pk_bf16_f32 v95, v147, v148
	s_waitcnt lgkmcnt(14)
	v_mfma_f32_16x16x32_bf16 v[68:71], v[160:163], v[96:99], v[68:71]
	v_mov_b32_e32 v137, v158
	v_mfma_f32_16x16x32_bf16 v[108:111], v[160:163], v[92:95], v[116:119]
	s_waitcnt lgkmcnt(12)
	v_mfma_f32_16x16x32_bf16 v[100:103], v[164:167], v[92:95], v[120:123]
	s_nop 0
	v_cvt_pk_bf16_f32 v116, v128, v139
	v_cvt_pk_bf16_f32 v117, v140, v141
	v_cvt_pk_bf16_f32 v118, v154, v155
	v_mfma_f32_16x16x32_bf16 v[72:75], v[164:167], v[96:99], v[72:75]
	v_cvt_pk_bf16_f32 v119, v156, v157
	v_mov_b32_e32 v141, v142
	s_waitcnt lgkmcnt(10)
	v_mfma_f32_16x16x32_bf16 v[112:115], v[168:171], v[92:95], v[88:91]
	s_nop 2
	v_mov_b32_e32 v140, v124
	v_mov_b32_e32 v139, v125
	v_mfma_f32_16x16x32_bf16 v[76:79], v[168:171], v[96:99], v[76:79]
	s_waitcnt lgkmcnt(8)
	v_mfma_f32_16x16x32_bf16 v[104:107], v[172:175], v[92:95], v[84:87]
	v_mfma_f32_16x16x32_bf16 v[80:83], v[172:175], v[96:99], v[80:83]
	v_cvt_pk_bf16_f32 v96, v126, v127
	v_cvt_pk_bf16_f32 v97, v149, v150
	v_cvt_pk_bf16_f32 v98, v151, v152
	v_cvt_pk_bf16_f32 v99, v153, v143
	s_waitcnt lgkmcnt(6)
	v_mfma_f32_16x16x32_bf16 v[68:71], v[176:179], v[116:119], v[68:71]
	v_mfma_f32_16x16x32_bf16 v[84:87], v[176:179], v[96:99], v[108:111]
	s_waitcnt lgkmcnt(4)
	v_mfma_f32_16x16x32_bf16 v[88:91], v[180:183], v[96:99], v[100:103]
	s_nop 2
	v_mfma_f32_16x16x32_bf16 v[72:75], v[180:183], v[116:119], v[72:75]
	s_waitcnt lgkmcnt(2)
	v_mfma_f32_16x16x32_bf16 v[92:95], v[184:187], v[96:99], v[112:115]
	v_mfma_f32_16x16x32_bf16 v[76:79], v[184:187], v[116:119], v[76:79]
	s_waitcnt lgkmcnt(0)
	v_mfma_f32_16x16x32_bf16 v[96:99], v[188:191], v[96:99], v[104:107]
	v_mfma_f32_16x16x32_bf16 v[80:83], v[188:191], v[116:119], v[80:83]

.LBB0_452:
	s_or_b64 exec, exec, s[8:9]
	v_max_f32_e32 v146, v130, v131
	v_max_f32_e32 v147, v126, v127
	v_max3_f32 v146, v128, v129, v146
	v_max3_f32 v147, v124, v125, v147
	v_max3_f32 v146, v146, s28, v147
	v_max_f32_e32 v147, v118, v119
	v_max_f32_e32 v149, v122, v122
	v_max_f32_e32 v148, v149, v123
	v_max3_f32 v147, v116, v117, v147
	v_max3_f32 v148, v120, v121, v148
	v_max3_f32 v146, v146, v147, v148
	v_mov_b32_e32 v147, v146
	s_nop 1
	v_permlane16_swap_b32_e32 v146, v147
	v_max_f32_e32 v146, v146, v147
	v_mov_b32_e32 v147, v146
	s_nop 1
	v_permlane32_swap_b32_e32 v146, v147
	s_and_saveexec_b64 s[8:9], s[2:3]
	s_xor_b64 s[2:3], exec, s[8:9]
	s_cbranch_execz .LBB0_454
	v_or_b32_e32 v148, 16, v145
	v_lshlrev_b32_e32 v142, 2, v144
	v_sub_u32_e32 v144, v148, v142
	v_cmp_ge_i32_e64 s[38:39], v144, v143
	v_cmp_le_i32_e64 s[40:41], v144, v0
	s_and_b64 s[38:39], s[38:39], s[40:41]
	v_xad_u32 v144, v142, -1, v148
	v_cndmask_b32_e64 v108, v212, v108, s[38:39]
	v_cmp_ge_i32_e64 s[38:39], v144, v143
	v_cmp_le_i32_e64 s[40:41], v144, v0
	v_or_b32_e32 v144, 2, v142
	s_and_b64 s[38:39], s[38:39], s[40:41]
	v_sub_u32_e32 v144, v148, v144
	v_cndmask_b32_e64 v109, v212, v109, s[38:39]
	v_cmp_ge_i32_e64 s[38:39], v144, v143
	v_cmp_le_i32_e64 s[40:41], v144, v0
	v_or_b32_e32 v144, 3, v142
	s_and_b64 s[38:39], s[38:39], s[40:41]
	v_sub_u32_e32 v144, v148, v144
	v_cndmask_b32_e64 v110, v212, v110, s[38:39]
	v_cmp_ge_i32_e64 s[38:39], v144, v143
	v_cmp_le_i32_e64 s[40:41], v144, v0
	s_and_b64 s[38:39], s[38:39], s[40:41]
	v_sub_u32_e32 v144, v145, v142
	v_cndmask_b32_e64 v111, v212, v111, s[38:39]
	v_cmp_ge_i32_e64 s[38:39], v144, v143
	v_cmp_le_i32_e64 s[40:41], v144, v0
	v_or_b32_e32 v144, 17, v142
	s_and_b64 s[38:39], s[38:39], s[40:41]
	v_sub_u32_e32 v144, v148, v144
	v_cndmask_b32_e64 v104, v212, v104, s[38:39]
	v_cmp_ge_i32_e64 s[38:39], v144, v143
	v_cmp_le_i32_e64 s[40:41], v144, v0
	v_or_b32_e32 v144, 18, v142
	s_and_b64 s[38:39], s[38:39], s[40:41]
	v_sub_u32_e32 v144, v148, v144
	v_cndmask_b32_e64 v105, v212, v105, s[38:39]
	v_cmp_ge_i32_e64 s[38:39], v144, v143
	v_cmp_le_i32_e64 s[40:41], v144, v0
	v_or_b32_e32 v144, 19, v142
	s_and_b64 s[38:39], s[38:39], s[40:41]
	v_sub_u32_e32 v144, v148, v144
	v_cndmask_b32_e64 v106, v212, v106, s[38:39]
	v_cmp_ge_i32_e64 s[38:39], v144, v143
	v_cmp_le_i32_e64 s[40:41], v144, v0
	v_or_b32_e32 v144, 32, v142
	s_and_b64 s[38:39], s[38:39], s[40:41]
	v_sub_u32_e32 v144, v148, v144
	v_cndmask_b32_e64 v107, v212, v107, s[38:39]
	v_cmp_ge_i32_e64 s[38:39], v144, v143
	v_cmp_le_i32_e64 s[40:41], v144, v0
	v_or_b32_e32 v144, 33, v142
	s_and_b64 s[38:39], s[38:39], s[40:41]
	v_sub_u32_e32 v144, v148, v144
	v_cndmask_b32_e64 v100, v212, v100, s[38:39]
	v_cmp_ge_i32_e64 s[38:39], v144, v143
	v_cmp_le_i32_e64 s[40:41], v144, v0
	v_or_b32_e32 v144, 34, v142
	s_and_b64 s[38:39], s[38:39], s[40:41]
	v_sub_u32_e32 v144, v148, v144
	v_cndmask_b32_e64 v101, v212, v101, s[38:39]
	v_cmp_ge_i32_e64 s[38:39], v144, v143
	v_cmp_le_i32_e64 s[40:41], v144, v0
	v_or_b32_e32 v144, 35, v142
	s_and_b64 s[38:39], s[38:39], s[40:41]
	v_sub_u32_e32 v144, v148, v144
	v_cndmask_b32_e64 v102, v212, v102, s[38:39]
	v_cmp_ge_i32_e64 s[38:39], v144, v143
	v_cmp_le_i32_e64 s[40:41], v144, v0
	v_or_b32_e32 v144, 48, v142
	s_and_b64 s[38:39], s[38:39], s[40:41]
	v_sub_u32_e32 v144, v148, v144
	v_cndmask_b32_e64 v103, v212, v103, s[38:39]
	v_cmp_ge_i32_e64 s[38:39], v144, v143
	v_cmp_le_i32_e64 s[40:41], v144, v0
	v_or_b32_e32 v144, 49, v142
	s_and_b64 s[38:39], s[38:39], s[40:41]
	v_sub_u32_e32 v144, v148, v144
	v_cndmask_b32_e64 v112, v212, v112, s[38:39]
	v_cmp_ge_i32_e64 s[38:39], v144, v143
	v_cmp_le_i32_e64 s[40:41], v144, v0
	v_or_b32_e32 v144, 50, v142
	s_and_b64 s[38:39], s[38:39], s[40:41]
	v_sub_u32_e32 v144, v148, v144
	v_cndmask_b32_e64 v113, v212, v113, s[38:39]
	v_cmp_ge_i32_e64 s[38:39], v144, v143
	v_cmp_le_i32_e64 s[40:41], v144, v0
	v_or_b32_e32 v144, 51, v142
	s_and_b64 s[38:39], s[38:39], s[40:41]
	v_sub_u32_e32 v144, v148, v144
	v_cndmask_b32_e64 v114, v212, v114, s[38:39]
	v_cmp_ge_i32_e64 s[38:39], v144, v143
	v_cmp_le_i32_e64 s[40:41], v144, v0
	s_and_b64 s[38:39], s[38:39], s[40:41]
	v_cndmask_b32_e64 v115, v212, v115, s[38:39]
.LBB0_454:
	s_andn2_saveexec_b64 s[2:3], s[2:3]
	s_or_b64 exec, exec, s[2:3]
	v_max3_f32 v143, v141, v146, v147
	v_mul_f32_e32 v144, 0x3e38aa3b, v143
	v_cmp_ngt_f32_e64 s[38:39], s36, v143
	v_sub_f32_e32 v141, v141, v143
	v_mul_f32_e32 v141, 0x3e38aa3b, v141
	v_cndmask_b32_e64 v144, 0, v144, s[38:39]
	v_fma_f32 v128, v128, s29, -v144
	v_exp_f32_e32 v145, v128
	v_fma_f32 v129, v129, s29, -v144
	v_exp_f32_e32 v129, v129
	v_fma_f32 v130, v130, s29, -v144
	v_exp_f32_e32 v130, v130
	v_fma_f32 v131, v131, s29, -v144
	v_exp_f32_e32 v131, v131
	v_fma_f32 v124, v124, s29, -v144
	v_add_f32_e32 v128, 0, v145
	v_exp_f32_e32 v146, v124
	v_add_f32_e32 v128, v129, v128
	v_add_f32_e32 v128, v130, v128
	v_fma_f32 v125, v125, s29, -v144
	v_add_f32_e32 v128, v131, v128
	v_exp_f32_e32 v147, v125
	v_fma_f32 v125, v126, s29, -v144
	v_fma_f32 v117, v117, s29, -v144
	v_add_f32_e32 v124, v146, v128
	v_exp_f32_e32 v148, v125
	v_fma_f32 v125, v127, s29, -v144
	v_exp_f32_e32 v127, v117
	v_fma_f32 v117, v118, s29, -v144
	v_exp_f32_e32 v128, v141
	v_exp_f32_e32 v150, v117
	v_fma_f32 v117, v119, s29, -v144
	v_exp_f32_e32 v151, v117
	v_fma_f32 v117, v120, s29, -v144
	v_exp_f32_e32 v152, v117
	v_fma_f32 v117, v121, s29, -v144
	v_exp_f32_e32 v153, v117
	v_fma_f32 v117, v122, s29, -v144
	v_pk_mul_f32 v[120:121], v[88:89], v[128:129] op_sel_hi:[1,0]
	v_pk_mul_f32 v[88:89], v[92:93], v[128:129] op_sel_hi:[1,0]
	v_exp_f32_e32 v154, v117
	v_fma_f32 v117, v123, s29, -v144
	v_pk_mul_f32 v[122:123], v[90:91], v[128:129] op_sel_hi:[1,0]
	v_pk_mul_f32 v[90:91], v[94:95], v[128:129] op_sel_hi:[1,0]
	v_max_f32_e32 v92, v110, v111
	v_max_f32_e32 v93, v106, v107
	v_max3_f32 v92, v108, v109, v92
	v_max3_f32 v93, v104, v105, v93
	v_max3_f32 v92, v92, s28, v93
	v_max_f32_e32 v93, v102, v103
	v_max_f32_e32 v95, v114, v114
	v_max_f32_e32 v94, v95, v115
	v_exp_f32_e32 v149, v125
	v_fma_f32 v116, v116, s29, -v144
	v_max3_f32 v93, v100, v101, v93
	v_max3_f32 v94, v112, v113, v94
	v_exp_f32_e32 v126, v116
	v_max3_f32 v92, v92, v93, v94
	v_add_f32_e32 v124, v147, v124
	v_mov_b32_e32 v93, v92
	v_add_f32_e32 v124, v148, v124
	s_nop 0
	v_permlane16_swap_b32_e32 v92, v93
	v_add_f32_e32 v124, v149, v124
	v_add_f32_e32 v116, v126, v124
	v_max_f32_e32 v92, v92, v93
	v_add_f32_e32 v116, v127, v116
	v_mov_b32_e32 v93, v92
	v_add_f32_e32 v116, v150, v116
	s_nop 0
	v_permlane32_swap_b32_e32 v92, v93
	v_add_f32_e32 v116, v151, v116
	v_exp_f32_e32 v144, v117
	v_max3_f32 v125, v139, v92, v93
	v_add_f32_e32 v116, v152, v116
	v_mul_f32_e32 v93, 0x3e38aa3b, v125
	v_cmp_ngt_f32_e64 s[38:39], s36, v125
	v_add_f32_e32 v116, v153, v116
	v_add_f32_e32 v116, v154, v116
	v_cndmask_b32_e64 v93, 0, v93, s[38:39]
	v_fma_f32 v94, v108, s29, -v93
	v_add_f32_e32 v124, v144, v116
	v_pk_mul_f32 v[116:117], v[84:85], v[128:129] op_sel_hi:[1,0]
	v_pk_mul_f32 v[84:85], v[96:97], v[128:129] op_sel_hi:[1,0]
	v_exp_f32_e32 v96, v94
	v_fma_f32 v95, v109, s29, -v93
	v_exp_f32_e32 v97, v95
	v_fma_f32 v95, v110, s29, -v93
	v_pk_mul_f32 v[118:119], v[86:87], v[128:129] op_sel_hi:[1,0]
	v_pk_mul_f32 v[86:87], v[98:99], v[128:129] op_sel_hi:[1,0]
	v_exp_f32_e32 v98, v95
	v_fma_f32 v95, v111, s29, -v93
	v_exp_f32_e32 v99, v95
	v_fma_f32 v95, v104, s29, -v93
	v_add_f32_e32 v94, 0, v96
	v_exp_f32_e32 v104, v95
	v_fma_f32 v95, v105, s29, -v93
	v_add_f32_e32 v94, v97, v94
	v_exp_f32_e32 v105, v95
	v_fma_f32 v95, v106, s29, -v93
	v_add_f32_e32 v94, v98, v94
	v_exp_f32_e32 v106, v95
	v_fma_f32 v95, v107, s29, -v93
	v_add_f32_e32 v94, v99, v94
	v_exp_f32_e32 v107, v95
	v_fma_f32 v95, v100, s29, -v93
	v_fmac_f32_e32 v124, v140, v128
	v_add_f32_e32 v94, v104, v94
	v_exp_f32_e32 v128, v95
	v_fma_f32 v95, v101, s29, -v93
	v_sub_f32_e32 v92, v139, v125
	v_add_f32_e32 v94, v105, v94
	v_exp_f32_e32 v139, v95
	v_fma_f32 v95, v102, s29, -v93
	v_lshrrev_b32_e32 v3, 2, v3
	v_lshlrev_b32_e32 v1, 3, v1
	v_add_f32_e32 v94, v106, v94
	v_exp_f32_e32 v140, v95
	v_fma_f32 v95, v103, s29, -v93
	v_or_b32_e32 v3, v142, v3
	v_and_b32_e32 v1, 24, v1
	v_add_f32_e32 v94, v107, v94
	v_exp_f32_e32 v141, v95
	v_fma_f32 v95, v112, s29, -v93
	v_mad_i32_i24 v1, v3, s0, v1
	v_add_f32_e32 v94, v128, v94
	v_exp_f32_e32 v155, v95
	v_fma_f32 v95, v113, s29, -v93
	v_cvt_pk_bf16_f32 v96, v96, v97
	v_cvt_pk_bf16_f32 v97, v98, v99
	v_cvt_pk_bf16_f32 v98, v104, v105
	v_cvt_pk_bf16_f32 v99, v106, v107
	ds_read_b64_tr_b16 v[162:163], v1 offset:20736
	ds_read_b64_tr_b16 v[160:161], v1 offset:18432
	ds_read_b64_tr_b16 v[164:165], v1 offset:18464
	ds_read_b64_tr_b16 v[166:167], v1 offset:20768
	ds_read_b64_tr_b16 v[168:169], v1 offset:18496
	ds_read_b64_tr_b16 v[170:171], v1 offset:20800
	ds_read_b64_tr_b16 v[172:173], v1 offset:18528
	ds_read_b64_tr_b16 v[174:175], v1 offset:20832
	ds_read_b64_tr_b16 v[176:177], v1 offset:23040
	ds_read_b64_tr_b16 v[178:179], v1 offset:25344
	ds_read_b64_tr_b16 v[180:181], v1 offset:23072
	ds_read_b64_tr_b16 v[182:183], v1 offset:25376
	ds_read_b64_tr_b16 v[184:185], v1 offset:23104
	ds_read_b64_tr_b16 v[186:187], v1 offset:25408
	ds_read_b64_tr_b16 v[188:189], v1 offset:23136
	ds_read_b64_tr_b16 v[190:191], v1 offset:25440
	v_add_f32_e32 v94, v139, v94
	v_exp_f32_e32 v156, v95
	v_fma_f32 v95, v114, s29, -v93
	v_add_f32_e32 v94, v140, v94
	v_exp_f32_e32 v157, v95
	v_fma_f32 v93, v115, s29, -v93
	v_mul_f32_e32 v92, 0x3e38aa3b, v92
	v_add_f32_e32 v94, v141, v94
	v_exp_f32_e32 v158, v93
	v_add_f32_e32 v94, v155, v94
	v_exp_f32_e32 v92, v92
	v_add_f32_e32 v94, v156, v94
	v_add_f32_e32 v94, v157, v94
	v_add_f32_e32 v159, v158, v94
	v_fmac_f32_e32 v159, v137, v92
	v_pk_mul_f32 v[70:71], v[70:71], v[92:93] op_sel_hi:[1,0]
	v_pk_mul_f32 v[68:69], v[68:69], v[92:93] op_sel_hi:[1,0]
	v_pk_mul_f32 v[74:75], v[74:75], v[92:93] op_sel_hi:[1,0]
	v_pk_mul_f32 v[72:73], v[72:73], v[92:93] op_sel_hi:[1,0]
	v_pk_mul_f32 v[78:79], v[78:79], v[92:93] op_sel_hi:[1,0]
	v_pk_mul_f32 v[76:77], v[76:77], v[92:93] op_sel_hi:[1,0]
	v_pk_mul_f32 v[82:83], v[82:83], v[92:93] op_sel_hi:[1,0]
	v_pk_mul_f32 v[80:81], v[80:81], v[92:93] op_sel_hi:[1,0]
	v_cvt_pk_bf16_f32 v92, v145, v129
	v_cvt_pk_bf16_f32 v93, v130, v131
	v_cvt_pk_bf16_f32 v94, v146, v147
	v_cvt_pk_bf16_f32 v95, v148, v149
	s_waitcnt lgkmcnt(14)
	v_mfma_f32_16x16x32_bf16 v[68:71], v[160:163], v[96:99], v[68:71]
	v_mov_b32_e32 v137, v159
	v_mfma_f32_16x16x32_bf16 v[108:111], v[160:163], v[92:95], v[116:119]
	s_waitcnt lgkmcnt(12)
	v_mfma_f32_16x16x32_bf16 v[100:103], v[164:167], v[92:95], v[120:123]
	s_nop 0
	v_cvt_pk_bf16_f32 v116, v128, v139
	v_cvt_pk_bf16_f32 v117, v140, v141
	v_cvt_pk_bf16_f32 v118, v155, v156
	v_mfma_f32_16x16x32_bf16 v[72:75], v[164:167], v[96:99], v[72:75]
	v_cvt_pk_bf16_f32 v119, v157, v158
	v_mov_b32_e32 v141, v143
	s_waitcnt lgkmcnt(10)
	v_mfma_f32_16x16x32_bf16 v[112:115], v[168:171], v[92:95], v[88:91]
	s_nop 2
	v_mov_b32_e32 v140, v124
	v_mov_b32_e32 v139, v125
	v_mfma_f32_16x16x32_bf16 v[76:79], v[168:171], v[96:99], v[76:79]
	s_waitcnt lgkmcnt(8)
	v_mfma_f32_16x16x32_bf16 v[104:107], v[172:175], v[92:95], v[84:87]
	v_mfma_f32_16x16x32_bf16 v[80:83], v[172:175], v[96:99], v[80:83]
	v_cvt_pk_bf16_f32 v96, v126, v127
	v_cvt_pk_bf16_f32 v97, v150, v151
	v_cvt_pk_bf16_f32 v98, v152, v153
	v_cvt_pk_bf16_f32 v99, v154, v144
	s_waitcnt lgkmcnt(6)
	v_mfma_f32_16x16x32_bf16 v[68:71], v[176:179], v[116:119], v[68:71]
	v_mfma_f32_16x16x32_bf16 v[84:87], v[176:179], v[96:99], v[108:111]
	s_waitcnt lgkmcnt(4)
	v_mfma_f32_16x16x32_bf16 v[88:91], v[180:183], v[96:99], v[100:103]
	s_nop 2
	v_mfma_f32_16x16x32_bf16 v[72:75], v[180:183], v[116:119], v[72:75]
	s_waitcnt lgkmcnt(2)
	v_mfma_f32_16x16x32_bf16 v[92:95], v[184:187], v[96:99], v[112:115]
	v_mfma_f32_16x16x32_bf16 v[76:79], v[184:187], v[116:119], v[76:79]
	s_waitcnt lgkmcnt(0)
	v_mfma_f32_16x16x32_bf16 v[96:99], v[188:191], v[96:99], v[104:107]
	v_mfma_f32_16x16x32_bf16 v[80:83], v[188:191], v[116:119], v[80:83]

.LBB0_458:
	s_or_b64 exec, exec, s[8:9]
	v_max_f32_e32 v146, v130, v131
	v_max_f32_e32 v147, v126, v127
	v_max3_f32 v146, v128, v129, v146
	v_max3_f32 v147, v124, v125, v147
	v_max3_f32 v146, v146, s28, v147
	v_max_f32_e32 v147, v118, v119
	v_max_f32_e32 v149, v122, v122
	v_max_f32_e32 v148, v149, v123
	v_max3_f32 v147, v116, v117, v147
	v_max3_f32 v148, v120, v121, v148
	v_max3_f32 v146, v146, v147, v148
	v_mov_b32_e32 v147, v146
	s_nop 1
	v_permlane16_swap_b32_e32 v146, v147
	v_max_f32_e32 v146, v146, v147
	v_mov_b32_e32 v147, v146
	s_nop 1
	v_permlane32_swap_b32_e32 v146, v147
	s_and_saveexec_b64 s[8:9], s[2:3]
	s_xor_b64 s[2:3], exec, s[8:9]
	s_cbranch_execz .LBB0_445
	v_or_b32_e32 v148, 16, v145
	v_lshlrev_b32_e32 v3, 2, v144
	v_sub_u32_e32 v144, v148, v3
	v_cmp_ge_i32_e32 vcc, v144, v143
	v_cmp_le_i32_e64 s[38:39], v144, v142
	s_and_b64 vcc, vcc, s[38:39]
	v_xad_u32 v144, v3, -1, v148
	v_cndmask_b32_e32 v108, v212, v108, vcc
	v_cmp_ge_i32_e32 vcc, v144, v143
	v_cmp_le_i32_e64 s[38:39], v144, v142
	v_or_b32_e32 v144, 2, v3
	s_and_b64 vcc, vcc, s[38:39]
	v_sub_u32_e32 v144, v148, v144
	v_cndmask_b32_e32 v109, v212, v109, vcc
	v_cmp_ge_i32_e32 vcc, v144, v143
	v_cmp_le_i32_e64 s[38:39], v144, v142
	v_or_b32_e32 v144, 3, v3
	s_and_b64 vcc, vcc, s[38:39]
	v_sub_u32_e32 v144, v148, v144
	v_cndmask_b32_e32 v110, v212, v110, vcc
	v_cmp_ge_i32_e32 vcc, v144, v143
	v_cmp_le_i32_e64 s[38:39], v144, v142
	s_and_b64 vcc, vcc, s[38:39]
	v_sub_u32_e32 v144, v145, v3
	v_cndmask_b32_e32 v111, v212, v111, vcc
	v_cmp_ge_i32_e32 vcc, v144, v143
	v_cmp_le_i32_e64 s[38:39], v144, v142
	v_or_b32_e32 v144, 17, v3
	s_and_b64 vcc, vcc, s[38:39]
	v_sub_u32_e32 v144, v148, v144
	v_cndmask_b32_e32 v104, v212, v104, vcc
	v_cmp_ge_i32_e32 vcc, v144, v143
	v_cmp_le_i32_e64 s[38:39], v144, v142
	v_or_b32_e32 v144, 18, v3
	s_and_b64 vcc, vcc, s[38:39]
	v_sub_u32_e32 v144, v148, v144
	v_cndmask_b32_e32 v105, v212, v105, vcc
	v_cmp_ge_i32_e32 vcc, v144, v143
	v_cmp_le_i32_e64 s[38:39], v144, v142
	v_or_b32_e32 v144, 19, v3
	s_and_b64 vcc, vcc, s[38:39]
	v_sub_u32_e32 v144, v148, v144
	v_cndmask_b32_e32 v106, v212, v106, vcc
	v_cmp_ge_i32_e32 vcc, v144, v143
	v_cmp_le_i32_e64 s[38:39], v144, v142
	v_or_b32_e32 v144, 32, v3
	s_and_b64 vcc, vcc, s[38:39]
	v_sub_u32_e32 v144, v148, v144
	v_cndmask_b32_e32 v107, v212, v107, vcc
	v_cmp_ge_i32_e32 vcc, v144, v143
	v_cmp_le_i32_e64 s[38:39], v144, v142
	v_or_b32_e32 v144, 33, v3
	s_and_b64 vcc, vcc, s[38:39]
	v_sub_u32_e32 v144, v148, v144
	v_cndmask_b32_e32 v100, v212, v100, vcc
	v_cmp_ge_i32_e32 vcc, v144, v143
	v_cmp_le_i32_e64 s[38:39], v144, v142
	v_or_b32_e32 v144, 34, v3
	s_and_b64 vcc, vcc, s[38:39]
	v_sub_u32_e32 v144, v148, v144
	v_cndmask_b32_e32 v101, v212, v101, vcc
	v_cmp_ge_i32_e32 vcc, v144, v143
	v_cmp_le_i32_e64 s[38:39], v144, v142
	v_or_b32_e32 v144, 35, v3
	s_and_b64 vcc, vcc, s[38:39]
	v_sub_u32_e32 v144, v148, v144
	v_cndmask_b32_e32 v102, v212, v102, vcc
	v_cmp_ge_i32_e32 vcc, v144, v143
	v_cmp_le_i32_e64 s[38:39], v144, v142
	v_or_b32_e32 v144, 48, v3
	s_and_b64 vcc, vcc, s[38:39]
	v_sub_u32_e32 v144, v148, v144
	v_cndmask_b32_e32 v103, v212, v103, vcc
	v_cmp_ge_i32_e32 vcc, v144, v143
	v_cmp_le_i32_e64 s[38:39], v144, v142
	v_or_b32_e32 v144, 49, v3
	s_and_b64 vcc, vcc, s[38:39]
	v_sub_u32_e32 v144, v148, v144
	v_cndmask_b32_e32 v112, v212, v112, vcc
	v_cmp_ge_i32_e32 vcc, v144, v143
	v_cmp_le_i32_e64 s[38:39], v144, v142
	v_or_b32_e32 v144, 50, v3
	s_and_b64 vcc, vcc, s[38:39]
	v_sub_u32_e32 v144, v148, v144
	v_cndmask_b32_e32 v113, v212, v113, vcc
	v_cmp_ge_i32_e32 vcc, v144, v143
	v_cmp_le_i32_e64 s[38:39], v144, v142
	v_or_b32_e32 v144, 51, v3
	s_and_b64 vcc, vcc, s[38:39]
	v_sub_u32_e32 v144, v148, v144
	v_cndmask_b32_e32 v114, v212, v114, vcc
	v_cmp_ge_i32_e32 vcc, v144, v143
	v_cmp_le_i32_e64 s[38:39], v144, v142
	s_and_b64 vcc, vcc, s[38:39]
	v_cndmask_b32_e32 v115, v212, v115, vcc
	s_branch .LBB0_445

.LBB0_471:
	s_or_b64 exec, exec, s[2:3]
	v_mov_b32_e32 v199, v201
	s_waitcnt lgkmcnt(0)
	s_barrier
	flat_load_dword v8, v[198:199] sc0 sc1
	s_waitcnt vmcnt(0)
	s_movk_i32 s2, 0x200
	s_waitcnt lgkmcnt(0)
	v_cmp_gt_i32_e32 vcc, s2, v8
	s_mov_b64 s[2:3], -1
	s_and_saveexec_b64 s[40:41], vcc
	s_cbranch_execz .LBB0_466
	v_mov_b32_e32 v3, v197
	v_and_b32_e32 v7, 0x7f, v8
	v_ashrrev_i32_e32 v17, 7, v8
	v_ashrrev_i32_e32 v16, 6, v3
	v_lshlrev_b32_e32 v15, 5, v7
	v_lshl_or_b32 v9, v17, 12, v15
	v_lshlrev_b32_e32 v4, 5, v16
	v_bfe_u32 v47, v3, 5, 1
	s_movk_i32 s2, 0x1200
	v_ashrrev_i32_e32 v5, 31, v4
	v_or_b32_e32 v19, v47, v9
	v_mov_b64_e32 v[12:13], s[4:5]
	v_mul_lo_u32 v0, v16, s2
	v_and_b32_e32 v48, 31, v3
	v_mad_i64_i32 v[20:21], s[2:3], v19, s93, v[12:13]
	v_lshlrev_b64 v[52:53], 1, v[4:5]
	v_and_b32_e32 v1, 63, v3
	v_lshl_add_u64 v[20:21], v[20:21], 0, v[52:53]
	v_lshlrev_b32_e32 v54, 1, v48
	v_mov_b32_e32 v55, v2
	v_lshl_add_u64 v[20:21], v[20:21], 0, v[54:55]
	v_or_b32_e32 v58, 64, v1
	v_add_co_u32_e32 v20, vcc, s94, v20
	v_lshrrev_b32_e32 v45, 5, v58
	s_nop 0
	v_addc_co_u32_e32 v21, vcc, 0, v21, vcc
	v_or_b32_e32 v5, v45, v9
	global_load_ushort v50, v[20:21], off offset:1280
	v_mad_i64_i32 v[20:21], s[2:3], v5, s93, v[12:13]
	v_lshl_add_u64 v[20:21], v[20:21], 0, v[52:53]
	v_lshl_add_u64 v[20:21], v[20:21], 0, v[54:55]
	v_or_b32_e32 v60, 0x80, v1
	v_add_co_u32_e32 v20, vcc, s94, v20
	v_lshrrev_b32_e32 v43, 5, v60
	s_nop 0
	v_addc_co_u32_e32 v21, vcc, 0, v21, vcc
	v_or_b32_e32 v5, v43, v9
	global_load_ushort v49, v[20:21], off offset:1280
	v_mad_i64_i32 v[20:21], s[2:3], v5, s93, v[12:13]
	v_lshl_add_u64 v[20:21], v[20:21], 0, v[52:53]
	v_lshl_add_u64 v[20:21], v[20:21], 0, v[54:55]
	v_or_b32_e32 v66, 0xc0, v1
	v_add_co_u32_e32 v20, vcc, s94, v20
	v_lshrrev_b32_e32 v41, 5, v66
	s_nop 0
	v_addc_co_u32_e32 v21, vcc, 0, v21, vcc
	v_or_b32_e32 v5, v41, v9
	global_load_ushort v46, v[20:21], off offset:1280
	v_mad_i64_i32 v[20:21], s[2:3], v5, s93, v[12:13]
	v_lshl_add_u64 v[20:21], v[20:21], 0, v[52:53]
	v_lshl_add_u64 v[20:21], v[20:21], 0, v[54:55]
	v_add_co_u32_e32 v20, vcc, s94, v20
	v_or_b32_e32 v39, 8, v47
	s_nop 0
	v_addc_co_u32_e32 v21, vcc, 0, v21, vcc
	v_or_b32_e32 v5, v39, v9
	global_load_ushort v44, v[20:21], off offset:1280
	v_mad_i64_i32 v[20:21], s[2:3], v5, s93, v[12:13]
	v_lshl_add_u64 v[20:21], v[20:21], 0, v[52:53]
	v_lshl_add_u64 v[20:21], v[20:21], 0, v[54:55]
	v_add_co_u32_e32 v20, vcc, s94, v20
	v_or_b32_e32 v37, 10, v47
	s_nop 0
	v_addc_co_u32_e32 v21, vcc, 0, v21, vcc
	v_or_b32_e32 v5, v37, v9
	global_load_ushort v42, v[20:21], off offset:1280
	v_mad_i64_i32 v[20:21], s[2:3], v5, s93, v[12:13]
	v_lshl_add_u64 v[20:21], v[20:21], 0, v[52:53]
	v_lshl_add_u64 v[20:21], v[20:21], 0, v[54:55]
	v_add_co_u32_e32 v20, vcc, s94, v20
	v_or_b32_e32 v36, 12, v47
	s_nop 0
	v_addc_co_u32_e32 v21, vcc, 0, v21, vcc
	v_or_b32_e32 v5, v36, v9
	global_load_ushort v40, v[20:21], off offset:1280
	v_mad_i64_i32 v[20:21], s[2:3], v5, s93, v[12:13]
	v_lshl_add_u64 v[20:21], v[20:21], 0, v[52:53]
	v_lshl_add_u64 v[20:21], v[20:21], 0, v[54:55]
	v_add_co_u32_e32 v20, vcc, s94, v20
	v_or_b32_e32 v32, 14, v47
	s_nop 0
	v_addc_co_u32_e32 v21, vcc, 0, v21, vcc
	v_or_b32_e32 v5, v32, v9
	global_load_ushort v38, v[20:21], off offset:1280
	v_mad_i64_i32 v[20:21], s[2:3], v5, s93, v[12:13]
	v_lshl_add_u64 v[20:21], v[20:21], 0, v[52:53]
	v_lshl_add_u64 v[20:21], v[20:21], 0, v[54:55]
	v_add_co_u32_e32 v20, vcc, s94, v20
	v_or_b32_e32 v31, 16, v47
	s_nop 0
	v_addc_co_u32_e32 v21, vcc, 0, v21, vcc
	v_or_b32_e32 v5, v31, v9
	global_load_ushort v35, v[20:21], off offset:1280
	v_mad_i64_i32 v[20:21], s[2:3], v5, s93, v[12:13]
	v_lshl_add_u64 v[20:21], v[20:21], 0, v[52:53]
	v_lshl_add_u64 v[20:21], v[20:21], 0, v[54:55]
	v_add_co_u32_e32 v20, vcc, s94, v20
	v_or_b32_e32 v29, 18, v47
	s_nop 0
	v_addc_co_u32_e32 v21, vcc, 0, v21, vcc
	v_or_b32_e32 v5, v29, v9
	global_load_ushort v34, v[20:21], off offset:1280
	v_mad_i64_i32 v[20:21], s[2:3], v5, s93, v[12:13]
	v_lshl_add_u64 v[20:21], v[20:21], 0, v[52:53]
	v_lshl_add_u64 v[20:21], v[20:21], 0, v[54:55]
	v_add_co_u32_e32 v20, vcc, s94, v20
	v_or_b32_e32 v27, 20, v47
	s_nop 0
	v_addc_co_u32_e32 v21, vcc, 0, v21, vcc
	v_or_b32_e32 v5, v27, v9
	global_load_ushort v33, v[20:21], off offset:1280
	v_mad_i64_i32 v[20:21], s[2:3], v5, s93, v[12:13]
	v_lshl_add_u64 v[20:21], v[20:21], 0, v[52:53]
	v_lshl_add_u64 v[20:21], v[20:21], 0, v[54:55]
	v_add_co_u32_e32 v20, vcc, s94, v20
	v_or_b32_e32 v25, 22, v47
	s_nop 0
	v_addc_co_u32_e32 v21, vcc, 0, v21, vcc
	v_or_b32_e32 v5, v25, v9
	global_load_ushort v30, v[20:21], off offset:1280
	v_mad_i64_i32 v[20:21], s[2:3], v5, s93, v[12:13]
	v_lshl_add_u64 v[20:21], v[20:21], 0, v[52:53]
	v_lshl_add_u64 v[20:21], v[20:21], 0, v[54:55]
	v_add_co_u32_e32 v20, vcc, s94, v20
	v_or_b32_e32 v23, 24, v47
	s_nop 0
	v_addc_co_u32_e32 v21, vcc, 0, v21, vcc
	v_or_b32_e32 v5, v23, v9
	global_load_ushort v28, v[20:21], off offset:1280
	v_mad_i64_i32 v[20:21], s[2:3], v5, s93, v[12:13]
	v_lshl_add_u64 v[20:21], v[20:21], 0, v[52:53]
	v_lshl_add_u64 v[20:21], v[20:21], 0, v[54:55]
	v_add_co_u32_e32 v20, vcc, s94, v20
	v_bfe_u32 v70, v3, 3, 3
	s_nop 0
	v_addc_co_u32_e32 v21, vcc, 0, v21, vcc
	global_load_ushort v26, v[20:21], off offset:1280
	v_or_b32_e32 v21, 26, v47
	v_or_b32_e32 v5, v21, v9
	v_mad_i64_i32 v[56:57], s[2:3], v5, s93, v[12:13]
	v_lshl_add_u64 v[56:57], v[56:57], 0, v[52:53]
	v_lshl_add_u64 v[56:57], v[56:57], 0, v[54:55]
	v_add_co_u32_e32 v56, vcc, s94, v56
	v_or_b32_e32 v20, 28, v47
	s_nop 0
	v_addc_co_u32_e32 v57, vcc, 0, v57, vcc
	v_or_b32_e32 v5, v20, v9
	global_load_ushort v24, v[56:57], off offset:1280
	v_mad_i64_i32 v[56:57], s[2:3], v5, s93, v[12:13]
	v_lshl_add_u64 v[56:57], v[56:57], 0, v[52:53]
	v_lshl_add_u64 v[56:57], v[56:57], 0, v[54:55]
	v_add_co_u32_e32 v56, vcc, s94, v56
	v_or_b32_e32 v5, 30, v47
	s_nop 0
	v_addc_co_u32_e32 v57, vcc, 0, v57, vcc
	v_or_b32_e32 v19, v5, v9
	global_load_ushort v22, v[56:57], off offset:1280
	v_mad_i64_i32 v[56:57], s[2:3], v19, s93, v[12:13]
	v_lshl_add_u64 v[52:53], v[56:57], 0, v[52:53]
	v_lshl_add_u64 v[52:53], v[52:53], 0, v[54:55]
	v_add_co_u32_e32 v52, vcc, s94, v52
	v_or_b32_e32 v51, v70, v9
	s_nop 0
	v_addc_co_u32_e32 v53, vcc, 0, v53, vcc
	global_load_ushort v19, v[52:53], off offset:1280
	v_and_b32_e32 v52, 0xffffffc0, v3
	v_ashrrev_i32_e32 v53, 31, v52
	v_mad_i64_i32 v[54:55], s[2:3], v51, s93, v[12:13]
	v_lshlrev_b64 v[64:65], 1, v[52:53]
	v_lshlrev_b32_e32 v51, 4, v3
	v_lshrrev_b32_e32 v71, 3, v58
	v_lshl_add_u64 v[52:53], v[54:55], 0, v[64:65]
	v_and_b32_e32 v68, 0x70, v51
	v_mov_b32_e32 v69, v2
	v_or_b32_e32 v56, v71, v9
	v_lshl_add_u64 v[52:53], v[52:53], 0, v[68:69]
	v_mad_i64_i32 v[56:57], s[2:3], v56, s93, v[12:13]
	v_lshrrev_b32_e32 v72, 3, v60
	v_add_co_u32_e32 v52, vcc, s94, v52
	v_lshl_add_u64 v[56:57], v[56:57], 0, v[64:65]
	v_or_b32_e32 v60, v72, v9
	v_addc_co_u32_e32 v53, vcc, 0, v53, vcc
	v_lshl_add_u64 v[56:57], v[56:57], 0, v[68:69]
	v_mad_i64_i32 v[60:61], s[2:3], v60, s93, v[12:13]
	v_lshrrev_b32_e32 v73, 3, v66
	v_add_co_u32_e32 v56, vcc, s94, v56
	v_lshl_add_u64 v[60:61], v[60:61], 0, v[64:65]
	v_or_b32_e32 v66, v73, v9
	v_addc_co_u32_e32 v57, vcc, 0, v57, vcc
	v_lshl_add_u64 v[60:61], v[60:61], 0, v[68:69]
	v_mad_i64_i32 v[66:67], s[2:3], v66, s93, v[12:13]
	v_add_co_u32_e32 v60, vcc, s94, v60
	v_lshl_add_u64 v[64:65], v[66:67], 0, v[64:65]
	global_load_dwordx4 v[52:55], v[52:53], off offset:1536
	v_addc_co_u32_e32 v61, vcc, 0, v61, vcc
	v_lshl_add_u64 v[64:65], v[64:65], 0, v[68:69]
	global_load_dwordx4 v[56:59], v[56:57], off offset:1536
	v_add_co_u32_e32 v64, vcc, s94, v64
	global_load_dwordx4 v[60:63], v[60:61], off offset:1536
	s_nop 0
	v_addc_co_u32_e32 v65, vcc, 0, v65, vcc
	global_load_dwordx4 v[64:67], v[64:65], off offset:1536
	v_or_b32_e32 v68, v0, v68
	v_mad_u32_u24 v69, v70, s0, v68
	v_readlane_b32 s98, v250, 34
	v_readlane_b32 s99, v250, 35
	v_readlane_b32 s100, v250, 36
	v_readlane_b32 s101, v250, 37
	v_and_b32_e32 v236, 0x7f, v197
	v_or_b32_e32 v238, s14, v236
	v_mov_b32_e32 v239, v2
	v_lshl_add_u64 v[238:239], v[238:239], 2, s[98:99]
	v_add_co_u32_e32 v240, vcc, s94, v238
	global_load_dword v216, v[238:239], off
	global_load_dword v217, v[238:239], off offset:512
	global_load_dword v218, v[238:239], off offset:1024
	global_load_dword v219, v[238:239], off offset:1536
	global_load_dword v220, v[238:239], off offset:2048
	global_load_dword v221, v[238:239], off offset:2560
	global_load_dword v222, v[238:239], off offset:3072
	global_load_dword v223, v[238:239], off offset:3584
	v_addc_co_u32_e32 v241, vcc, 0, v239, vcc
	global_load_dword v224, v[240:241], off
	global_load_dword v225, v[240:241], off offset:512
	global_load_dword v226, v[240:241], off offset:1024
	global_load_dword v227, v[240:241], off offset:1536
	global_load_dword v228, v[240:241], off offset:2048
	global_load_dword v229, v[240:241], off offset:2560
	global_load_dword v230, v[240:241], off offset:3072
	global_load_dword v231, v[240:241], off offset:3584
	v_or_b32_e32 v238, s15, v236
	v_mov_b32_e32 v239, v2
	v_lshl_add_u64 v[238:239], v[238:239], 2, s[100:101]
	global_load_dword v232, v[238:239], off
	v_ashrrev_i32_e32 v238, 4, v197
	v_add_u32_e32 v242, 0x100, v197
	v_add_u32_e32 v238, v238, v9
	v_and_b32_e32 v240, 15, v197
	v_mad_i64_i32 v[238:239], s[2:3], v238, s93, v[12:13]
	v_lshlrev_b32_e32 v240, 1, v240
	v_mov_b32_e32 v241, v2
	v_ashrrev_i32_e32 v242, 4, v242
	v_lshl_add_u64 v[238:239], v[238:239], 0, v[240:241]
	v_add_u32_e32 v242, v242, v9
	v_mad_i64_i32 v[242:243], s[2:3], v242, s93, v[12:13]
	v_add_co_u32_e32 v238, vcc, s94, v238
	v_lshl_add_u64 v[242:243], v[242:243], 0, v[240:241]
	s_nop 0
	v_addc_co_u32_e32 v239, vcc, 0, v239, vcc
	v_add_co_u32_e32 v242, vcc, s94, v242
	global_load_ushort v233, v[238:239], off offset:2560
	s_nop 0
	v_addc_co_u32_e32 v243, vcc, 0, v243, vcc
	global_load_ushort v234, v[242:243], off offset:2560
	s_barrier
	v_readlane_b32 s44, v250, 24
	v_readlane_b32 s45, v250, 25
	v_readlane_b32 s46, v250, 26
	v_readlane_b32 s47, v250, 27
	v_readlane_b32 s48, v250, 28
	v_readlane_b32 s49, v250, 29
	v_readlane_b32 s50, v250, 30
	v_readlane_b32 s51, v250, 31
	v_readlane_b32 s52, v250, 32
	v_readlane_b32 s53, v250, 33
	v_readlane_b32 s54, v250, 34
	v_readlane_b32 s55, v250, 35
	v_readlane_b32 s56, v250, 36
	v_readlane_b32 s57, v250, 37
	v_readlane_b32 s58, v250, 38
	v_readlane_b32 s59, v250, 39
	s_mov_b64 s[44:45], s[52:53]
	s_mov_b64 s[46:47], s[54:55]
	s_mov_b64 s[48:49], s[56:57]
	s_mov_b64 s[50:51], s[58:59]
	s_waitcnt vmcnt(22)
	ds_write_b128 v69, v[52:55] offset:26624
	v_mad_u32_u24 v52, v71, s0, v68
	v_mov_b32_e32 v55, v2
	s_waitcnt vmcnt(21)
	ds_write_b128 v52, v[56:59] offset:26624
	v_mad_u32_u24 v52, v72, s0, v68
	s_waitcnt vmcnt(20)
	ds_write_b128 v52, v[60:63] offset:26624
	v_mad_u32_u24 v52, v73, s0, v68
	v_mov_b32_e32 v73, v2
	s_waitcnt vmcnt(19)
	ds_write_b128 v52, v[64:67] offset:26624
	v_mov_b32_e32 v52, v197
	s_nop 0
	v_and_b32_e32 v74, 0x7f, v52
	v_or_b32_e32 v54, s14, v74
	v_lshl_add_u64 v[54:55], v[54:55], 2, s[46:47]
	v_add_co_u32_e32 v70, vcc, s94, v54
	s_waitcnt vmcnt(0)
	v_mov_b32_e32 v66, v216
	v_mov_b32_e32 v68, v217
	v_mov_b32_e32 v64, v218
	v_mov_b32_e32 v67, v219
	v_mov_b32_e32 v60, v220
	v_mov_b32_e32 v65, v221
	v_mov_b32_e32 v59, v222
	v_mov_b32_e32 v63, v223
	v_addc_co_u32_e32 v71, vcc, 0, v55, vcc
	v_mov_b32_e32 v58, v224
	v_mov_b32_e32 v62, v225
	v_mov_b32_e32 v56, v226
	v_mov_b32_e32 v61, v227
	v_mov_b32_e32 v54, v228
	v_mov_b32_e32 v57, v229
	v_mov_b32_e32 v53, v230
	v_mov_b32_e32 v55, v231
	v_or_b32_e32 v70, s15, v74
	v_mov_b32_e32 v71, v2
	v_lshl_add_u64 v[70:71], v[70:71], 2, s[48:49]
	v_mov_b32_e32 v69, v232
	v_ashrrev_i32_e32 v70, 4, v52
	v_add_u32_e32 v75, 0x100, v52
	v_add_u32_e32 v70, v70, v9
	v_and_b32_e32 v72, 15, v52
	v_mad_i64_i32 v[70:71], s[2:3], v70, s93, v[12:13]
	v_lshlrev_b32_e32 v72, 1, v72
	v_ashrrev_i32_e32 v75, 4, v75
	v_lshl_add_u64 v[70:71], v[70:71], 0, v[72:73]
	v_add_u32_e32 v9, v75, v9
	v_mad_i64_i32 v[12:13], s[2:3], v9, s93, v[12:13]
	v_add_co_u32_e32 v70, vcc, s94, v70
	v_lshl_add_u64 v[12:13], v[12:13], 0, v[72:73]
	s_nop 0
	v_addc_co_u32_e32 v71, vcc, 0, v71, vcc
	v_add_co_u32_e32 v12, vcc, s94, v12
	v_mov_b32_e32 v9, v233
	s_nop 0
	v_addc_co_u32_e32 v13, vcc, 0, v13, vcc
	v_mov_b32_e32 v12, v234
	v_ashrrev_i32_e32 v13, 3, v52
	s_mov_b32 s2, 0xbfb8aa3b
	s_waitcnt vmcnt(1)
	v_lshlrev_b32_e32 v70, 16, v9
	v_lshlrev_b32_e32 v9, 2, v52
	s_waitcnt vmcnt(0)
	v_lshlrev_b32_e32 v12, 16, v12
	ds_write2st64_b32 v9, v70, v12 offset0:64 offset1:68
	v_and_b32_e32 v70, -16, v13
	v_lshlrev_b32_e32 v71, 6, v70
	s_waitcnt lgkmcnt(0)
	s_barrier
	v_lshlrev_b32_e32 v12, 2, v74
	ds_read_b128 v[72:75], v71 offset:16384
	ds_read_b128 v[76:79], v71 offset:16400
	ds_read_b128 v[80:83], v71 offset:16416
	ds_read_b128 v[84:87], v71 offset:16432
	v_or_b32_e32 v13, 15, v13
	s_waitcnt lgkmcnt(3)
	v_mul_f32_e32 v71, v68, v73
	v_fmac_f32_e32 v71, v66, v72
	v_mul_f32_e32 v72, v67, v75
	v_fmac_f32_e32 v72, v64, v74
	v_add_f32_e32 v71, v71, v72
	s_waitcnt lgkmcnt(2)
	v_mul_f32_e32 v72, v65, v77
	v_mul_f32_e32 v73, v63, v79
	v_fmac_f32_e32 v72, v60, v76
	v_fmac_f32_e32 v73, v59, v78
	v_add_f32_e32 v71, v69, v71
	v_add_f32_e32 v72, v72, v73
	v_add_f32_e32 v71, v71, v72
	s_waitcnt lgkmcnt(1)
	v_mul_f32_e32 v72, v62, v81
	v_mul_f32_e32 v73, v61, v83
	v_fmac_f32_e32 v72, v58, v80
	v_fmac_f32_e32 v73, v56, v82
	v_add_f32_e32 v72, v72, v73
	v_add_f32_e32 v71, v71, v72
	s_waitcnt lgkmcnt(0)
	v_mul_f32_e32 v72, v57, v85
	v_mul_f32_e32 v73, v55, v87
	v_fmac_f32_e32 v72, v54, v84
	v_fmac_f32_e32 v73, v53, v86
	v_add_f32_e32 v72, v72, v73
	v_add_f32_e32 v71, v71, v72
	v_min_f32_e32 v72, 0, v71
	v_mul_f32_e64 v71, |v71|, s2
	v_exp_f32_e32 v71, v71
	s_nop 0
	v_add_f32_e32 v71, 1.0, v71
	v_cmp_gt_f32_e32 vcc, s22, v71
	s_nop 1
	v_cndmask_b32_e64 v73, 0, 32, vcc
	v_ldexp_f32 v71, v71, v73
	v_log_f32_e32 v71, v71
	s_nop 0
	v_mul_f32_e32 v73, 0x3f317217, v71
	v_fma_f32 v73, v71, s37, -v73
	v_fmac_f32_e32 v73, 0x3377d1cf, v71
	v_fmac_f32_e32 v73, 0x3f317217, v71
	v_cmp_lt_f32_e64 s[38:39], |v71|, s1
	s_nop 1
	v_cndmask_b32_e64 v71, v71, v73, s[38:39]
	v_cndmask_b32_e32 v73, 0, v213, vcc
	v_sub_f32_e32 v71, v71, v73
	v_sub_f32_e32 v71, v72, v71
	v_mul_f32_e32 v71, 0x3d800000, v71
	v_lshl_or_b32 v72, v70, 9, v12
	ds_write_b32 v72, v71
	v_or_b32_e32 v71, 1, v70
	v_lshlrev_b32_e32 v84, 6, v71
	ds_read_b128 v[72:75], v84 offset:16384
	ds_read_b128 v[76:79], v84 offset:16400
	ds_read_b128 v[80:83], v84 offset:16416
	ds_read_b128 v[84:87], v84 offset:16432
	v_lshl_or_b32 v71, v71, 9, v12
	s_waitcnt lgkmcnt(3)
	v_mul_f32_e32 v73, v68, v73
	v_fmac_f32_e32 v73, v66, v72
	v_mul_f32_e32 v72, v67, v75
	v_fmac_f32_e32 v72, v64, v74
	v_add_f32_e32 v72, v73, v72
	s_waitcnt lgkmcnt(2)
	v_mul_f32_e32 v73, v65, v77
	v_mul_f32_e32 v74, v63, v79
	v_fmac_f32_e32 v73, v60, v76
	v_fmac_f32_e32 v74, v59, v78
	v_add_f32_e32 v72, v69, v72
	v_add_f32_e32 v73, v73, v74
	v_add_f32_e32 v72, v72, v73
	s_waitcnt lgkmcnt(1)
	v_mul_f32_e32 v73, v62, v81
	v_mul_f32_e32 v74, v61, v83
	v_fmac_f32_e32 v73, v58, v80
	v_fmac_f32_e32 v74, v56, v82
	v_add_f32_e32 v73, v73, v74
	v_add_f32_e32 v72, v72, v73
	s_waitcnt lgkmcnt(0)
	v_mul_f32_e32 v73, v57, v85
	v_mul_f32_e32 v74, v55, v87
	v_fmac_f32_e32 v73, v54, v84
	v_fmac_f32_e32 v74, v53, v86
	v_add_f32_e32 v73, v73, v74
	v_add_f32_e32 v72, v72, v73
	v_min_f32_e32 v73, 0, v72
	v_mul_f32_e64 v72, |v72|, s2
	v_exp_f32_e32 v72, v72
	s_nop 0
	v_add_f32_e32 v72, 1.0, v72
	v_cmp_gt_f32_e32 vcc, s22, v72
	s_nop 1
	v_cndmask_b32_e64 v74, 0, 32, vcc
	v_ldexp_f32 v72, v72, v74
	v_log_f32_e32 v72, v72
	s_nop 0
	v_mul_f32_e32 v74, 0x3f317217, v72
	v_fma_f32 v74, v72, s37, -v74
	v_fmac_f32_e32 v74, 0x3377d1cf, v72
	v_fmac_f32_e32 v74, 0x3f317217, v72
	v_cmp_lt_f32_e64 s[38:39], |v72|, s1
	s_nop 1
	v_cndmask_b32_e64 v72, v72, v74, s[38:39]
	v_cndmask_b32_e32 v74, 0, v213, vcc
	v_sub_f32_e32 v72, v72, v74
	v_sub_f32_e32 v72, v73, v72
	v_mul_f32_e32 v72, 0x3d800000, v72
	ds_write_b32 v71, v72
	v_or_b32_e32 v71, 2, v70
	v_lshlrev_b32_e32 v84, 6, v71
	ds_read_b128 v[72:75], v84 offset:16384
	ds_read_b128 v[76:79], v84 offset:16400
	ds_read_b128 v[80:83], v84 offset:16416
	ds_read_b128 v[84:87], v84 offset:16432
	v_lshl_or_b32 v71, v71, 9, v12
	s_waitcnt lgkmcnt(3)
	v_mul_f32_e32 v73, v68, v73
	v_fmac_f32_e32 v73, v66, v72
	v_mul_f32_e32 v72, v67, v75
	v_fmac_f32_e32 v72, v64, v74
	v_add_f32_e32 v72, v73, v72
	s_waitcnt lgkmcnt(2)
	v_mul_f32_e32 v73, v65, v77
	v_mul_f32_e32 v74, v63, v79
	v_fmac_f32_e32 v73, v60, v76
	v_fmac_f32_e32 v74, v59, v78
	v_add_f32_e32 v72, v69, v72
	v_add_f32_e32 v73, v73, v74
	v_add_f32_e32 v72, v72, v73
	s_waitcnt lgkmcnt(1)
	v_mul_f32_e32 v73, v62, v81
	v_mul_f32_e32 v74, v61, v83
	v_fmac_f32_e32 v73, v58, v80
	v_fmac_f32_e32 v74, v56, v82
	v_add_f32_e32 v73, v73, v74
	v_add_f32_e32 v72, v72, v73
	s_waitcnt lgkmcnt(0)
	v_mul_f32_e32 v73, v57, v85
	v_mul_f32_e32 v74, v55, v87
	v_fmac_f32_e32 v73, v54, v84
	v_fmac_f32_e32 v74, v53, v86
	v_add_f32_e32 v73, v73, v74
	v_add_f32_e32 v72, v72, v73
	v_min_f32_e32 v73, 0, v72
	v_mul_f32_e64 v72, |v72|, s2
	v_exp_f32_e32 v72, v72
	s_nop 0
	v_add_f32_e32 v72, 1.0, v72
	v_cmp_gt_f32_e32 vcc, s22, v72
	s_nop 1
	v_cndmask_b32_e64 v74, 0, 32, vcc
	v_ldexp_f32 v72, v72, v74
	v_log_f32_e32 v72, v72
	s_nop 0
	v_mul_f32_e32 v74, 0x3f317217, v72
	v_fma_f32 v74, v72, s37, -v74
	v_fmac_f32_e32 v74, 0x3377d1cf, v72
	v_fmac_f32_e32 v74, 0x3f317217, v72
	v_cmp_lt_f32_e64 s[38:39], |v72|, s1
	s_nop 1
	v_cndmask_b32_e64 v72, v72, v74, s[38:39]
	v_cndmask_b32_e32 v74, 0, v213, vcc
	v_sub_f32_e32 v72, v72, v74
	v_sub_f32_e32 v72, v73, v72
	v_mul_f32_e32 v72, 0x3d800000, v72
	ds_write_b32 v71, v72
	v_or_b32_e32 v71, 3, v70
	v_lshlrev_b32_e32 v84, 6, v71
	ds_read_b128 v[72:75], v84 offset:16384
	ds_read_b128 v[76:79], v84 offset:16400
	ds_read_b128 v[80:83], v84 offset:16416
	ds_read_b128 v[84:87], v84 offset:16432
	v_lshl_or_b32 v71, v71, 9, v12
	s_waitcnt lgkmcnt(3)
	v_mul_f32_e32 v73, v68, v73
	v_fmac_f32_e32 v73, v66, v72
	v_mul_f32_e32 v72, v67, v75
	v_fmac_f32_e32 v72, v64, v74
	v_add_f32_e32 v72, v73, v72
	s_waitcnt lgkmcnt(2)
	v_mul_f32_e32 v73, v65, v77
	v_mul_f32_e32 v74, v63, v79
	v_fmac_f32_e32 v73, v60, v76
	v_fmac_f32_e32 v74, v59, v78
	v_add_f32_e32 v72, v69, v72
	v_add_f32_e32 v73, v73, v74
	v_add_f32_e32 v72, v72, v73
	s_waitcnt lgkmcnt(1)
	v_mul_f32_e32 v73, v62, v81
	v_mul_f32_e32 v74, v61, v83
	v_fmac_f32_e32 v73, v58, v80
	v_fmac_f32_e32 v74, v56, v82
	v_add_f32_e32 v73, v73, v74
	v_add_f32_e32 v72, v72, v73
	s_waitcnt lgkmcnt(0)
	v_mul_f32_e32 v73, v57, v85
	v_mul_f32_e32 v74, v55, v87
	v_fmac_f32_e32 v73, v54, v84
	v_fmac_f32_e32 v74, v53, v86
	v_add_f32_e32 v73, v73, v74
	v_add_f32_e32 v72, v72, v73
	v_min_f32_e32 v73, 0, v72
	v_mul_f32_e64 v72, |v72|, s2
	v_exp_f32_e32 v72, v72
	s_nop 0
	v_add_f32_e32 v72, 1.0, v72
	v_cmp_gt_f32_e32 vcc, s22, v72
	s_nop 1
	v_cndmask_b32_e64 v74, 0, 32, vcc
	v_ldexp_f32 v72, v72, v74
	v_log_f32_e32 v72, v72
	s_nop 0
	v_mul_f32_e32 v74, 0x3f317217, v72
	v_fma_f32 v74, v72, s37, -v74
	v_fmac_f32_e32 v74, 0x3377d1cf, v72
	v_fmac_f32_e32 v74, 0x3f317217, v72
	v_cmp_lt_f32_e64 s[38:39], |v72|, s1
	s_nop 1
	v_cndmask_b32_e64 v72, v72, v74, s[38:39]
	v_cndmask_b32_e32 v74, 0, v213, vcc
	v_sub_f32_e32 v72, v72, v74
	v_sub_f32_e32 v72, v73, v72
	v_mul_f32_e32 v72, 0x3d800000, v72
	ds_write_b32 v71, v72
	v_or_b32_e32 v71, 4, v70
	v_lshlrev_b32_e32 v84, 6, v71
	ds_read_b128 v[72:75], v84 offset:16384
	ds_read_b128 v[76:79], v84 offset:16400
	ds_read_b128 v[80:83], v84 offset:16416
	ds_read_b128 v[84:87], v84 offset:16432
	v_lshl_or_b32 v71, v71, 9, v12
	s_waitcnt lgkmcnt(3)
	v_mul_f32_e32 v73, v68, v73
	v_fmac_f32_e32 v73, v66, v72
	v_mul_f32_e32 v72, v67, v75
	v_fmac_f32_e32 v72, v64, v74
	v_add_f32_e32 v72, v73, v72
	s_waitcnt lgkmcnt(2)
	v_mul_f32_e32 v73, v65, v77
	v_mul_f32_e32 v74, v63, v79
	v_fmac_f32_e32 v73, v60, v76
	v_fmac_f32_e32 v74, v59, v78
	v_add_f32_e32 v72, v69, v72
	v_add_f32_e32 v73, v73, v74
	v_add_f32_e32 v72, v72, v73
	s_waitcnt lgkmcnt(1)
	v_mul_f32_e32 v73, v62, v81
	v_mul_f32_e32 v74, v61, v83
	v_fmac_f32_e32 v73, v58, v80
	v_fmac_f32_e32 v74, v56, v82
	v_add_f32_e32 v73, v73, v74
	v_add_f32_e32 v72, v72, v73
	s_waitcnt lgkmcnt(0)
	v_mul_f32_e32 v73, v57, v85
	v_mul_f32_e32 v74, v55, v87
	v_fmac_f32_e32 v73, v54, v84
	v_fmac_f32_e32 v74, v53, v86
	v_add_f32_e32 v73, v73, v74
	v_add_f32_e32 v72, v72, v73
	v_min_f32_e32 v73, 0, v72
	v_mul_f32_e64 v72, |v72|, s2
	v_exp_f32_e32 v72, v72
	s_nop 0
	v_add_f32_e32 v72, 1.0, v72
	v_cmp_gt_f32_e32 vcc, s22, v72
	s_nop 1
	v_cndmask_b32_e64 v74, 0, 32, vcc
	v_ldexp_f32 v72, v72, v74
	v_log_f32_e32 v72, v72
	s_nop 0
	v_mul_f32_e32 v74, 0x3f317217, v72
	v_fma_f32 v74, v72, s37, -v74
	v_fmac_f32_e32 v74, 0x3377d1cf, v72
	v_fmac_f32_e32 v74, 0x3f317217, v72
	v_cmp_lt_f32_e64 s[38:39], |v72|, s1
	s_nop 1
	v_cndmask_b32_e64 v72, v72, v74, s[38:39]
	v_cndmask_b32_e32 v74, 0, v213, vcc
	v_sub_f32_e32 v72, v72, v74
	v_sub_f32_e32 v72, v73, v72
	v_mul_f32_e32 v72, 0x3d800000, v72
	ds_write_b32 v71, v72
	v_or_b32_e32 v71, 5, v70
	v_lshlrev_b32_e32 v84, 6, v71
	ds_read_b128 v[72:75], v84 offset:16384
	ds_read_b128 v[76:79], v84 offset:16400
	ds_read_b128 v[80:83], v84 offset:16416
	ds_read_b128 v[84:87], v84 offset:16432
	v_lshl_or_b32 v71, v71, 9, v12
	s_waitcnt lgkmcnt(3)
	v_mul_f32_e32 v73, v68, v73
	v_fmac_f32_e32 v73, v66, v72
	v_mul_f32_e32 v72, v67, v75
	v_fmac_f32_e32 v72, v64, v74
	v_add_f32_e32 v72, v73, v72
	s_waitcnt lgkmcnt(2)
	v_mul_f32_e32 v73, v65, v77
	v_mul_f32_e32 v74, v63, v79
	v_fmac_f32_e32 v73, v60, v76
	v_fmac_f32_e32 v74, v59, v78
	v_add_f32_e32 v72, v69, v72
	v_add_f32_e32 v73, v73, v74
	v_add_f32_e32 v72, v72, v73
	s_waitcnt lgkmcnt(1)
	v_mul_f32_e32 v73, v62, v81
	v_mul_f32_e32 v74, v61, v83
	v_fmac_f32_e32 v73, v58, v80
	v_fmac_f32_e32 v74, v56, v82
	v_add_f32_e32 v73, v73, v74
	v_add_f32_e32 v72, v72, v73
	s_waitcnt lgkmcnt(0)
	v_mul_f32_e32 v73, v57, v85
	v_mul_f32_e32 v74, v55, v87
	v_fmac_f32_e32 v73, v54, v84
	v_fmac_f32_e32 v74, v53, v86
	v_add_f32_e32 v73, v73, v74
	v_add_f32_e32 v72, v72, v73
	v_min_f32_e32 v73, 0, v72
	v_mul_f32_e64 v72, |v72|, s2
	v_exp_f32_e32 v72, v72
	s_nop 0
	v_add_f32_e32 v72, 1.0, v72
	v_cmp_gt_f32_e32 vcc, s22, v72
	s_nop 1
	v_cndmask_b32_e64 v74, 0, 32, vcc
	v_ldexp_f32 v72, v72, v74
	v_log_f32_e32 v72, v72
	s_nop 0
	v_mul_f32_e32 v74, 0x3f317217, v72
	v_fma_f32 v74, v72, s37, -v74
	v_fmac_f32_e32 v74, 0x3377d1cf, v72
	v_fmac_f32_e32 v74, 0x3f317217, v72
	v_cmp_lt_f32_e64 s[38:39], |v72|, s1
	s_nop 1
	v_cndmask_b32_e64 v72, v72, v74, s[38:39]
	v_cndmask_b32_e32 v74, 0, v213, vcc
	v_sub_f32_e32 v72, v72, v74
	v_sub_f32_e32 v72, v73, v72
	v_mul_f32_e32 v72, 0x3d800000, v72
	ds_write_b32 v71, v72
	v_or_b32_e32 v71, 6, v70
	v_lshlrev_b32_e32 v84, 6, v71
	ds_read_b128 v[72:75], v84 offset:16384
	ds_read_b128 v[76:79], v84 offset:16400
	ds_read_b128 v[80:83], v84 offset:16416
	ds_read_b128 v[84:87], v84 offset:16432
	v_lshl_or_b32 v71, v71, 9, v12
	s_waitcnt lgkmcnt(3)
	v_mul_f32_e32 v73, v68, v73
	v_fmac_f32_e32 v73, v66, v72
	v_mul_f32_e32 v72, v67, v75
	v_fmac_f32_e32 v72, v64, v74
	v_add_f32_e32 v72, v73, v72
	s_waitcnt lgkmcnt(2)
	v_mul_f32_e32 v73, v65, v77
	v_mul_f32_e32 v74, v63, v79
	v_fmac_f32_e32 v73, v60, v76
	v_fmac_f32_e32 v74, v59, v78
	v_add_f32_e32 v72, v69, v72
	v_add_f32_e32 v73, v73, v74
	v_add_f32_e32 v72, v72, v73
	s_waitcnt lgkmcnt(1)
	v_mul_f32_e32 v73, v62, v81
	v_mul_f32_e32 v74, v61, v83
	v_fmac_f32_e32 v73, v58, v80
	v_fmac_f32_e32 v74, v56, v82
	v_add_f32_e32 v73, v73, v74
	v_add_f32_e32 v72, v72, v73
	s_waitcnt lgkmcnt(0)
	v_mul_f32_e32 v73, v57, v85
	v_mul_f32_e32 v74, v55, v87
	v_fmac_f32_e32 v73, v54, v84
	v_fmac_f32_e32 v74, v53, v86
	v_add_f32_e32 v73, v73, v74
	v_add_f32_e32 v72, v72, v73
	v_min_f32_e32 v73, 0, v72
	v_mul_f32_e64 v72, |v72|, s2
	v_exp_f32_e32 v72, v72
	s_nop 0
	v_add_f32_e32 v72, 1.0, v72
	v_cmp_gt_f32_e32 vcc, s22, v72
	s_nop 1
	v_cndmask_b32_e64 v74, 0, 32, vcc
	v_ldexp_f32 v72, v72, v74
	v_log_f32_e32 v72, v72
	s_nop 0
	v_mul_f32_e32 v74, 0x3f317217, v72
	v_fma_f32 v74, v72, s37, -v74
	v_fmac_f32_e32 v74, 0x3377d1cf, v72
	v_fmac_f32_e32 v74, 0x3f317217, v72
	v_cmp_lt_f32_e64 s[38:39], |v72|, s1
	s_nop 1
	v_cndmask_b32_e64 v72, v72, v74, s[38:39]
	v_cndmask_b32_e32 v74, 0, v213, vcc
	v_sub_f32_e32 v72, v72, v74
	v_sub_f32_e32 v72, v73, v72
	v_mul_f32_e32 v72, 0x3d800000, v72
	ds_write_b32 v71, v72
	v_or_b32_e32 v71, 7, v70
	v_lshlrev_b32_e32 v84, 6, v71
	ds_read_b128 v[72:75], v84 offset:16384
	ds_read_b128 v[76:79], v84 offset:16400
	ds_read_b128 v[80:83], v84 offset:16416
	ds_read_b128 v[84:87], v84 offset:16432
	v_lshl_or_b32 v71, v71, 9, v12
	s_waitcnt lgkmcnt(3)
	v_mul_f32_e32 v73, v68, v73
	v_fmac_f32_e32 v73, v66, v72
	v_mul_f32_e32 v72, v67, v75
	v_fmac_f32_e32 v72, v64, v74
	v_add_f32_e32 v72, v73, v72
	s_waitcnt lgkmcnt(2)
	v_mul_f32_e32 v73, v65, v77
	v_mul_f32_e32 v74, v63, v79
	v_fmac_f32_e32 v73, v60, v76
	v_fmac_f32_e32 v74, v59, v78
	v_add_f32_e32 v72, v69, v72
	v_add_f32_e32 v73, v73, v74
	v_add_f32_e32 v72, v72, v73
	s_waitcnt lgkmcnt(1)
	v_mul_f32_e32 v73, v62, v81
	v_mul_f32_e32 v74, v61, v83
	v_fmac_f32_e32 v73, v58, v80
	v_fmac_f32_e32 v74, v56, v82
	v_add_f32_e32 v73, v73, v74
	v_add_f32_e32 v72, v72, v73
	s_waitcnt lgkmcnt(0)
	v_mul_f32_e32 v73, v57, v85
	v_mul_f32_e32 v74, v55, v87
	v_fmac_f32_e32 v73, v54, v84
	v_fmac_f32_e32 v74, v53, v86
	v_add_f32_e32 v73, v73, v74
	v_add_f32_e32 v72, v72, v73
	v_min_f32_e32 v73, 0, v72
	v_mul_f32_e64 v72, |v72|, s2
	v_exp_f32_e32 v72, v72
	s_nop 0
	v_add_f32_e32 v72, 1.0, v72
	v_cmp_gt_f32_e32 vcc, s22, v72
	s_nop 1
	v_cndmask_b32_e64 v74, 0, 32, vcc
	v_ldexp_f32 v72, v72, v74
	v_log_f32_e32 v72, v72
	s_nop 0
	v_mul_f32_e32 v74, 0x3f317217, v72
	v_fma_f32 v74, v72, s37, -v74
	v_fmac_f32_e32 v74, 0x3377d1cf, v72
	v_fmac_f32_e32 v74, 0x3f317217, v72
	v_cmp_lt_f32_e64 s[38:39], |v72|, s1
	s_nop 1
	v_cndmask_b32_e64 v72, v72, v74, s[38:39]
	v_cndmask_b32_e32 v74, 0, v213, vcc
	v_sub_f32_e32 v72, v72, v74
	v_sub_f32_e32 v72, v73, v72
	v_mul_f32_e32 v72, 0x3d800000, v72
	ds_write_b32 v71, v72
	v_or_b32_e32 v71, 8, v70
	v_lshlrev_b32_e32 v84, 6, v71
	ds_read_b128 v[72:75], v84 offset:16384
	ds_read_b128 v[76:79], v84 offset:16400
	ds_read_b128 v[80:83], v84 offset:16416
	ds_read_b128 v[84:87], v84 offset:16432
	v_lshl_or_b32 v71, v71, 9, v12
	s_waitcnt lgkmcnt(3)
	v_mul_f32_e32 v73, v68, v73
	v_fmac_f32_e32 v73, v66, v72
	v_mul_f32_e32 v72, v67, v75
	v_fmac_f32_e32 v72, v64, v74
	v_add_f32_e32 v72, v73, v72
	s_waitcnt lgkmcnt(2)
	v_mul_f32_e32 v73, v65, v77
	v_mul_f32_e32 v74, v63, v79
	v_fmac_f32_e32 v73, v60, v76
	v_fmac_f32_e32 v74, v59, v78
	v_add_f32_e32 v72, v69, v72
	v_add_f32_e32 v73, v73, v74
	v_add_f32_e32 v72, v72, v73
	s_waitcnt lgkmcnt(1)
	v_mul_f32_e32 v73, v62, v81
	v_mul_f32_e32 v74, v61, v83
	v_fmac_f32_e32 v73, v58, v80
	v_fmac_f32_e32 v74, v56, v82
	v_add_f32_e32 v73, v73, v74
	v_add_f32_e32 v72, v72, v73
	s_waitcnt lgkmcnt(0)
	v_mul_f32_e32 v73, v57, v85
	v_mul_f32_e32 v74, v55, v87
	v_fmac_f32_e32 v73, v54, v84
	v_fmac_f32_e32 v74, v53, v86
	v_add_f32_e32 v73, v73, v74
	v_add_f32_e32 v72, v72, v73
	v_min_f32_e32 v73, 0, v72
	v_mul_f32_e64 v72, |v72|, s2
	v_exp_f32_e32 v72, v72
	s_nop 0
	v_add_f32_e32 v72, 1.0, v72
	v_cmp_gt_f32_e32 vcc, s22, v72
	s_nop 1
	v_cndmask_b32_e64 v74, 0, 32, vcc
	v_ldexp_f32 v72, v72, v74
	v_log_f32_e32 v72, v72
	s_nop 0
	v_mul_f32_e32 v74, 0x3f317217, v72
	v_fma_f32 v74, v72, s37, -v74
	v_fmac_f32_e32 v74, 0x3377d1cf, v72
	v_fmac_f32_e32 v74, 0x3f317217, v72
	v_cmp_lt_f32_e64 s[38:39], |v72|, s1
	s_nop 1
	v_cndmask_b32_e64 v72, v72, v74, s[38:39]
	v_cndmask_b32_e32 v74, 0, v213, vcc
	v_sub_f32_e32 v72, v72, v74
	v_sub_f32_e32 v72, v73, v72
	v_mul_f32_e32 v72, 0x3d800000, v72
	ds_write_b32 v71, v72
	v_or_b32_e32 v71, 9, v70
	v_lshlrev_b32_e32 v84, 6, v71
	ds_read_b128 v[72:75], v84 offset:16384
	ds_read_b128 v[76:79], v84 offset:16400
	ds_read_b128 v[80:83], v84 offset:16416
	ds_read_b128 v[84:87], v84 offset:16432
	v_lshl_or_b32 v71, v71, 9, v12
	s_waitcnt lgkmcnt(3)
	v_mul_f32_e32 v73, v68, v73
	v_fmac_f32_e32 v73, v66, v72
	v_mul_f32_e32 v72, v67, v75
	v_fmac_f32_e32 v72, v64, v74
	v_add_f32_e32 v72, v73, v72
	s_waitcnt lgkmcnt(2)
	v_mul_f32_e32 v73, v65, v77
	v_mul_f32_e32 v74, v63, v79
	v_fmac_f32_e32 v73, v60, v76
	v_fmac_f32_e32 v74, v59, v78
	v_add_f32_e32 v72, v69, v72
	v_add_f32_e32 v73, v73, v74
	v_add_f32_e32 v72, v72, v73
	s_waitcnt lgkmcnt(1)
	v_mul_f32_e32 v73, v62, v81
	v_mul_f32_e32 v74, v61, v83
	v_fmac_f32_e32 v73, v58, v80
	v_fmac_f32_e32 v74, v56, v82
	v_add_f32_e32 v73, v73, v74
	v_add_f32_e32 v72, v72, v73
	s_waitcnt lgkmcnt(0)
	v_mul_f32_e32 v73, v57, v85
	v_mul_f32_e32 v74, v55, v87
	v_fmac_f32_e32 v73, v54, v84
	v_fmac_f32_e32 v74, v53, v86
	v_add_f32_e32 v73, v73, v74
	v_add_f32_e32 v72, v72, v73
	v_min_f32_e32 v73, 0, v72
	v_mul_f32_e64 v72, |v72|, s2
	v_exp_f32_e32 v72, v72
	s_nop 0
	v_add_f32_e32 v72, 1.0, v72
	v_cmp_gt_f32_e32 vcc, s22, v72
	s_nop 1
	v_cndmask_b32_e64 v74, 0, 32, vcc
	v_ldexp_f32 v72, v72, v74
	v_log_f32_e32 v72, v72
	s_nop 0
	v_mul_f32_e32 v74, 0x3f317217, v72
	v_fma_f32 v74, v72, s37, -v74
	v_fmac_f32_e32 v74, 0x3377d1cf, v72
	v_fmac_f32_e32 v74, 0x3f317217, v72
	v_cmp_lt_f32_e64 s[38:39], |v72|, s1
	s_nop 1
	v_cndmask_b32_e64 v72, v72, v74, s[38:39]
	v_cndmask_b32_e32 v74, 0, v213, vcc
	v_sub_f32_e32 v72, v72, v74
	v_sub_f32_e32 v72, v73, v72
	v_mul_f32_e32 v72, 0x3d800000, v72
	ds_write_b32 v71, v72
	v_or_b32_e32 v71, 10, v70
	v_lshlrev_b32_e32 v84, 6, v71
	ds_read_b128 v[72:75], v84 offset:16384
	ds_read_b128 v[76:79], v84 offset:16400
	ds_read_b128 v[80:83], v84 offset:16416
	ds_read_b128 v[84:87], v84 offset:16432
	v_lshl_or_b32 v71, v71, 9, v12
	s_waitcnt lgkmcnt(3)
	v_mul_f32_e32 v73, v68, v73
	v_fmac_f32_e32 v73, v66, v72
	v_mul_f32_e32 v72, v67, v75
	v_fmac_f32_e32 v72, v64, v74
	v_add_f32_e32 v72, v73, v72
	s_waitcnt lgkmcnt(2)
	v_mul_f32_e32 v73, v65, v77
	v_mul_f32_e32 v74, v63, v79
	v_fmac_f32_e32 v73, v60, v76
	v_fmac_f32_e32 v74, v59, v78
	v_add_f32_e32 v72, v69, v72
	v_add_f32_e32 v73, v73, v74
	v_add_f32_e32 v72, v72, v73
	s_waitcnt lgkmcnt(1)
	v_mul_f32_e32 v73, v62, v81
	v_mul_f32_e32 v74, v61, v83
	v_fmac_f32_e32 v73, v58, v80
	v_fmac_f32_e32 v74, v56, v82
	v_add_f32_e32 v73, v73, v74
	v_add_f32_e32 v72, v72, v73
	s_waitcnt lgkmcnt(0)
	v_mul_f32_e32 v73, v57, v85
	v_mul_f32_e32 v74, v55, v87
	v_fmac_f32_e32 v73, v54, v84
	v_fmac_f32_e32 v74, v53, v86
	v_add_f32_e32 v73, v73, v74
	v_add_f32_e32 v72, v72, v73
	v_min_f32_e32 v73, 0, v72
	v_mul_f32_e64 v72, |v72|, s2
	v_exp_f32_e32 v72, v72
	s_nop 0
	v_add_f32_e32 v72, 1.0, v72
	v_cmp_gt_f32_e32 vcc, s22, v72
	s_nop 1
	v_cndmask_b32_e64 v74, 0, 32, vcc
	v_ldexp_f32 v72, v72, v74
	v_log_f32_e32 v72, v72
	s_nop 0
	v_mul_f32_e32 v74, 0x3f317217, v72
	v_fma_f32 v74, v72, s37, -v74
	v_fmac_f32_e32 v74, 0x3377d1cf, v72
	v_fmac_f32_e32 v74, 0x3f317217, v72
	v_cmp_lt_f32_e64 s[38:39], |v72|, s1
	s_nop 1
	v_cndmask_b32_e64 v72, v72, v74, s[38:39]
	v_cndmask_b32_e32 v74, 0, v213, vcc
	v_sub_f32_e32 v72, v72, v74
	v_sub_f32_e32 v72, v73, v72
	v_mul_f32_e32 v72, 0x3d800000, v72
	ds_write_b32 v71, v72
	v_or_b32_e32 v71, 11, v70
	v_lshlrev_b32_e32 v84, 6, v71
	ds_read_b128 v[72:75], v84 offset:16384
	ds_read_b128 v[76:79], v84 offset:16400
	ds_read_b128 v[80:83], v84 offset:16416
	ds_read_b128 v[84:87], v84 offset:16432
	v_lshl_or_b32 v71, v71, 9, v12
	s_waitcnt lgkmcnt(3)
	v_mul_f32_e32 v73, v68, v73
	v_fmac_f32_e32 v73, v66, v72
	v_mul_f32_e32 v72, v67, v75
	v_fmac_f32_e32 v72, v64, v74
	v_add_f32_e32 v72, v73, v72
	s_waitcnt lgkmcnt(2)
	v_mul_f32_e32 v73, v65, v77
	v_mul_f32_e32 v74, v63, v79
	v_fmac_f32_e32 v73, v60, v76
	v_fmac_f32_e32 v74, v59, v78
	v_add_f32_e32 v72, v69, v72
	v_add_f32_e32 v73, v73, v74
	v_add_f32_e32 v72, v72, v73
	s_waitcnt lgkmcnt(1)
	v_mul_f32_e32 v73, v62, v81
	v_mul_f32_e32 v74, v61, v83
	v_fmac_f32_e32 v73, v58, v80
	v_fmac_f32_e32 v74, v56, v82
	v_add_f32_e32 v73, v73, v74
	v_add_f32_e32 v72, v72, v73
	s_waitcnt lgkmcnt(0)
	v_mul_f32_e32 v73, v57, v85
	v_mul_f32_e32 v74, v55, v87
	v_fmac_f32_e32 v73, v54, v84
	v_fmac_f32_e32 v74, v53, v86
	v_add_f32_e32 v73, v73, v74
	v_add_f32_e32 v72, v72, v73
	v_min_f32_e32 v73, 0, v72
	v_mul_f32_e64 v72, |v72|, s2
	v_exp_f32_e32 v72, v72
	s_nop 0
	v_add_f32_e32 v72, 1.0, v72
	v_cmp_gt_f32_e32 vcc, s22, v72
	s_nop 1
	v_cndmask_b32_e64 v74, 0, 32, vcc
	v_ldexp_f32 v72, v72, v74
	v_log_f32_e32 v72, v72
	s_nop 0
	v_mul_f32_e32 v74, 0x3f317217, v72
	v_fma_f32 v74, v72, s37, -v74
	v_fmac_f32_e32 v74, 0x3377d1cf, v72
	v_fmac_f32_e32 v74, 0x3f317217, v72
	v_cmp_lt_f32_e64 s[38:39], |v72|, s1
	s_nop 1
	v_cndmask_b32_e64 v72, v72, v74, s[38:39]
	v_cndmask_b32_e32 v74, 0, v213, vcc
	v_sub_f32_e32 v72, v72, v74
	v_sub_f32_e32 v72, v73, v72
	v_mul_f32_e32 v72, 0x3d800000, v72
	ds_write_b32 v71, v72
	v_or_b32_e32 v71, 12, v70
	v_lshlrev_b32_e32 v84, 6, v71
	ds_read_b128 v[72:75], v84 offset:16384
	ds_read_b128 v[76:79], v84 offset:16400
	ds_read_b128 v[80:83], v84 offset:16416
	ds_read_b128 v[84:87], v84 offset:16432
	v_lshl_or_b32 v71, v71, 9, v12
	s_waitcnt lgkmcnt(3)
	v_mul_f32_e32 v73, v68, v73
	v_fmac_f32_e32 v73, v66, v72
	v_mul_f32_e32 v72, v67, v75
	v_fmac_f32_e32 v72, v64, v74
	v_add_f32_e32 v72, v73, v72
	s_waitcnt lgkmcnt(2)
	v_mul_f32_e32 v73, v65, v77
	v_mul_f32_e32 v74, v63, v79
	v_fmac_f32_e32 v73, v60, v76
	v_fmac_f32_e32 v74, v59, v78
	v_add_f32_e32 v72, v69, v72
	v_add_f32_e32 v73, v73, v74
	v_add_f32_e32 v72, v72, v73
	s_waitcnt lgkmcnt(1)
	v_mul_f32_e32 v73, v62, v81
	v_mul_f32_e32 v74, v61, v83
	v_fmac_f32_e32 v73, v58, v80
	v_fmac_f32_e32 v74, v56, v82
	v_add_f32_e32 v73, v73, v74
	v_add_f32_e32 v72, v72, v73
	s_waitcnt lgkmcnt(0)
	v_mul_f32_e32 v73, v57, v85
	v_mul_f32_e32 v74, v55, v87
	v_fmac_f32_e32 v73, v54, v84
	v_fmac_f32_e32 v74, v53, v86
	v_add_f32_e32 v73, v73, v74
	v_add_f32_e32 v72, v72, v73
	v_min_f32_e32 v73, 0, v72
	v_mul_f32_e64 v72, |v72|, s2
	v_exp_f32_e32 v72, v72
	s_nop 0
	v_add_f32_e32 v72, 1.0, v72
	v_cmp_gt_f32_e32 vcc, s22, v72
	s_nop 1
	v_cndmask_b32_e64 v74, 0, 32, vcc
	v_ldexp_f32 v72, v72, v74
	v_log_f32_e32 v72, v72
	s_nop 0
	v_mul_f32_e32 v74, 0x3f317217, v72
	v_fma_f32 v74, v72, s37, -v74
	v_fmac_f32_e32 v74, 0x3377d1cf, v72
	v_fmac_f32_e32 v74, 0x3f317217, v72
	v_cmp_lt_f32_e64 s[38:39], |v72|, s1
	s_nop 1
	v_cndmask_b32_e64 v72, v72, v74, s[38:39]
	v_cndmask_b32_e32 v74, 0, v213, vcc
	v_sub_f32_e32 v72, v72, v74
	v_sub_f32_e32 v72, v73, v72
	v_mul_f32_e32 v72, 0x3d800000, v72
	ds_write_b32 v71, v72
	v_or_b32_e32 v71, 13, v70
	v_lshlrev_b32_e32 v84, 6, v71
	ds_read_b128 v[72:75], v84 offset:16384
	ds_read_b128 v[76:79], v84 offset:16400
	ds_read_b128 v[80:83], v84 offset:16416
	ds_read_b128 v[84:87], v84 offset:16432
	v_lshl_or_b32 v71, v71, 9, v12
	s_waitcnt lgkmcnt(3)
	v_mul_f32_e32 v73, v68, v73
	v_fmac_f32_e32 v73, v66, v72
	v_mul_f32_e32 v72, v67, v75
	v_fmac_f32_e32 v72, v64, v74
	v_add_f32_e32 v72, v73, v72
	s_waitcnt lgkmcnt(2)
	v_mul_f32_e32 v73, v65, v77
	v_mul_f32_e32 v74, v63, v79
	v_fmac_f32_e32 v73, v60, v76
	v_fmac_f32_e32 v74, v59, v78
	v_add_f32_e32 v72, v69, v72
	v_add_f32_e32 v73, v73, v74
	v_add_f32_e32 v72, v72, v73
	s_waitcnt lgkmcnt(1)
	v_mul_f32_e32 v73, v62, v81
	v_mul_f32_e32 v74, v61, v83
	v_fmac_f32_e32 v73, v58, v80
	v_fmac_f32_e32 v74, v56, v82
	v_add_f32_e32 v73, v73, v74
	v_add_f32_e32 v72, v72, v73
	s_waitcnt lgkmcnt(0)
	v_mul_f32_e32 v73, v57, v85
	v_mul_f32_e32 v74, v55, v87
	v_fmac_f32_e32 v73, v54, v84
	v_fmac_f32_e32 v74, v53, v86
	v_add_f32_e32 v73, v73, v74
	v_add_f32_e32 v72, v72, v73
	v_min_f32_e32 v73, 0, v72
	v_mul_f32_e64 v72, |v72|, s2
	v_exp_f32_e32 v72, v72
	v_or_b32_e32 v86, 14, v70
	v_lshlrev_b32_e32 v82, 6, v86
	v_add_f32_e32 v72, 1.0, v72
	v_cmp_gt_f32_e32 vcc, s22, v72
	s_nop 1
	v_cndmask_b32_e64 v74, 0, 32, vcc
	v_ldexp_f32 v72, v72, v74
	v_log_f32_e32 v72, v72
	s_nop 0
	v_mul_f32_e32 v74, 0x3f317217, v72
	v_fma_f32 v74, v72, s37, -v74
	v_fmac_f32_e32 v74, 0x3377d1cf, v72
	v_fmac_f32_e32 v74, 0x3f317217, v72
	v_cmp_lt_f32_e64 s[38:39], |v72|, s1
	s_nop 1
	v_cndmask_b32_e64 v72, v72, v74, s[38:39]
	v_cndmask_b32_e32 v74, 0, v213, vcc
	v_sub_f32_e32 v72, v72, v74
	v_sub_f32_e32 v72, v73, v72
	v_mul_f32_e32 v72, 0x3d800000, v72
	ds_write_b32 v71, v72
	ds_read_b128 v[70:73], v82 offset:16384
	ds_read_b128 v[74:77], v82 offset:16400
	ds_read_b128 v[78:81], v82 offset:16416
	ds_read_b128 v[82:85], v82 offset:16432
	s_waitcnt lgkmcnt(3)
	v_mul_f32_e32 v71, v68, v71
	v_fmac_f32_e32 v71, v66, v70
	v_mul_f32_e32 v70, v67, v73
	v_fmac_f32_e32 v70, v64, v72
	v_add_f32_e32 v70, v71, v70
	s_waitcnt lgkmcnt(2)
	v_mul_f32_e32 v71, v65, v75
	v_mul_f32_e32 v72, v63, v77
	v_fmac_f32_e32 v71, v60, v74
	v_fmac_f32_e32 v72, v59, v76
	v_add_f32_e32 v70, v69, v70
	v_add_f32_e32 v71, v71, v72
	v_add_f32_e32 v70, v70, v71
	s_waitcnt lgkmcnt(1)
	v_mul_f32_e32 v71, v62, v79
	v_mul_f32_e32 v72, v61, v81
	v_fmac_f32_e32 v71, v58, v78
	v_fmac_f32_e32 v72, v56, v80
	v_add_f32_e32 v71, v71, v72
	v_add_f32_e32 v70, v70, v71
	s_waitcnt lgkmcnt(0)
	v_mul_f32_e32 v71, v57, v83
	v_mul_f32_e32 v72, v55, v85
	v_fmac_f32_e32 v71, v54, v82
	v_fmac_f32_e32 v72, v53, v84
	v_add_f32_e32 v71, v71, v72
	v_add_f32_e32 v70, v70, v71
	v_min_f32_e32 v71, 0, v70
	v_mul_f32_e64 v70, |v70|, s2
	v_exp_f32_e32 v70, v70
	v_lshlrev_b32_e32 v82, 6, v13
	v_add_f32_e32 v70, 1.0, v70
	v_cmp_gt_f32_e32 vcc, s22, v70
	s_nop 1
	v_cndmask_b32_e64 v72, 0, 32, vcc
	v_ldexp_f32 v70, v70, v72
	v_log_f32_e32 v70, v70
	s_nop 0
	v_mul_f32_e32 v72, 0x3f317217, v70
	v_fma_f32 v72, v70, s37, -v72
	v_fmac_f32_e32 v72, 0x3377d1cf, v70
	v_fmac_f32_e32 v72, 0x3f317217, v70
	v_cmp_lt_f32_e64 s[38:39], |v70|, s1
	s_nop 1
	v_cndmask_b32_e64 v70, v70, v72, s[38:39]
	v_cndmask_b32_e32 v72, 0, v213, vcc
	v_sub_f32_e32 v70, v70, v72
	v_sub_f32_e32 v70, v71, v70
	v_mul_f32_e32 v70, 0x3d800000, v70
	v_lshl_or_b32 v71, v86, 9, v12
	ds_write_b32 v71, v70
	ds_read_b128 v[70:73], v82 offset:16384
	ds_read_b128 v[74:77], v82 offset:16400
	ds_read_b128 v[78:81], v82 offset:16416
	ds_read_b128 v[82:85], v82 offset:16432
	v_lshl_or_b32 v12, v13, 9, v12
	s_waitcnt lgkmcnt(3)
	v_mul_f32_e32 v68, v68, v71
	s_waitcnt lgkmcnt(2)
	v_mul_f32_e32 v65, v65, v75
	v_fmac_f32_e32 v65, v60, v74
	v_mul_f32_e32 v60, v63, v77
	v_fmac_f32_e32 v68, v66, v70
	v_mul_f32_e32 v66, v67, v73
	v_fmac_f32_e32 v60, v59, v76
	v_fmac_f32_e32 v66, v64, v72
	v_add_f32_e32 v59, v65, v60
	s_waitcnt lgkmcnt(1)
	v_mul_f32_e32 v60, v62, v79
	v_add_f32_e32 v64, v68, v66
	v_fmac_f32_e32 v60, v58, v78
	v_mul_f32_e32 v58, v61, v81
	s_waitcnt lgkmcnt(0)
	v_mul_f32_e32 v57, v57, v83
	v_add_f32_e32 v64, v69, v64
	v_fmac_f32_e32 v58, v56, v80
	v_fmac_f32_e32 v57, v54, v82
	v_mul_f32_e32 v54, v55, v85
	v_add_f32_e32 v59, v64, v59
	v_add_f32_e32 v56, v60, v58
	v_fmac_f32_e32 v54, v53, v84
	v_add_f32_e32 v56, v59, v56
	v_add_f32_e32 v53, v57, v54
	v_add_f32_e32 v53, v56, v53
	v_min_f32_e32 v54, 0, v53
	v_mul_f32_e64 v53, |v53|, s2
	v_exp_f32_e32 v53, v53
	s_movk_i32 s2, 0x80
	v_add_f32_e32 v53, 1.0, v53
	v_cmp_gt_f32_e32 vcc, s22, v53
	s_nop 1
	v_cndmask_b32_e64 v55, 0, 32, vcc
	v_ldexp_f32 v53, v53, v55
	v_log_f32_e32 v53, v53
	s_nop 0
	v_mul_f32_e32 v55, 0x3f317217, v53
	v_fma_f32 v55, v53, s37, -v55
	v_fmac_f32_e32 v55, 0x3377d1cf, v53
	v_fmac_f32_e32 v55, 0x3f317217, v53
	v_cmp_lt_f32_e64 s[38:39], |v53|, s1
	s_nop 1
	v_cndmask_b32_e64 v53, v53, v55, s[38:39]
	v_cndmask_b32_e32 v55, 0, v213, vcc
	v_sub_f32_e32 v53, v53, v55
	v_sub_f32_e32 v53, v54, v53
	v_mul_f32_e32 v53, 0x3d800000, v53
	v_cmp_gt_i32_e32 vcc, s2, v52
	ds_write_b32 v12, v53
	s_waitcnt lgkmcnt(0)
	s_barrier
	s_and_saveexec_b64 s[2:3], vcc
	s_cbranch_execz .LBB0_474
	ds_read2st64_b32 v[12:13], v9 offset1:2
	s_waitcnt lgkmcnt(0)
	v_add_f32_e32 v12, 0, v12
	v_add_f32_e32 v52, v12, v13
	ds_write2st64_b32 v9, v12, v52 offset1:2
	ds_read2st64_b32 v[12:13], v9 offset0:4 offset1:6
	s_waitcnt lgkmcnt(0)
	v_add_f32_e32 v12, v52, v12
	v_add_f32_e32 v52, v12, v13
	ds_write2st64_b32 v9, v12, v52 offset0:4 offset1:6
	ds_read2st64_b32 v[12:13], v9 offset0:8 offset1:10
	s_waitcnt lgkmcnt(0)
	v_add_f32_e32 v12, v52, v12
	v_add_f32_e32 v52, v12, v13
	ds_write2st64_b32 v9, v12, v52 offset0:8 offset1:10
	ds_read2st64_b32 v[12:13], v9 offset0:12 offset1:14
	s_waitcnt lgkmcnt(0)
	v_add_f32_e32 v12, v52, v12
	v_add_f32_e32 v52, v12, v13
	ds_write2st64_b32 v9, v12, v52 offset0:12 offset1:14
	ds_read2st64_b32 v[12:13], v9 offset0:16 offset1:18
	s_waitcnt lgkmcnt(0)
	v_add_f32_e32 v12, v52, v12
	v_add_f32_e32 v52, v12, v13
	ds_write2st64_b32 v9, v12, v52 offset0:16 offset1:18
	ds_read2st64_b32 v[12:13], v9 offset0:20 offset1:22
	s_waitcnt lgkmcnt(0)
	v_add_f32_e32 v12, v52, v12
	v_add_f32_e32 v52, v12, v13
	ds_write2st64_b32 v9, v12, v52 offset0:20 offset1:22
	ds_read2st64_b32 v[12:13], v9 offset0:24 offset1:26
	s_waitcnt lgkmcnt(0)
	v_add_f32_e32 v12, v52, v12
	v_add_f32_e32 v52, v12, v13
	ds_write2st64_b32 v9, v12, v52 offset0:24 offset1:26
	ds_read2st64_b32 v[12:13], v9 offset0:28 offset1:30
	s_waitcnt lgkmcnt(0)
	v_add_f32_e32 v12, v52, v12
	v_add_f32_e32 v52, v12, v13
	ds_write2st64_b32 v9, v12, v52 offset0:28 offset1:30
	ds_read2st64_b32 v[12:13], v9 offset0:32 offset1:34
	s_waitcnt lgkmcnt(0)
	v_add_f32_e32 v12, v52, v12
	v_add_f32_e32 v52, v12, v13
	ds_write2st64_b32 v9, v12, v52 offset0:32 offset1:34
	ds_read2st64_b32 v[12:13], v9 offset0:36 offset1:38
	s_waitcnt lgkmcnt(0)
	v_add_f32_e32 v12, v52, v12
	v_add_f32_e32 v52, v12, v13
	ds_write2st64_b32 v9, v12, v52 offset0:36 offset1:38
	ds_read2st64_b32 v[12:13], v9 offset0:40 offset1:42
	s_waitcnt lgkmcnt(0)
	v_add_f32_e32 v12, v52, v12
	v_add_f32_e32 v52, v12, v13
	ds_write2st64_b32 v9, v12, v52 offset0:40 offset1:42
	ds_read2st64_b32 v[12:13], v9 offset0:44 offset1:46
	s_waitcnt lgkmcnt(0)
	v_add_f32_e32 v12, v52, v12
	v_add_f32_e32 v52, v12, v13
	ds_write2st64_b32 v9, v12, v52 offset0:44 offset1:46
	ds_read2st64_b32 v[12:13], v9 offset0:48 offset1:50
	s_waitcnt lgkmcnt(0)
	v_add_f32_e32 v12, v52, v12
	v_add_f32_e32 v52, v12, v13
	ds_write2st64_b32 v9, v12, v52 offset0:48 offset1:50
	ds_read2st64_b32 v[12:13], v9 offset0:52 offset1:54
	s_waitcnt lgkmcnt(0)
	v_add_f32_e32 v12, v52, v12
	v_add_f32_e32 v52, v12, v13
	ds_write2st64_b32 v9, v12, v52 offset0:52 offset1:54
	ds_read2st64_b32 v[12:13], v9 offset0:56 offset1:58
	s_waitcnt lgkmcnt(0)
	v_add_f32_e32 v12, v52, v12
	v_add_f32_e32 v52, v12, v13
	ds_write2st64_b32 v9, v12, v52 offset0:56 offset1:58
	ds_read2st64_b32 v[12:13], v9 offset0:60 offset1:62
	s_waitcnt lgkmcnt(0)
	v_add_f32_e32 v12, v52, v12
	v_add_f32_e32 v13, v12, v13
	ds_write2st64_b32 v9, v12, v13 offset0:60 offset1:62

.LBB0_745:
	v_readlane_b32 s0, v248, 29
	v_readlane_b32 s1, v248, 30
	s_and_b64 vcc, exec, s[0:1]
	s_cbranch_vccnz .LBB0_748
	v_ashrrev_i32_e32 v0, 4, v197
	v_and_b32_e32 v1, -4, v0
	v_lshlrev_b32_e32 v0, 2, v197
	v_and_b32_e32 v0, 0xfc, v0
	v_mov_b32_e32 v25, 0
	v_lshlrev_b32_e32 v24, 1, v0
	v_lshl_add_u64 v[26:27], s[4:5], 0, v[24:25]
	v_readlane_b32 s0, v250, 0
	v_lshlrev_b32_e32 v24, 2, v0
	v_readlane_b32 s1, v250, 1
	v_readlane_b32 s2, v250, 2
	v_readlane_b32 s3, v250, 3
	v_readlane_b32 s4, v250, 4
	v_readlane_b32 s5, v250, 5
	v_lshl_add_u64 v[2:3], s[2:3], 0, v[24:25]
	s_mov_b64 s[0:1], 0x1000
	v_lshl_add_u64 v[4:5], s[4:5], 0, v[24:25]
	v_lshl_add_u64 v[28:29], v[2:3], 0, s[0:1]
	v_lshl_add_u64 v[30:31], v[4:5], 0, s[0:1]
	s_mov_b64 s[0:1], 0x1400
	v_lshl_add_u64 v[32:33], v[2:3], 0, s[0:1]
	v_lshl_add_u64 v[34:35], v[4:5], 0, s[0:1]
	s_mov_b64 s[0:1], 0x1800
	v_readlane_b32 s6, v250, 6
	v_readlane_b32 s7, v250, 7
	v_lshl_add_u64 v[36:37], v[2:3], 0, s[0:1]
	v_lshl_add_u64 v[38:39], v[4:5], 0, s[0:1]
	s_mov_b64 s[0:1], 0x1c00
	v_lshl_add_u64 v[40:41], v[2:3], 0, s[0:1]
	v_lshl_add_u64 v[42:43], v[4:5], 0, s[0:1]
	v_lshl_add_u64 v[44:45], s[6:7], 0, v[24:25]
	v_readlane_b32 s0, v249, 25
	s_mov_b32 s6, 0x3727c5ac
	v_lshlrev_b32_e32 v24, 2, v0
	v_add_u32_e32 v46, s0, v1
	s_mov_b64 s[0:1], 0x2000
	s_movk_i32 s3, 0x2000
	s_mov_b32 s2, 0x3fb504f3
	s_mov_b32 s4, 0x3a800000
	s_waitcnt vmcnt(8)
	v_mov_b64_e32 v[48:49], s[6:7]
	s_mov_b32 s5, 0x800000
	global_load_dwordx4 v[216:219], v[28:29], off
	global_load_dwordx4 v[220:223], v[30:31], off
	global_load_dwordx4 v[224:227], v[32:33], off
	global_load_dwordx4 v[228:231], v[34:35], off
	global_load_dwordx4 v[232:235], v[36:37], off
	global_load_dwordx4 v[236:239], v[38:39], off
	global_load_dwordx4 v[240:243], v[40:41], off
	global_load_dwordx4 v[244:247], v[42:43], off
	s_waitcnt vmcnt(0)
.LBB0_747:
	v_ashrrev_i32_e32 v47, 31, v46
	v_lshrrev_b32_e32 v2, 20, v47
	v_add_u32_e32 v2, v46, v2
	v_lshlrev_b64 v[0:1], 11, v[46:47]
	v_ashrrev_i32_e32 v2, 12, v2
	v_lshl_add_u64 v[50:51], v[26:27], 0, v[0:1]
	v_add_u32_e32 v0, 4, v2
	v_mul_hi_i32_i24_e32 v1, 0x3000, v0
	v_mul_i32_i24_e32 v0, 0x3000, v0
	v_lshl_add_u64 v[0:1], s[84:85], 0, v[0:1]
	v_lshl_add_u64 v[4:5], v[0:1], 0, v[24:25]
	v_add_co_u32_e32 v0, vcc, s3, v4
	v_lshlrev_b64 v[16:17], 12, v[46:47]
	s_nop 0
	v_addc_co_u32_e32 v1, vcc, 0, v5, vcc
	v_lshl_add_u64 v[12:13], v[4:5], 0, s[0:1]
	v_lshl_add_u64 v[60:61], v[44:45], 0, v[16:17]
	global_load_dwordx2 v[70:71], v[50:51], off nt
	global_load_dwordx2 v[72:73], v[50:51], off offset:512 nt
	global_load_dwordx2 v[74:75], v[50:51], off offset:1024 nt
	s_add_i32 s74, s74, s26
	global_load_dwordx4 v[0:3], v[0:1], off
	s_nop 0
	global_load_dwordx4 v[4:7], v[12:13], off offset:1024
	global_load_dwordx4 v[8:11], v[12:13], off offset:2048
	s_cmpk_lt_i32 s74, 0x400
	global_load_dwordx4 v[12:15], v[12:13], off offset:3072
	s_nop 0
	global_load_dwordx4 v[16:19], v[60:61], off nt
	global_load_dwordx4 v[20:23], v[60:61], off offset:1024 nt
	global_load_dwordx4 v[52:55], v[60:61], off offset:2048 nt
	global_load_dwordx4 v[56:59], v[60:61], off offset:3072 nt
	global_load_dwordx2 v[112:113], v[50:51], off offset:1536 nt
	v_add_u32_e32 v50, 1, v46
	v_ashrrev_i32_e32 v51, 31, v50
	v_lshrrev_b32_e32 v47, 20, v51
	v_add_u32_e32 v47, v50, v47
	v_ashrrev_i32_e32 v47, 12, v47
	v_add_u32_e32 v47, 4, v47
	v_mul_hi_i32_i24_e32 v63, 0x3000, v47
	v_mul_i32_i24_e32 v62, 0x3000, v47
	v_lshl_add_u64 v[62:63], s[84:85], 0, v[62:63]
	v_lshl_add_u64 v[76:77], v[62:63], 0, v[24:25]
	v_lshlrev_b64 v[66:67], 11, v[50:51]
	v_add_co_u32_e32 v62, vcc, s3, v76
	v_lshl_add_u64 v[78:79], v[26:27], 0, v[66:67]
	s_nop 0
	v_addc_co_u32_e32 v63, vcc, 0, v77, vcc
	global_load_dwordx4 v[62:65], v[62:63], off
	v_lshlrev_b64 v[50:51], 12, v[50:51]
	global_load_dwordx2 v[114:115], v[78:79], off nt
	v_lshl_add_u64 v[50:51], v[44:45], 0, v[50:51]
	global_load_dwordx4 v[66:69], v[50:51], off nt
	v_lshl_add_u64 v[76:77], v[76:77], 0, s[0:1]
	global_load_dwordx4 v[88:91], v[76:77], off offset:1024
	global_load_dwordx2 v[116:117], v[78:79], off offset:512 nt
	global_load_dwordx4 v[92:95], v[50:51], off offset:1024 nt
	global_load_dwordx4 v[96:99], v[76:77], off offset:2048
	global_load_dwordx2 v[118:119], v[78:79], off offset:1024 nt
	global_load_dwordx4 v[100:103], v[50:51], off offset:2048 nt
	global_load_dwordx4 v[104:107], v[76:77], off offset:3072
	global_load_dwordx2 v[120:121], v[78:79], off offset:1536 nt
	global_load_dwordx4 v[108:111], v[50:51], off offset:3072 nt
	s_waitcnt vmcnt(23)
	v_lshlrev_b32_e32 v76, 16, v70
	v_and_b32_e32 v77, 0xffff0000, v70
	v_lshlrev_b32_e32 v70, 16, v71
	v_and_b32_e32 v71, 0xffff0000, v71
	s_waitcnt vmcnt(22)
	v_lshlrev_b32_e32 v78, 16, v72
	v_and_b32_e32 v79, 0xffff0000, v72
	s_waitcnt vmcnt(20)
	v_pk_add_f32 v[2:3], v[2:3], 1.0 op_sel_hi:[1,0]
	v_pk_add_f32 v[0:1], v[0:1], 1.0 op_sel_hi:[1,0]
	s_waitcnt vmcnt(19)
	v_pk_add_f32 v[4:5], v[4:5], 1.0 op_sel_hi:[1,0]
	v_lshlrev_b32_e32 v80, 16, v74
	v_and_b32_e32 v81, 0xffff0000, v74
	s_waitcnt vmcnt(18)
	v_pk_add_f32 v[8:9], v[8:9], 1.0 op_sel_hi:[1,0]
	v_pk_mul_f32 v[2:3], v[2:3], v[70:71]
	v_pk_mul_f32 v[0:1], v[0:1], v[76:77]
	v_pk_mul_f32 v[4:5], v[4:5], v[78:79]
	s_waitcnt vmcnt(17)
	v_pk_add_f32 v[14:15], v[14:15], 1.0 op_sel_hi:[1,0]
	v_pk_mul_f32 v[8:9], v[8:9], v[80:81]
	s_waitcnt vmcnt(16)
	v_pk_fma_f32 v[84:85], v[18:19], s[2:3], v[2:3] op_sel_hi:[1,0,1]
	v_pk_fma_f32 v[86:87], v[16:17], s[2:3], v[0:1] op_sel_hi:[1,0,1]
	s_waitcnt vmcnt(15)
	v_pk_fma_f32 v[80:81], v[20:21], s[2:3], v[4:5] op_sel_hi:[1,0,1]
	v_pk_add_f32 v[0:1], v[12:13], 1.0 op_sel_hi:[1,0]
	s_waitcnt vmcnt(12)
	v_lshlrev_b32_e32 v2, 16, v112
	v_and_b32_e32 v3, 0xffff0000, v112
	v_lshlrev_b32_e32 v4, 16, v113
	v_and_b32_e32 v5, 0xffff0000, v113
	v_lshlrev_b32_e32 v72, 16, v73
	v_and_b32_e32 v73, 0xffff0000, v73
	v_pk_add_f32 v[6:7], v[6:7], 1.0 op_sel_hi:[1,0]
	v_pk_mul_f32 v[0:1], v[0:1], v[2:3]
	v_pk_mul_f32 v[2:3], v[14:15], v[4:5]
	v_pk_mul_f32 v[6:7], v[6:7], v[72:73]
	v_pk_fma_f32 v[72:73], v[58:59], s[2:3], v[2:3] op_sel_hi:[1,0,1]
	s_waitcnt vmcnt(11)
	v_pk_add_f32 v[2:3], v[62:63], 1.0 op_sel_hi:[1,0]
	s_waitcnt vmcnt(10)
	v_lshlrev_b32_e32 v4, 16, v114
	v_and_b32_e32 v5, 0xffff0000, v114
	v_pk_mul_f32 v[2:3], v[2:3], v[4:5]
	s_waitcnt vmcnt(7)
	v_lshlrev_b32_e32 v4, 16, v116
	v_pk_fma_f32 v[66:67], v[66:67], s[2:3], v[2:3] op_sel_hi:[1,0,1]
	v_pk_add_f32 v[2:3], v[88:89], 1.0 op_sel_hi:[1,0]
	v_and_b32_e32 v5, 0xffff0000, v116
	v_pk_mul_f32 v[2:3], v[2:3], v[4:5]
	s_waitcnt vmcnt(4)
	v_lshlrev_b32_e32 v4, 16, v118
	v_pk_fma_f32 v[62:63], v[92:93], s[2:3], v[2:3] op_sel_hi:[1,0,1]
	v_pk_add_f32 v[2:3], v[96:97], 1.0 op_sel_hi:[1,0]
	v_and_b32_e32 v5, 0xffff0000, v118
	v_pk_mul_f32 v[2:3], v[2:3], v[4:5]
	v_lshlrev_b32_e32 v74, 16, v75
	v_and_b32_e32 v75, 0xffff0000, v75
	v_pk_add_f32 v[10:11], v[10:11], 1.0 op_sel_hi:[1,0]
	v_pk_fma_f32 v[82:83], v[22:23], s[2:3], v[6:7] op_sel_hi:[1,0,1]
	v_pk_fma_f32 v[70:71], v[56:57], s[2:3], v[0:1] op_sel_hi:[1,0,1]
	s_waitcnt vmcnt(3)
	v_pk_fma_f32 v[56:57], v[100:101], s[2:3], v[2:3] op_sel_hi:[1,0,1]
	s_waitcnt vmcnt(2)
	v_pk_add_f32 v[2:3], v[104:105], 1.0 op_sel_hi:[1,0]
	v_add_f32_e32 v47, v86, v87
	v_add_f32_e32 v104, v84, v85
	v_pk_mul_f32 v[10:11], v[10:11], v[74:75]
	v_add_f32_e32 v47, v47, v104
	v_add_f32_e32 v104, v80, v81
	v_add_f32_e32 v105, v82, v83
	v_pk_fma_f32 v[78:79], v[54:55], s[2:3], v[10:11] op_sel_hi:[1,0,1]
	v_pk_fma_f32 v[76:77], v[52:53], s[2:3], v[8:9] op_sel_hi:[1,0,1]
	v_add_f32_e32 v47, 0, v47
	v_add_f32_e32 v104, v104, v105
	v_add_f32_e32 v47, v47, v104
	v_add_f32_e32 v104, v76, v77
	v_add_f32_e32 v105, v78, v79
	v_add_f32_e32 v104, v104, v105
	v_add_f32_e32 v47, v47, v104
	v_add_f32_e32 v104, v70, v71
	v_add_f32_e32 v105, v72, v73
	v_add_f32_e32 v104, v104, v105
	v_add_f32_e32 v47, v47, v104
	v_pk_add_f32 v[0:1], v[64:65], 1.0 op_sel_hi:[1,0]
	v_lshlrev_b32_e32 v6, 16, v115
	v_add_f32_dpp v47, v47, v47 row_ror:8 row_mask:0xf bank_mask:0xf bound_ctrl:1
	v_and_b32_e32 v7, 0xffff0000, v115
	v_pk_mul_f32 v[0:1], v[0:1], v[6:7]
	v_add_f32_dpp v47, v47, v47 row_ror:4 row_mask:0xf bank_mask:0xf bound_ctrl:1
	v_pk_fma_f32 v[68:69], v[68:69], s[2:3], v[0:1] op_sel_hi:[1,0,1]
	v_pk_add_f32 v[0:1], v[90:91], 1.0 op_sel_hi:[1,0]
	v_add_f32_dpp v47, v47, v47 row_ror:2 row_mask:0xf bank_mask:0xf bound_ctrl:1
	v_lshlrev_b32_e32 v6, 16, v117
	v_and_b32_e32 v7, 0xffff0000, v117
	v_add_f32_dpp v47, v47, v47 row_ror:1 row_mask:0xf bank_mask:0xf bound_ctrl:1
	v_mov_b32_e32 v104, v47
	s_nop 1
	v_permlane16_swap_b32_e32 v47, v104
	v_add_f32_e32 v47, v47, v104
	v_mov_b32_e32 v104, v47
	s_nop 1
	v_permlane32_swap_b32_e32 v47, v104
	v_add_f32_e32 v47, v47, v104
	v_pk_mul_f32 v[0:1], v[0:1], v[6:7]
	v_fmac_f32_e32 v85, 0xba800000, v47
	v_fmac_f32_e32 v87, 0xba800000, v47
	v_pk_fma_f32 v[64:65], v[94:95], s[2:3], v[0:1] op_sel_hi:[1,0,1]
	v_pk_add_f32 v[0:1], v[98:99], 1.0 op_sel_hi:[1,0]
	v_lshlrev_b32_e32 v6, 16, v119
	v_and_b32_e32 v7, 0xffff0000, v119
	s_waitcnt vmcnt(1)
	v_lshlrev_b32_e32 v4, 16, v120
	v_and_b32_e32 v5, 0xffff0000, v120
	v_add_u32_e32 v74, 2, v46
	v_fmamk_f32 v84, v47, 0xba800000, v84
	v_fmamk_f32 v86, v47, 0xba800000, v86
	v_mul_f32_e32 v104, v87, v87
	v_mul_f32_e32 v105, v85, v85
	v_pk_mul_f32 v[0:1], v[0:1], v[6:7]
	v_pk_mul_f32 v[2:3], v[2:3], v[4:5]
	v_ashrrev_i32_e32 v75, 31, v74
	v_fmac_f32_e32 v104, v86, v86
	v_fmac_f32_e32 v105, v84, v84
	v_fmac_f32_e32 v83, 0xba800000, v47
	v_fmac_f32_e32 v81, 0xba800000, v47
	v_pk_fma_f32 v[58:59], v[102:103], s[2:3], v[0:1] op_sel_hi:[1,0,1]
	v_pk_add_f32 v[0:1], v[106:107], 1.0 op_sel_hi:[1,0]
	s_waitcnt vmcnt(0)
	v_pk_fma_f32 v[52:53], v[108:109], s[2:3], v[2:3] op_sel_hi:[1,0,1]
	v_lshrrev_b32_e32 v2, 20, v75
	v_add_f32_e32 v104, v104, v105
	v_fmamk_f32 v82, v47, 0xba800000, v82
	v_fmamk_f32 v80, v47, 0xba800000, v80
	v_mul_f32_e32 v105, v81, v81
	v_mul_f32_e32 v106, v83, v83
	v_add_u32_e32 v2, v74, v2
	v_fmac_f32_e32 v105, v80, v80
	v_fmac_f32_e32 v106, v82, v82
	v_ashrrev_i32_e32 v2, 12, v2
	v_add_f32_e32 v105, v105, v106
	v_fmac_f32_e32 v79, 0xba800000, v47
	v_fmac_f32_e32 v77, 0xba800000, v47
	v_lshlrev_b32_e32 v6, 16, v121
	v_and_b32_e32 v7, 0xffff0000, v121
	v_add_u32_e32 v2, 4, v2
	v_add_f32_e32 v104, v104, v105
	v_fmamk_f32 v78, v47, 0xba800000, v78
	v_fmamk_f32 v76, v47, 0xba800000, v76
	v_mul_f32_e32 v105, v77, v77
	v_mul_f32_e32 v106, v79, v79
	v_pk_mul_f32 v[0:1], v[0:1], v[6:7]
	v_mul_hi_i32_i24_e32 v3, 0x3000, v2
	v_mul_i32_i24_e32 v2, 0x3000, v2
	v_fmac_f32_e32 v105, v76, v76
	v_fmac_f32_e32 v106, v78, v78
	v_pk_fma_f32 v[54:55], v[110:111], s[2:3], v[0:1] op_sel_hi:[1,0,1]
	v_lshlrev_b64 v[0:1], 11, v[74:75]
	v_lshl_add_u64 v[2:3], s[84:85], 0, v[2:3]
	v_add_f32_e32 v105, v105, v106
	v_fmac_f32_e32 v73, 0xba800000, v47
	v_fmac_f32_e32 v71, 0xba800000, v47
	v_lshl_add_u64 v[16:17], v[26:27], 0, v[0:1]
	v_lshl_add_u64 v[0:1], v[2:3], 0, v[24:25]
	v_add_u32_e32 v96, 3, v46
	v_add_f32_e32 v104, v105, v104
	v_fmamk_f32 v72, v47, 0xba800000, v72
	v_fmamk_f32 v70, v47, 0xba800000, v70
	v_mul_f32_e32 v47, v71, v71
	v_mul_f32_e32 v105, v73, v73
	v_lshl_add_u64 v[18:19], v[0:1], 0, s[0:1]
	v_add_co_u32_e32 v20, vcc, s3, v0
	v_ashrrev_i32_e32 v97, 31, v96
	v_fmac_f32_e32 v47, v70, v70
	v_fmac_f32_e32 v105, v72, v72
	v_addc_co_u32_e32 v21, vcc, 0, v1, vcc
	global_load_dwordx4 v[0:3], v[18:19], off offset:1024
	global_load_dwordx4 v[4:7], v[18:19], off offset:2048
	global_load_dwordx2 v[92:93], v[16:17], off nt
	global_load_dwordx2 v[90:91], v[16:17], off offset:512 nt
	global_load_dwordx2 v[88:89], v[16:17], off offset:1024 nt
	global_load_dwordx2 v[94:95], v[16:17], off offset:1536 nt
	global_load_dwordx4 v[12:15], v[20:21], off
	global_load_dwordx4 v[8:11], v[18:19], off offset:3072
	v_lshrrev_b32_e32 v18, 20, v97
	v_add_f32_e32 v47, v47, v105
	v_add_u32_e32 v18, v96, v18
	v_add_f32_e32 v47, v47, v104
	v_ashrrev_i32_e32 v18, 12, v18
	v_add_u32_e32 v18, 4, v18
	v_add_f32_dpp v47, v47, v47 row_ror:8 row_mask:0xf bank_mask:0xf bound_ctrl:1
	v_mul_hi_i32_i24_e32 v19, 0x3000, v18
	v_mul_i32_i24_e32 v18, 0x3000, v18
	v_add_f32_dpp v47, v47, v47 row_ror:4 row_mask:0xf bank_mask:0xf bound_ctrl:1
	v_lshlrev_b64 v[16:17], 11, v[96:97]
	v_lshl_add_u64 v[18:19], s[84:85], 0, v[18:19]
	v_add_f32_dpp v47, v47, v47 row_ror:2 row_mask:0xf bank_mask:0xf bound_ctrl:1
	v_lshl_add_u64 v[98:99], v[26:27], 0, v[16:17]
	v_lshl_add_u64 v[16:17], v[18:19], 0, v[24:25]
	v_add_f32_dpp v47, v47, v47 row_ror:1 row_mask:0xf bank_mask:0xf bound_ctrl:1
	v_mov_b32_e32 v104, v47
	v_lshl_add_u64 v[100:101], v[16:17], 0, s[0:1]
	v_add_co_u32_e32 v102, vcc, s3, v16
	v_permlane16_swap_b32_e32 v47, v104
	s_nop 0
	v_addc_co_u32_e32 v103, vcc, 0, v17, vcc
	global_load_dwordx4 v[16:19], v[100:101], off offset:1024
	global_load_dwordx4 v[20:23], v[100:101], off offset:2048
	v_add_f32_e32 v113, v47, v104
	s_nop 1
	v_mov_b64_e32 v[104:105], v[216:217]
	v_mov_b64_e32 v[106:107], v[218:219]
	s_nop 1
	v_mov_b64_e32 v[108:109], v[220:221]
	v_mov_b64_e32 v[110:111], v[222:223]
	v_add_f32_e32 v47, v66, v67
	v_add_f32_e32 v112, v68, v69
	v_add_f32_e32 v47, v47, v112
	v_add_f32_e32 v112, v62, v63
	v_add_f32_e32 v114, v64, v65
	v_add_f32_e32 v47, 0, v47
	v_add_f32_e32 v112, v112, v114
	v_add_f32_e32 v47, v47, v112
	v_add_f32_e32 v112, v56, v57
	v_add_f32_e32 v114, v58, v59
	v_add_f32_e32 v112, v112, v114
	v_add_f32_e32 v47, v47, v112
	v_add_f32_e32 v112, v52, v53
	v_add_f32_e32 v114, v54, v55
	v_add_f32_e32 v112, v112, v114
	v_add_f32_e32 v47, v47, v112
	v_mov_b32_e32 v115, v113
	s_nop 1
	v_permlane32_swap_b32_e32 v113, v115
	v_add_f32_dpp v47, v47, v47 row_ror:8 row_mask:0xf bank_mask:0xf bound_ctrl:1
	v_add_u32_e32 v46, s75, v46
	s_waitcnt vmcnt(9)
	v_pk_add_f32 v[2:3], v[2:3], 1.0 op_sel_hi:[1,0]
	v_add_f32_dpp v47, v47, v47 row_ror:4 row_mask:0xf bank_mask:0xf bound_ctrl:1
	v_pk_add_f32 v[0:1], v[0:1], 1.0 op_sel_hi:[1,0]
	s_waitcnt vmcnt(8)
	v_pk_add_f32 v[6:7], v[6:7], 1.0 op_sel_hi:[1,0]
	v_add_f32_dpp v47, v47, v47 row_ror:2 row_mask:0xf bank_mask:0xf bound_ctrl:1
	v_pk_add_f32 v[4:5], v[4:5], 1.0 op_sel_hi:[1,0]
	s_waitcnt vmcnt(3)
	v_pk_add_f32 v[14:15], v[14:15], 1.0 op_sel_hi:[1,0]
	v_add_f32_dpp v47, v47, v47 row_ror:1 row_mask:0xf bank_mask:0xf bound_ctrl:1
	v_mov_b32_e32 v112, v47
	s_nop 1
	v_permlane16_swap_b32_e32 v47, v112
	v_add_f32_e32 v47, v47, v112
	v_mov_b32_e32 v112, v47
	s_nop 1
	v_permlane32_swap_b32_e32 v47, v112
	v_add_f32_e32 v47, v47, v112
	v_fmac_f32_e32 v69, 0xba800000, v47
	v_fmac_f32_e32 v67, 0xba800000, v47
	v_fmamk_f32 v68, v47, 0xba800000, v68
	v_fmamk_f32 v66, v47, 0xba800000, v66
	v_mul_f32_e32 v112, v67, v67
	v_mul_f32_e32 v114, v69, v69
	v_fmac_f32_e32 v112, v66, v66
	v_fmac_f32_e32 v114, v68, v68
	v_fmac_f32_e32 v65, 0xba800000, v47
	v_fmac_f32_e32 v63, 0xba800000, v47
	v_add_f32_e32 v112, v112, v114
	v_fmamk_f32 v64, v47, 0xba800000, v64
	v_fmamk_f32 v62, v47, 0xba800000, v62
	v_mul_f32_e32 v114, v63, v63
	v_mul_f32_e32 v116, v65, v65
	v_fmac_f32_e32 v114, v62, v62
	v_fmac_f32_e32 v116, v64, v64
	v_add_f32_e32 v114, v114, v116
	v_fmac_f32_e32 v59, 0xba800000, v47
	v_fmac_f32_e32 v57, 0xba800000, v47
	v_add_f32_e32 v112, v112, v114
	v_fmamk_f32 v58, v47, 0xba800000, v58
	v_fmamk_f32 v56, v47, 0xba800000, v56
	v_mul_f32_e32 v114, v57, v57
	v_mul_f32_e32 v116, v59, v59
	v_fmac_f32_e32 v114, v56, v56
	v_fmac_f32_e32 v116, v58, v58
	v_add_f32_e32 v114, v114, v116
	v_fmac_f32_e32 v55, 0xba800000, v47
	v_fmac_f32_e32 v53, 0xba800000, v47
	v_add_f32_e32 v112, v114, v112
	v_fmamk_f32 v54, v47, 0xba800000, v54
	v_fmamk_f32 v52, v47, 0xba800000, v52
	v_mul_f32_e32 v47, v53, v53
	v_mul_f32_e32 v114, v55, v55
	v_fmac_f32_e32 v47, v52, v52
	v_fmac_f32_e32 v114, v54, v54
	v_add_f32_e32 v47, v47, v114
	v_add_f32_e32 v47, v47, v112
	v_pk_add_f32 v[12:13], v[12:13], 1.0 op_sel_hi:[1,0]
	s_waitcnt vmcnt(2)
	v_pk_add_f32 v[10:11], v[10:11], 1.0 op_sel_hi:[1,0]
	v_add_f32_dpp v47, v47, v47 row_ror:8 row_mask:0xf bank_mask:0xf bound_ctrl:1
	v_pk_add_f32 v[8:9], v[8:9], 1.0 op_sel_hi:[1,0]
	s_waitcnt vmcnt(1)
	v_pk_add_f32 v[18:19], v[18:19], 1.0 op_sel_hi:[1,0]
	v_add_f32_dpp v47, v47, v47 row_ror:4 row_mask:0xf bank_mask:0xf bound_ctrl:1
	v_pk_add_f32 v[16:17], v[16:17], 1.0 op_sel_hi:[1,0]
	s_waitcnt vmcnt(0)
	v_pk_add_f32 v[22:23], v[22:23], 1.0 op_sel_hi:[1,0]
	v_add_f32_dpp v47, v47, v47 row_ror:2 row_mask:0xf bank_mask:0xf bound_ctrl:1
	v_pk_add_f32 v[20:21], v[20:21], 1.0 op_sel_hi:[1,0]
	s_nop 0
	v_add_f32_dpp v47, v47, v47 row_ror:1 row_mask:0xf bank_mask:0xf bound_ctrl:1
	v_mov_b32_e32 v112, v47
	s_nop 1
	v_permlane16_swap_b32_e32 v47, v112
	v_add_f32_e32 v112, v47, v112
	v_mov_b32_e32 v114, v112
	s_nop 1
	v_permlane32_swap_b32_e32 v112, v114
	v_pk_add_f32 v[112:113], v[112:113], v[114:115]
	s_nop 0
	v_pk_fma_f32 v[116:117], v[112:113], s[4:5], v[48:49] op_sel_hi:[1,0,0]
	global_load_dwordx2 v[136:137], v[98:99], off nt
	global_load_dwordx2 v[138:139], v[98:99], off offset:512 nt
	global_load_dwordx2 v[140:141], v[98:99], off offset:1024 nt
	global_load_dwordx2 v[142:143], v[98:99], off offset:1536 nt
	global_load_dwordx4 v[112:115], v[102:103], off
	s_nop 0
	global_load_dwordx4 v[98:101], v[100:101], off offset:3072
	v_mul_f32_e32 v47, 0x4b800000, v117
	v_cmp_gt_f32_e32 vcc, s5, v117
	s_waitcnt vmcnt(2)
	v_lshlrev_b32_e32 v144, 16, v142
	v_cndmask_b32_e32 v47, v117, v47, vcc
	v_rsq_f32_e32 v47, v47
	s_waitcnt vmcnt(1)
	v_pk_add_f32 v[114:115], v[114:115], 1.0 op_sel_hi:[1,0]
	v_pk_add_f32 v[112:113], v[112:113], 1.0 op_sel_hi:[1,0]
	v_and_b32_e32 v145, 0xffff0000, v142
	v_mul_f32_e32 v102, 0x45800000, v47
	v_cndmask_b32_e32 v118, v47, v102, vcc
	v_pk_mul_f32 v[102:103], v[86:87], v[118:119] op_sel_hi:[1,0]
	v_pk_mul_f32 v[84:85], v[84:85], v[118:119] op_sel_hi:[1,0]
	v_pk_mul_f32 v[82:83], v[82:83], v[118:119] op_sel_hi:[1,0]
	v_pk_fma_f32 v[86:87], v[106:107], v[84:85], v[110:111]
	v_pk_fma_f32 v[84:85], v[104:105], v[102:103], v[108:109]
	global_store_dwordx4 v[60:61], v[84:87], off nt
	s_nop 1
	v_mov_b64_e32 v[84:85], v[224:225]
	v_mov_b64_e32 v[86:87], v[226:227]
	s_nop 0
	s_nop 1
	v_mov_b64_e32 v[102:103], v[228:229]
	v_mov_b64_e32 v[104:105], v[230:231]
	v_pk_mul_f32 v[80:81], v[80:81], v[118:119] op_sel_hi:[1,0]
	v_pk_mul_f32 v[78:79], v[78:79], v[118:119] op_sel_hi:[1,0]
	v_pk_mul_f32 v[76:77], v[76:77], v[118:119] op_sel_hi:[1,0]
	v_pk_mul_f32 v[72:73], v[72:73], v[118:119] op_sel_hi:[1,0]
	v_pk_mul_f32 v[70:71], v[70:71], v[118:119] op_sel_hi:[1,0]
	v_mul_f32_e32 v47, 0x4b800000, v116
	v_cmp_gt_f32_e32 vcc, s5, v116
	v_lshlrev_b32_e32 v110, 16, v94
	v_and_b32_e32 v111, 0xffff0000, v94
	v_cndmask_b32_e32 v47, v116, v47, vcc
	v_rsq_f32_e32 v47, v47
	v_lshlrev_b32_e32 v94, 16, v95
	v_and_b32_e32 v95, 0xffff0000, v95
	v_lshlrev_b32_e32 v142, 16, v143
	v_and_b32_e32 v143, 0xffff0000, v143
	s_waitcnt vmcnt(1)
	v_pk_add_f32 v[100:101], v[100:101], 1.0 op_sel_hi:[1,0]
	v_pk_add_f32 v[98:99], v[98:99], 1.0 op_sel_hi:[1,0]
	v_pk_mul_f32 v[8:9], v[8:9], v[110:111]
	v_pk_mul_f32 v[10:11], v[10:11], v[94:95]
	v_pk_mul_f32 v[98:99], v[98:99], v[144:145]
	v_pk_mul_f32 v[100:101], v[100:101], v[142:143]
	s_waitcnt vmcnt(1)
	v_pk_fma_f32 v[80:81], v[84:85], v[80:81], v[102:103]
	v_pk_fma_f32 v[82:83], v[86:87], v[82:83], v[104:105]
	global_store_dwordx4 v[60:61], v[80:83], off offset:1024 nt
	s_nop 1
	v_mov_b64_e32 v[80:81], v[232:233]
	v_mov_b64_e32 v[82:83], v[234:235]
	s_nop 0
	s_nop 1
	v_mov_b64_e32 v[84:85], v[236:237]
	v_mov_b64_e32 v[86:87], v[238:239]
	s_waitcnt vmcnt(2)
	v_pk_fma_f32 v[76:77], v[80:81], v[76:77], v[84:85]
	v_pk_fma_f32 v[78:79], v[82:83], v[78:79], v[86:87]
	global_store_dwordx4 v[60:61], v[76:79], off offset:2048 nt
	s_nop 1
	v_mov_b64_e32 v[76:77], v[240:241]
	v_mov_b64_e32 v[78:79], v[242:243]
	s_nop 0
	s_nop 1
	v_mov_b64_e32 v[80:81], v[244:245]
	v_mov_b64_e32 v[82:83], v[246:247]
	s_waitcnt vmcnt(3)
	v_pk_fma_f32 v[70:71], v[76:77], v[70:71], v[80:81]
	v_pk_fma_f32 v[72:73], v[78:79], v[72:73], v[82:83]
	global_store_dwordx4 v[60:61], v[70:73], off offset:3072 nt
	s_nop 1
	v_mov_b64_e32 v[76:77], v[216:217]
	v_mov_b64_e32 v[78:79], v[218:219]
	s_nop 1
	v_mov_b64_e32 v[80:81], v[220:221]
	v_mov_b64_e32 v[82:83], v[222:223]
	v_mul_f32_e32 v60, 0x45800000, v47
	v_cndmask_b32_e32 v70, v47, v60, vcc
	v_pk_mul_f32 v[60:61], v[68:69], v[70:71] op_sel_hi:[1,0]
	v_pk_mul_f32 v[66:67], v[66:67], v[70:71] op_sel_hi:[1,0]
	v_pk_mul_f32 v[64:65], v[64:65], v[70:71] op_sel_hi:[1,0]
	v_pk_mul_f32 v[62:63], v[62:63], v[70:71] op_sel_hi:[1,0]
	v_lshlrev_b32_e32 v72, 16, v93
	v_and_b32_e32 v73, 0xffff0000, v93
	v_pk_mul_f32 v[14:15], v[14:15], v[72:73]
	v_and_b32_e32 v93, 0xffff0000, v90
	s_waitcnt vmcnt(4)
	v_pk_fma_f32 v[66:67], v[76:77], v[66:67], v[80:81]
	v_pk_fma_f32 v[68:69], v[78:79], v[60:61], v[82:83]
	global_store_dwordx4 v[50:51], v[66:69], off nt
	s_nop 1
	v_mov_b64_e32 v[76:77], v[224:225]
	v_mov_b64_e32 v[78:79], v[226:227]
	s_nop 1
	v_mov_b64_e32 v[80:81], v[228:229]
	v_mov_b64_e32 v[82:83], v[230:231]
	v_lshlrev_b64 v[60:61], 12, v[74:75]
	v_lshl_add_u64 v[66:67], v[44:45], 0, v[60:61]
	global_load_dwordx4 v[84:87], v[66:67], off nt
	v_lshlrev_b64 v[68:69], 12, v[96:97]
	v_lshl_add_u64 v[60:61], v[44:45], 0, v[68:69]
	global_load_dwordx4 v[102:105], v[66:67], off offset:1024 nt
	global_load_dwordx4 v[106:109], v[66:67], off offset:2048 nt
	global_load_dwordx4 v[116:119], v[66:67], off offset:3072 nt
	global_load_dwordx4 v[120:123], v[60:61], off nt
	global_load_dwordx4 v[124:127], v[60:61], off offset:1024 nt
	global_load_dwordx4 v[128:131], v[60:61], off offset:2048 nt
	global_load_dwordx4 v[132:135], v[60:61], off offset:3072 nt
	v_lshlrev_b32_e32 v68, 16, v92
	v_and_b32_e32 v69, 0xffff0000, v92
	v_lshlrev_b32_e32 v92, 16, v90
	v_lshlrev_b32_e32 v90, 16, v91
	v_and_b32_e32 v91, 0xffff0000, v91
	v_lshlrev_b32_e32 v96, 16, v88
	v_and_b32_e32 v97, 0xffff0000, v88
	v_lshlrev_b32_e32 v88, 16, v89
	v_and_b32_e32 v89, 0xffff0000, v89
	v_pk_mul_f32 v[12:13], v[12:13], v[68:69]
	v_pk_mul_f32 v[0:1], v[0:1], v[92:93]
	v_pk_mul_f32 v[2:3], v[2:3], v[90:91]
	v_pk_mul_f32 v[6:7], v[6:7], v[88:89]
	v_pk_mul_f32 v[4:5], v[4:5], v[96:97]
	s_waitcnt vmcnt(13)
	v_pk_fma_f32 v[62:63], v[76:77], v[62:63], v[80:81]
	v_pk_fma_f32 v[64:65], v[78:79], v[64:65], v[82:83]
	global_store_dwordx4 v[50:51], v[62:65], off offset:1024 nt
	s_nop 1
	v_mov_b64_e32 v[74:75], v[232:233]
	v_mov_b64_e32 v[76:77], v[234:235]
	s_nop 1
	v_mov_b64_e32 v[78:79], v[236:237]
	v_mov_b64_e32 v[80:81], v[238:239]
	s_waitcnt vmcnt(8)
	v_pk_fma_f32 v[72:73], v[86:87], s[2:3], v[14:15] op_sel_hi:[1,0,1]
	v_lshlrev_b32_e32 v62, 16, v136
	v_add_f32_e32 v71, v72, v73
	v_pk_mul_f32 v[58:59], v[58:59], v[70:71] op_sel_hi:[1,0]
	v_pk_mul_f32 v[56:57], v[56:57], v[70:71] op_sel_hi:[1,0]
	v_and_b32_e32 v63, 0xffff0000, v136
	v_lshlrev_b32_e32 v64, 16, v137
	v_and_b32_e32 v65, 0xffff0000, v137
	v_lshlrev_b32_e32 v82, 16, v138
	v_and_b32_e32 v83, 0xffff0000, v138
	v_lshlrev_b32_e32 v136, 16, v139
	v_and_b32_e32 v137, 0xffff0000, v139
	v_pk_mul_f32 v[88:89], v[114:115], v[64:65]
	v_pk_mul_f32 v[90:91], v[112:113], v[62:63]
	v_pk_fma_f32 v[68:69], v[84:85], s[2:3], v[12:13] op_sel_hi:[1,0,1]
	v_lshlrev_b32_e32 v138, 16, v140
	v_and_b32_e32 v139, 0xffff0000, v140
	v_lshlrev_b32_e32 v140, 16, v141
	v_and_b32_e32 v141, 0xffff0000, v141
	v_pk_mul_f32 v[82:83], v[16:17], v[82:83]
	v_pk_mul_f32 v[92:93], v[18:19], v[136:137]
	s_waitcnt vmcnt(7)
	v_pk_fma_f32 v[64:65], v[104:105], s[2:3], v[2:3] op_sel_hi:[1,0,1]
	v_pk_fma_f32 v[62:63], v[102:103], s[2:3], v[0:1] op_sel_hi:[1,0,1]
	s_waitcnt vmcnt(4)
	v_pk_fma_f32 v[14:15], v[122:123], s[2:3], v[88:89] op_sel_hi:[1,0,1]
	v_pk_fma_f32 v[12:13], v[120:121], s[2:3], v[90:91] op_sel_hi:[1,0,1]
	v_add_f32_e32 v47, v68, v69
	v_pk_mul_f32 v[94:95], v[20:21], v[138:139]
	v_pk_mul_f32 v[96:97], v[22:23], v[140:141]
	v_pk_fma_f32 v[22:23], v[108:109], s[2:3], v[6:7] op_sel_hi:[1,0,1]
	v_pk_fma_f32 v[20:21], v[106:107], s[2:3], v[4:5] op_sel_hi:[1,0,1]
	v_pk_fma_f32 v[18:19], v[118:119], s[2:3], v[10:11] op_sel_hi:[1,0,1]
	v_pk_fma_f32 v[16:17], v[116:117], s[2:3], v[8:9] op_sel_hi:[1,0,1]
	s_waitcnt vmcnt(3)
	v_pk_fma_f32 v[10:11], v[126:127], s[2:3], v[92:93] op_sel_hi:[1,0,1]
	v_pk_fma_f32 v[8:9], v[124:125], s[2:3], v[82:83] op_sel_hi:[1,0,1]
	s_waitcnt vmcnt(1)
	v_pk_fma_f32 v[2:3], v[134:135], s[2:3], v[100:101] op_sel_hi:[1,0,1]
	v_pk_fma_f32 v[0:1], v[132:133], s[2:3], v[98:99] op_sel_hi:[1,0,1]
	v_add_f32_e32 v82, v62, v63
	v_add_f32_e32 v83, v64, v65
	v_add_f32_e32 v88, v12, v13
	v_add_f32_e32 v89, v14, v15
	v_add_f32_e32 v47, v47, v71
	v_pk_fma_f32 v[6:7], v[130:131], s[2:3], v[96:97] op_sel_hi:[1,0,1]
	v_pk_fma_f32 v[4:5], v[128:129], s[2:3], v[94:95] op_sel_hi:[1,0,1]
	v_add_f32_e32 v84, v20, v21
	v_add_f32_e32 v85, v22, v23
	v_add_f32_e32 v90, v8, v9
	v_add_f32_e32 v91, v10, v11
	v_add_f32_e32 v71, v82, v83
	v_add_f32_e32 v83, v88, v89
	v_add_f32_e32 v47, 0, v47
	v_add_f32_e32 v86, v16, v17
	v_add_f32_e32 v87, v18, v19
	v_add_f32_e32 v92, v4, v5
	v_add_f32_e32 v47, v47, v71
	v_add_f32_e32 v82, v86, v87
	s_waitcnt vmcnt(1)
	v_pk_fma_f32 v[56:57], v[74:75], v[56:57], v[78:79]
	v_pk_fma_f32 v[58:59], v[76:77], v[58:59], v[80:81]
	global_store_dwordx4 v[50:51], v[56:59], off offset:2048 nt
	s_nop 1
	v_mov_b64_e32 v[56:57], v[240:241]
	v_mov_b64_e32 v[58:59], v[242:243]
	s_nop 0
	s_nop 1
	v_mov_b64_e32 v[74:75], v[244:245]
	v_mov_b64_e32 v[76:77], v[246:247]
	v_add_f32_e32 v79, v0, v1
	v_add_f32_e32 v80, v2, v3
	v_add_f32_e32 v78, v6, v7
	v_add_f32_e32 v81, v84, v85
	v_add_f32_e32 v84, v90, v91
	v_add_f32_e32 v79, v79, v80
	v_add_f32_e32 v80, 0, v83
	v_add_f32_e32 v78, v92, v78
	v_add_f32_e32 v71, v80, v84
	v_add_f32_e32 v47, v47, v81
	v_add_f32_e32 v71, v71, v78
	v_add_f32_e32 v47, v47, v82
	v_add_f32_e32 v71, v71, v79
	s_nop 0
	v_add_f32_dpp v47, v47, v47 row_ror:8 row_mask:0xf bank_mask:0xf bound_ctrl:1
	v_add_f32_dpp v71, v71, v71 row_ror:8 row_mask:0xf bank_mask:0xf bound_ctrl:1
	s_nop 0
	v_add_f32_dpp v47, v47, v47 row_ror:4 row_mask:0xf bank_mask:0xf bound_ctrl:1
	v_add_f32_dpp v71, v71, v71 row_ror:4 row_mask:0xf bank_mask:0xf bound_ctrl:1
	s_nop 0
	v_add_f32_dpp v47, v47, v47 row_ror:2 row_mask:0xf bank_mask:0xf bound_ctrl:1
	v_add_f32_dpp v71, v71, v71 row_ror:2 row_mask:0xf bank_mask:0xf bound_ctrl:1
	s_nop 0
	v_add_f32_dpp v47, v47, v47 row_ror:1 row_mask:0xf bank_mask:0xf bound_ctrl:1
	v_add_f32_dpp v71, v71, v71 row_ror:1 row_mask:0xf bank_mask:0xf bound_ctrl:1
	v_mov_b32_e32 v78, v47
	v_mov_b32_e32 v79, v71
	s_nop 0
	v_permlane16_swap_b32_e32 v47, v78
	v_permlane16_swap_b32_e32 v71, v79
	v_add_f32_e32 v47, v47, v78
	v_add_f32_e32 v71, v71, v79
	v_mov_b32_e32 v78, v47
	v_mov_b32_e32 v79, v71
	s_nop 0
	v_permlane32_swap_b32_e32 v47, v78
	v_permlane32_swap_b32_e32 v71, v79
	v_add_f32_e32 v47, v47, v78
	v_add_f32_e32 v71, v71, v79
	v_fmac_f32_e32 v73, 0xba800000, v47
	v_fmamk_f32 v14, v71, 0xba800000, v14
	v_fmac_f32_e32 v15, 0xba800000, v71
	v_fmamk_f32 v12, v71, 0xba800000, v12
	v_fmac_f32_e32 v13, 0xba800000, v71
	v_fmamk_f32 v10, v71, 0xba800000, v10
	v_fmac_f32_e32 v11, 0xba800000, v71
	v_fmamk_f32 v8, v71, 0xba800000, v8
	v_fmac_f32_e32 v9, 0xba800000, v71
	v_fmamk_f32 v6, v71, 0xba800000, v6
	v_fmac_f32_e32 v7, 0xba800000, v71
	v_fmamk_f32 v4, v71, 0xba800000, v4
	v_fmac_f32_e32 v5, 0xba800000, v71
	v_fmamk_f32 v2, v71, 0xba800000, v2
	v_fmac_f32_e32 v3, 0xba800000, v71
	v_fmamk_f32 v0, v71, 0xba800000, v0
	v_fmac_f32_e32 v1, 0xba800000, v71
	v_mul_f32_e32 v71, v73, v73
	v_pk_mul_f32 v[54:55], v[54:55], v[70:71] op_sel_hi:[1,0]
	v_pk_mul_f32 v[52:53], v[52:53], v[70:71] op_sel_hi:[1,0]
	v_fmac_f32_e32 v69, 0xba800000, v47
	v_fmac_f32_e32 v65, 0xba800000, v47
	v_fmac_f32_e32 v63, 0xba800000, v47
	v_fmac_f32_e32 v23, 0xba800000, v47
	v_fmac_f32_e32 v21, 0xba800000, v47
	v_fmamk_f32 v72, v47, 0xba800000, v72
	v_fmamk_f32 v68, v47, 0xba800000, v68
	v_fmamk_f32 v64, v47, 0xba800000, v64
	v_fmamk_f32 v62, v47, 0xba800000, v62
	v_fmamk_f32 v22, v47, 0xba800000, v22
	v_fmamk_f32 v20, v47, 0xba800000, v20
	v_fmamk_f32 v18, v47, 0xba800000, v18
	v_fmac_f32_e32 v19, 0xba800000, v47
	v_fmamk_f32 v16, v47, 0xba800000, v16
	v_fmac_f32_e32 v17, 0xba800000, v47
	v_mul_f32_e32 v47, v69, v69
	v_mul_f32_e32 v70, v21, v21
	v_mul_f32_e32 v78, v15, v15
	s_waitcnt vmcnt(2)
	v_pk_fma_f32 v[52:53], v[56:57], v[52:53], v[74:75]
	v_pk_fma_f32 v[54:55], v[58:59], v[54:55], v[76:77]
	global_store_dwordx4 v[50:51], v[52:55], off offset:3072 nt
	s_nop 1
	v_mov_b64_e32 v[50:51], v[216:217]
	v_mov_b64_e32 v[52:53], v[218:219]
	s_nop 0
	s_nop 1
	v_mov_b64_e32 v[54:55], v[220:221]
	v_mov_b64_e32 v[56:57], v[222:223]
	v_mul_f32_e32 v58, v63, v63
	v_mul_f32_e32 v59, v65, v65
	v_mul_f32_e32 v74, v23, v23
	v_mul_f32_e32 v77, v13, v13
	v_mul_f32_e32 v79, v9, v9
	v_mul_f32_e32 v80, v11, v11
	v_mul_f32_e32 v75, v17, v17
	v_mul_f32_e32 v76, v19, v19
	v_mul_f32_e32 v81, v5, v5
	v_mul_f32_e32 v82, v7, v7
	v_fmac_f32_e32 v47, v68, v68
	v_fmac_f32_e32 v71, v72, v72
	v_fmac_f32_e32 v58, v62, v62
	v_fmac_f32_e32 v59, v64, v64
	v_fmac_f32_e32 v70, v20, v20
	v_fmac_f32_e32 v74, v22, v22
	v_fmac_f32_e32 v77, v12, v12
	v_fmac_f32_e32 v78, v14, v14
	v_fmac_f32_e32 v79, v8, v8
	v_fmac_f32_e32 v80, v10, v10
	v_mul_f32_e32 v83, v1, v1
	v_mul_f32_e32 v84, v3, v3
	v_fmac_f32_e32 v75, v16, v16
	v_fmac_f32_e32 v76, v18, v18
	v_fmac_f32_e32 v81, v4, v4
	v_fmac_f32_e32 v82, v6, v6
	v_add_f32_e32 v47, v47, v71
	v_add_f32_e32 v58, v58, v59
	v_add_f32_e32 v59, v70, v74
	v_add_f32_e32 v71, v77, v78
	v_add_f32_e32 v74, v79, v80
	v_fmac_f32_e32 v83, v0, v0
	v_fmac_f32_e32 v84, v2, v2
	v_add_f32_e32 v70, v75, v76
	v_add_f32_e32 v75, v81, v82
	v_add_f32_e32 v47, v47, v58
	v_add_f32_e32 v58, v71, v74
	v_add_f32_e32 v76, v83, v84
	v_add_f32_e32 v47, v59, v47
	v_add_f32_e32 v58, v75, v58
	v_add_f32_e32 v47, v70, v47
	v_add_f32_e32 v58, v76, v58
	s_nop 0
	v_add_f32_dpp v47, v47, v47 row_ror:8 row_mask:0xf bank_mask:0xf bound_ctrl:1
	v_add_f32_dpp v58, v58, v58 row_ror:8 row_mask:0xf bank_mask:0xf bound_ctrl:1
	s_nop 0
	v_add_f32_dpp v47, v47, v47 row_ror:4 row_mask:0xf bank_mask:0xf bound_ctrl:1
	v_add_f32_dpp v58, v58, v58 row_ror:4 row_mask:0xf bank_mask:0xf bound_ctrl:1
	s_nop 0
	v_add_f32_dpp v47, v47, v47 row_ror:2 row_mask:0xf bank_mask:0xf bound_ctrl:1
	v_add_f32_dpp v58, v58, v58 row_ror:2 row_mask:0xf bank_mask:0xf bound_ctrl:1
	s_nop 0
	v_add_f32_dpp v47, v47, v47 row_ror:1 row_mask:0xf bank_mask:0xf bound_ctrl:1
	v_add_f32_dpp v58, v58, v58 row_ror:1 row_mask:0xf bank_mask:0xf bound_ctrl:1
	v_mov_b32_e32 v59, v47
	v_mov_b32_e32 v70, v58
	s_nop 0
	v_permlane16_swap_b32_e32 v47, v59
	v_permlane16_swap_b32_e32 v58, v70
	v_add_f32_e32 v59, v47, v59
	v_add_f32_e32 v58, v58, v70
	v_mov_b32_e32 v71, v59
	v_mov_b32_e32 v70, v58
	s_nop 0
	v_permlane32_swap_b32_e32 v59, v71
	v_permlane32_swap_b32_e32 v58, v70
	v_pk_add_f32 v[58:59], v[58:59], v[70:71]
	s_nop 0
	v_pk_fma_f32 v[58:59], v[58:59], s[4:5], v[48:49] op_sel_hi:[1,0,0]
	s_nop 0
	v_mul_f32_e32 v47, 0x4b800000, v59
	v_cmp_gt_f32_e32 vcc, s5, v59
	s_nop 1
	v_cndmask_b32_e32 v47, v59, v47, vcc
	v_rsq_f32_e32 v47, v47
	s_nop 0
	v_mul_f32_e32 v59, 0x45800000, v47
	v_cndmask_b32_e32 v70, v47, v59, vcc
	v_pk_mul_f32 v[72:73], v[72:73], v[70:71] op_sel_hi:[1,0]
	v_pk_mul_f32 v[68:69], v[68:69], v[70:71] op_sel_hi:[1,0]
	s_waitcnt vmcnt(3)
	v_pk_fma_f32 v[52:53], v[52:53], v[72:73], v[56:57]
	v_pk_fma_f32 v[50:51], v[50:51], v[68:69], v[54:55]
	global_store_dwordx4 v[66:67], v[50:53], off nt
	s_nop 1
	v_mov_b64_e32 v[50:51], v[224:225]
	v_mov_b64_e32 v[52:53], v[226:227]
	s_nop 0
	s_nop 1
	v_mov_b64_e32 v[54:55], v[228:229]
	v_mov_b64_e32 v[56:57], v[230:231]
	v_pk_mul_f32 v[64:65], v[64:65], v[70:71] op_sel_hi:[1,0]
	v_pk_mul_f32 v[62:63], v[62:63], v[70:71] op_sel_hi:[1,0]
	v_pk_mul_f32 v[22:23], v[22:23], v[70:71] op_sel_hi:[1,0]
	v_pk_mul_f32 v[20:21], v[20:21], v[70:71] op_sel_hi:[1,0]
	v_pk_mul_f32 v[18:19], v[18:19], v[70:71] op_sel_hi:[1,0]
	v_pk_mul_f32 v[16:17], v[16:17], v[70:71] op_sel_hi:[1,0]
	v_mul_f32_e32 v47, 0x4b800000, v58
	v_cmp_gt_f32_e32 vcc, s5, v58
	s_waitcnt vmcnt(4)
	v_pk_fma_f32 v[50:51], v[50:51], v[62:63], v[54:55]
	v_pk_fma_f32 v[52:53], v[52:53], v[64:65], v[56:57]
	global_store_dwordx4 v[66:67], v[50:53], off offset:1024 nt
	s_nop 1
	v_mov_b64_e32 v[50:51], v[232:233]
	v_mov_b64_e32 v[52:53], v[234:235]
	s_nop 0
	s_nop 1
	v_mov_b64_e32 v[54:55], v[236:237]
	v_mov_b64_e32 v[56:57], v[238:239]
	v_cndmask_b32_e32 v47, v58, v47, vcc
	v_rsq_f32_e32 v47, v47
	s_waitcnt vmcnt(5)
	v_pk_fma_f32 v[20:21], v[50:51], v[20:21], v[54:55]
	v_pk_fma_f32 v[22:23], v[52:53], v[22:23], v[56:57]
	global_store_dwordx4 v[66:67], v[20:23], off offset:2048 nt
	s_nop 1
	v_mov_b64_e32 v[20:21], v[240:241]
	v_mov_b64_e32 v[22:23], v[242:243]
	s_nop 0
	s_nop 1
	v_mov_b64_e32 v[50:51], v[244:245]
	v_mov_b64_e32 v[52:53], v[246:247]
	s_waitcnt vmcnt(6)
	v_pk_fma_f32 v[16:17], v[20:21], v[16:17], v[50:51]
	v_pk_fma_f32 v[18:19], v[22:23], v[18:19], v[52:53]
	global_store_dwordx4 v[66:67], v[16:19], off offset:3072 nt
	s_nop 1
	v_mov_b64_e32 v[16:17], v[216:217]
	v_mov_b64_e32 v[18:19], v[218:219]
	s_nop 0
	s_nop 1
	v_mov_b64_e32 v[20:21], v[220:221]
	v_mov_b64_e32 v[22:23], v[222:223]
	v_mul_f32_e32 v50, 0x45800000, v47
	v_cndmask_b32_e32 v50, v47, v50, vcc
	v_pk_mul_f32 v[14:15], v[14:15], v[50:51] op_sel_hi:[1,0]
	v_pk_mul_f32 v[12:13], v[12:13], v[50:51] op_sel_hi:[1,0]
	v_pk_mul_f32 v[10:11], v[10:11], v[50:51] op_sel_hi:[1,0]
	v_pk_mul_f32 v[8:9], v[8:9], v[50:51] op_sel_hi:[1,0]
	v_pk_mul_f32 v[6:7], v[6:7], v[50:51] op_sel_hi:[1,0]
	v_pk_mul_f32 v[4:5], v[4:5], v[50:51] op_sel_hi:[1,0]
	v_pk_mul_f32 v[2:3], v[2:3], v[50:51] op_sel_hi:[1,0]
	v_pk_mul_f32 v[0:1], v[0:1], v[50:51] op_sel_hi:[1,0]
	s_waitcnt vmcnt(7)
	v_pk_fma_f32 v[12:13], v[16:17], v[12:13], v[20:21]
	v_pk_fma_f32 v[14:15], v[18:19], v[14:15], v[22:23]
	global_store_dwordx4 v[60:61], v[12:15], off nt
	s_nop 1
	v_mov_b64_e32 v[12:13], v[224:225]
	v_mov_b64_e32 v[14:15], v[226:227]
	s_nop 0
	s_nop 1
	v_mov_b64_e32 v[16:17], v[228:229]
	v_mov_b64_e32 v[18:19], v[230:231]
	s_waitcnt vmcnt(8)
	v_pk_fma_f32 v[8:9], v[12:13], v[8:9], v[16:17]
	v_pk_fma_f32 v[10:11], v[14:15], v[10:11], v[18:19]
	global_store_dwordx4 v[60:61], v[8:11], off offset:1024 nt
	s_nop 1
	v_mov_b64_e32 v[8:9], v[232:233]
	v_mov_b64_e32 v[10:11], v[234:235]
	s_nop 0
	s_nop 1
	v_mov_b64_e32 v[12:13], v[236:237]
	v_mov_b64_e32 v[14:15], v[238:239]
	s_waitcnt vmcnt(9)
	v_pk_fma_f32 v[4:5], v[8:9], v[4:5], v[12:13]
	v_pk_fma_f32 v[6:7], v[10:11], v[6:7], v[14:15]
	global_store_dwordx4 v[60:61], v[4:7], off offset:2048 nt
	s_nop 1
	v_mov_b64_e32 v[4:5], v[240:241]
	v_mov_b64_e32 v[6:7], v[242:243]
	s_nop 0
	s_nop 1
	v_mov_b64_e32 v[8:9], v[244:245]
	v_mov_b64_e32 v[10:11], v[246:247]
	s_waitcnt vmcnt(10)
	v_pk_fma_f32 v[0:1], v[4:5], v[0:1], v[8:9]
	v_pk_fma_f32 v[2:3], v[6:7], v[2:3], v[10:11]
	global_store_dwordx4 v[60:61], v[0:3], off offset:3072 nt
	s_cbranch_scc1 .LBB0_747
